# K-loop compute blocks: progressive LDS waits thinned (7,5,3,1,0 -> 7,3,0 and 3,1,0 -> 3,0)
# baseline (speedup 1.0000x reference)
; #define PG8_STAGE(bufoff, gbase, voff) do { _Pragma("unroll") for (int _i = 0; _i < 2; ++_i) \
;         __builtin_amdgcn_global_load_lds((const unsigned*)((const char*)(gbase) + (voff)[_i]), (PG8_LAS unsigned*)(lds + (bufoff) + ldsw + _i * 8192), 16, 0, 0); } while (0)
; #define PG8_LDA(dst, b, h) do { _Pragma("unroll") for (int m = 0; m < 4; ++m) _Pragma("unroll") for (int k = 0; k < 2; ++k) dst[m][k] = *(const PG8_LAS bf16x8*)(lds + PG8_SA(b, h) + aoff + m * 2048 + k * 1024); } while (0)
; #define PG8_LDB(dst, b, h) do { _Pragma("unroll") for (int n = 0; n < 2; ++n) _Pragma("unroll") for (int k = 0; k < 2; ++k) dst[n][k] = *(const PG8_LAS bf16x8*)(lds + PG8_SB(b, h) + boff + n * 2048 + k * 1024); } while (0)
; #define PG8_MMA(ai, bj, At, Bt) do { __builtin_amdgcn_s_setprio(1); _Pragma("unroll") for (int m = 0; m < 4; ++m) _Pragma("unroll") for (int n = 0; n < 2; ++n) _Pragma("unroll") for (int k = 0; k < 2; ++k) \
;         acc[ai][bj][m][n] = __builtin_amdgcn_mfma_f32_16x16x32_bf16(Bt[n][k], At[m][k], acc[ai][bj][m][n], 0, 0, 0); __builtin_amdgcn_s_setprio(0); } while (0)
; #define PG8_WAIT_L(n) asm volatile("s_waitcnt lgkmcnt(" #n ")" ::: "memory")
; #define PG8_BAR __builtin_amdgcn_s_barrier()
; #define PG8_SCHED __builtin_amdgcn_sched_barrier(0)
; template <class Epi, class Sched>
; __device__ __forceinline__ void gemm_phase(PG8_LAS unsigned char* lds, const Gemm g, const Sched& S, const Epi& E) {
;     ...
;             const bool last = (t == nt - 2);
;             const char* a1 = cA + (size_t)(t + 1) * kstep;
;             const char* a2 = last ? nA : cA + (size_t)(t + 2) * kstep; const char* b2 = last ? nB : cB + (size_t)(t + 2) * kstep;
;             const char* a3 = a2 + kstep; const char* b3 = b2 + kstep;
;             if (last && has_next) S.a_ready(nxt);
;             PG8_LDB(B0, 0, 0); PG8_SCHED; PG8_LDA(At, 0, 0); PG8_STAGE(PG8_SA(1, 1), a1 + hstep, voffA);
;             PG8_WAIT_L(8); PG8_BAR; PG8_WAIT_L(0); PG8_MMA(0, 0, At, B0); PG8_BAR; PG8_SCHED;
;             PG8_LDB(B1, 0, 1); PG8_STAGE(PG8_SB(0, 0), b2, voffB);
;             PG8_BAR; PG8_WAIT_L(0); PG8_MMA(0, 1, At, B1); PG8_BAR;
;             PG8_LDA(At, 0, 1); PG8_STAGE(PG8_SA(0, 0), a2, voffA);
;             PG8_BAR; PG8_WAIT_L(0); PG8_MMA(1, 0, At, B0); PG8_BAR; PG8_SCHED;
.LBB0_267:
	s_add_u32 s16, s16, 0x80
	s_addc_u32 s17, s17, 0
	s_add_u32 s24, s20, 0x100
	s_addc_u32 s25, s21, 0
	s_mov_b32 s20, 0
	s_add_i32 s42, s20, 2
	s_add_u32 s22, s16, 0x80
	s_addc_u32 s21, s17, 0
	s_add_i32 s43, 0, 0x10000
	v_add_u32_e32 v142, s43, v170
	ds_read_b128 v[130:133], v142
	ds_read_b128 v[134:137], v142 offset:1024
	ds_read_b128 v[138:141], v142 offset:2048
	ds_read_b128 v[142:145], v142 offset:3072
	s_cmp_eq_u32 s66, s20
	s_cselect_b32 s20, s2, s22
	s_cselect_b32 s21, s3, s21
	s_cselect_b32 s23, s13, s25
	s_cselect_b32 s22, s12, s24
	v_lshl_add_u64 v[168:169], s[16:17], 0, v[164:165]
	s_add_i32 m0, s36, 0xc000
	ds_read_b128 v[176:179], v172
	ds_read_b128 v[180:183], v172 offset:1024
	ds_read_b128 v[184:187], v172 offset:2048
	ds_read_b128 v[188:191], v172 offset:3072
	ds_read_b128 v[192:195], v172 offset:4096
	ds_read_b128 v[196:199], v172 offset:5120
	ds_read_b128 v[200:203], v172 offset:6144
	ds_read_b128 v[204:207], v172 offset:7168
	global_load_lds_dwordx4 v[168:169], off
	s_add_i32 m0, s36, 0xe000
	v_lshl_add_u64 v[168:169], s[16:17], 0, v[166:167]
	global_load_lds_dwordx4 v[168:169], off
	s_waitcnt lgkmcnt(8)
	s_barrier
	s_waitcnt lgkmcnt(7)
	v_mfma_f32_16x16x32_bf16 v[126:129], v[130:133], v[176:179], 0
	v_mfma_f32_16x16x32_bf16 v[122:125], v[138:141], v[176:179], 0
	s_waitcnt lgkmcnt(3)
	v_mfma_f32_16x16x32_bf16 v[114:117], v[130:133], v[184:187], 0
	v_mfma_f32_16x16x32_bf16 v[110:113], v[138:141], v[184:187], 0
	v_mfma_f32_16x16x32_bf16 v[98:101], v[130:133], v[192:195], 0
	v_mfma_f32_16x16x32_bf16 v[94:97], v[138:141], v[192:195], 0
	s_waitcnt lgkmcnt(0)
	v_mfma_f32_16x16x32_bf16 v[82:85], v[130:133], v[200:203], 0
	v_mfma_f32_16x16x32_bf16 v[78:81], v[138:141], v[200:203], 0
	v_mfma_f32_16x16x32_bf16 v[126:129], v[134:137], v[180:183], v[126:129]
	v_mfma_f32_16x16x32_bf16 v[122:125], v[142:145], v[180:183], v[122:125]
	v_mfma_f32_16x16x32_bf16 v[114:117], v[134:137], v[188:191], v[114:117]
	v_mfma_f32_16x16x32_bf16 v[110:113], v[142:145], v[188:191], v[110:113]
	v_mfma_f32_16x16x32_bf16 v[98:101], v[134:137], v[196:199], v[98:101]
	v_mfma_f32_16x16x32_bf16 v[94:97], v[142:145], v[196:199], v[94:97]
	v_mfma_f32_16x16x32_bf16 v[82:85], v[134:137], v[204:207], v[82:85]
	v_mfma_f32_16x16x32_bf16 v[78:81], v[142:145], v[204:207], v[78:81]
	s_barrier
	s_add_i32 s44, 0, 0x14000
	v_add_u32_e32 v168, s44, v170
	s_add_i32 s43, s43, s35
	ds_read_b128 v[208:211], v168
	ds_read_b128 v[212:215], v168 offset:1024
	ds_read_b128 v[216:219], v168 offset:2048
	ds_read_b128 v[234:237], v168 offset:3072
	v_lshl_add_u64 v[168:169], s[22:23], 0, v[48:49]
	s_mov_b32 m0, s43
	v_lshl_add_u64 v[224:225], s[22:23], 0, v[146:147]
	global_load_lds_dwordx4 v[168:169], off
	s_add_i32 m0, s43, 0x2000
	s_nop 0
	global_load_lds_dwordx4 v[224:225], off
	s_barrier
	s_waitcnt lgkmcnt(3)
	v_mfma_f32_16x16x32_bf16 v[118:121], v[208:211], v[176:179], 0
	s_waitcnt lgkmcnt(0)
	v_mfma_f32_16x16x32_bf16 v[106:109], v[216:219], v[176:179], 0
	v_mfma_f32_16x16x32_bf16 v[102:105], v[208:211], v[184:187], 0
	v_mfma_f32_16x16x32_bf16 v[90:93], v[216:219], v[184:187], 0
	v_mfma_f32_16x16x32_bf16 v[86:89], v[208:211], v[192:195], 0
	v_mfma_f32_16x16x32_bf16 v[74:77], v[216:219], v[192:195], 0
	v_mfma_f32_16x16x32_bf16 v[70:73], v[208:211], v[200:203], 0
	v_mfma_f32_16x16x32_bf16 v[66:69], v[216:219], v[200:203], 0
	v_mfma_f32_16x16x32_bf16 v[118:121], v[212:215], v[180:183], v[118:121]
	v_mfma_f32_16x16x32_bf16 v[106:109], v[234:237], v[180:183], v[106:109]
	v_mfma_f32_16x16x32_bf16 v[102:105], v[212:215], v[188:191], v[102:105]
	v_mfma_f32_16x16x32_bf16 v[90:93], v[234:237], v[188:191], v[90:93]
	v_mfma_f32_16x16x32_bf16 v[86:89], v[212:215], v[196:199], v[86:89]
	v_mfma_f32_16x16x32_bf16 v[74:77], v[234:237], v[196:199], v[74:77]
	v_mfma_f32_16x16x32_bf16 v[70:73], v[212:215], v[204:207], v[70:73]
	v_mfma_f32_16x16x32_bf16 v[66:69], v[234:237], v[204:207], v[66:69]
	s_mov_b32 m0, s36
	v_lshl_add_u64 v[228:229], s[20:21], 0, v[48:49]
	s_barrier
	ds_read_b128 v[176:179], v172 offset:16384
	ds_read_b128 v[180:183], v172 offset:17408
	ds_read_b128 v[184:187], v172 offset:18432
	ds_read_b128 v[188:191], v172 offset:19456
	ds_read_b128 v[192:195], v172 offset:20480
	ds_read_b128 v[196:199], v172 offset:21504
	ds_read_b128 v[200:203], v172 offset:22528
	ds_read_b128 v[204:207], v172 offset:23552
	global_load_lds_dwordx4 v[228:229], off
	s_mov_b32 m0, s37
	v_lshl_add_u64 v[238:239], s[20:21], 0, v[146:147]
	global_load_lds_dwordx4 v[238:239], off
	s_barrier
	s_waitcnt lgkmcnt(7)
	v_mfma_f32_16x16x32_bf16 v[62:65], v[130:133], v[176:179], 0
	v_mfma_f32_16x16x32_bf16 v[58:61], v[138:141], v[176:179], 0
	s_waitcnt lgkmcnt(3)
	v_mfma_f32_16x16x32_bf16 v[50:53], v[130:133], v[184:187], 0
	v_mfma_f32_16x16x32_bf16 v[44:47], v[138:141], v[184:187], 0
	v_mfma_f32_16x16x32_bf16 v[32:35], v[130:133], v[192:195], 0
	v_mfma_f32_16x16x32_bf16 v[28:31], v[138:141], v[192:195], 0
	s_waitcnt lgkmcnt(0)
	v_mfma_f32_16x16x32_bf16 v[16:19], v[130:133], v[200:203], 0
	v_mfma_f32_16x16x32_bf16 v[12:15], v[138:141], v[200:203], 0
	v_mfma_f32_16x16x32_bf16 v[62:65], v[134:137], v[180:183], v[62:65]
	v_mfma_f32_16x16x32_bf16 v[58:61], v[142:145], v[180:183], v[58:61]
	v_mfma_f32_16x16x32_bf16 v[50:53], v[134:137], v[188:191], v[50:53]
	v_mfma_f32_16x16x32_bf16 v[44:47], v[142:145], v[188:191], v[44:47]
	v_mfma_f32_16x16x32_bf16 v[32:35], v[134:137], v[196:199], v[32:35]
	v_mfma_f32_16x16x32_bf16 v[28:31], v[142:145], v[196:199], v[28:31]
	v_mfma_f32_16x16x32_bf16 v[16:19], v[134:137], v[204:207], v[16:19]
	v_mfma_f32_16x16x32_bf16 v[12:15], v[142:145], v[204:207], v[12:15]
	s_barrier
; #define PG8_STAGE(bufoff, gbase, voff) do { _Pragma("unroll") for (int _i = 0; _i < 2; ++_i) \
;         __builtin_amdgcn_global_load_lds((const unsigned*)((const char*)(gbase) + (voff)[_i]), (PG8_LAS unsigned*)(lds + (bufoff) + ldsw + _i * 8192), 16, 0, 0); } while (0)
; #define PG8_LDA(dst, b, h) do { _Pragma("unroll") for (int m = 0; m < 4; ++m) _Pragma("unroll") for (int k = 0; k < 2; ++k) dst[m][k] = *(const PG8_LAS bf16x8*)(lds + PG8_SA(b, h) + aoff + m * 2048 + k * 1024); } while (0)
; #define PG8_LDB(dst, b, h) do { _Pragma("unroll") for (int n = 0; n < 2; ++n) _Pragma("unroll") for (int k = 0; k < 2; ++k) dst[n][k] = *(const PG8_LAS bf16x8*)(lds + PG8_SB(b, h) + boff + n * 2048 + k * 1024); } while (0)
; #define PG8_MMA(ai, bj, At, Bt) do { __builtin_amdgcn_s_setprio(1); _Pragma("unroll") for (int m = 0; m < 4; ++m) _Pragma("unroll") for (int n = 0; n < 2; ++n) _Pragma("unroll") for (int k = 0; k < 2; ++k) \
;         acc[ai][bj][m][n] = __builtin_amdgcn_mfma_f32_16x16x32_bf16(Bt[n][k], At[m][k], acc[ai][bj][m][n], 0, 0, 0); __builtin_amdgcn_s_setprio(0); } while (0)
; #define PG8_WAIT_V(n) asm volatile("s_waitcnt vmcnt(" #n ")" ::: "memory")
; #define PG8_WAIT_L(n) asm volatile("s_waitcnt lgkmcnt(" #n ")" ::: "memory")
; #define PG8_BAR __builtin_amdgcn_s_barrier()
; #define PG8_SCHED __builtin_amdgcn_sched_barrier(0)
; template <class Epi, class Sched>
; __device__ __forceinline__ void gemm_phase(PG8_LAS unsigned char* lds, const Gemm g, const Sched& S, const Epi& E) {
;     ...
;             PG8_STAGE(PG8_SB(0, 1), b2 + hstep, voffB);
;             PG8_WAIT_V(6); PG8_BAR; PG8_MMA(1, 1, At, B1); PG8_BAR;
;             PG8_LDB(B0, 1, 0); PG8_SCHED; PG8_LDA(At, 1, 0); PG8_STAGE(PG8_SA(0, 1), a2 + hstep, voffA);
;             PG8_WAIT_L(8); PG8_BAR; PG8_WAIT_L(0); PG8_MMA(0, 0, At, B0); PG8_BAR; PG8_SCHED;
;             PG8_LDB(B1, 1, 1); PG8_STAGE(PG8_SB(1, 0), b3, voffB);
;             PG8_BAR; PG8_WAIT_L(0); PG8_MMA(0, 1, At, B1); PG8_BAR;
;             PG8_LDA(At, 1, 1); PG8_STAGE(PG8_SA(1, 0), a3, voffA);
	s_add_u32 s22, s22, s10
	s_addc_u32 s23, s23, 0
	s_add_i32 s43, s44, s35
	v_lshl_add_u64 v[240:241], s[22:23], 0, v[48:49]
	s_mov_b32 m0, s43
	v_lshl_add_u64 v[242:243], s[22:23], 0, v[146:147]
	global_load_lds_dwordx4 v[240:241], off
	s_add_i32 m0, s43, 0x2000
	s_nop 0
	global_load_lds_dwordx4 v[242:243], off
	s_waitcnt vmcnt(6)
	s_barrier
	v_mfma_f32_16x16x32_bf16 v[54:57], v[208:211], v[176:179], 0
	v_mfma_f32_16x16x32_bf16 v[40:43], v[216:219], v[176:179], 0
	v_mfma_f32_16x16x32_bf16 v[36:39], v[208:211], v[184:187], 0
	v_mfma_f32_16x16x32_bf16 v[24:27], v[216:219], v[184:187], 0
	v_mfma_f32_16x16x32_bf16 v[20:23], v[208:211], v[192:195], 0
	v_mfma_f32_16x16x32_bf16 v[8:11], v[216:219], v[192:195], 0
	v_mfma_f32_16x16x32_bf16 v[4:7], v[208:211], v[200:203], 0
	v_mfma_f32_16x16x32_bf16 v[0:3], v[216:219], v[200:203], 0
	v_mfma_f32_16x16x32_bf16 v[54:57], v[212:215], v[180:183], v[54:57]
	v_mfma_f32_16x16x32_bf16 v[40:43], v[234:237], v[180:183], v[40:43]
	v_mfma_f32_16x16x32_bf16 v[36:39], v[212:215], v[188:191], v[36:39]
	v_mfma_f32_16x16x32_bf16 v[24:27], v[234:237], v[188:191], v[24:27]
	v_mfma_f32_16x16x32_bf16 v[20:23], v[212:215], v[196:199], v[20:23]
	v_mfma_f32_16x16x32_bf16 v[8:11], v[234:237], v[196:199], v[8:11]
	v_mfma_f32_16x16x32_bf16 v[4:7], v[212:215], v[204:207], v[4:7]
	v_mfma_f32_16x16x32_bf16 v[0:3], v[234:237], v[204:207], v[0:3]
	s_add_i32 s22, 0, 0x18000
	v_add_u32_e32 v142, s22, v170
	s_barrier
	ds_read_b128 v[130:133], v142
	ds_read_b128 v[134:137], v142 offset:1024
	ds_read_b128 v[138:141], v142 offset:2048
	ds_read_b128 v[142:145], v142 offset:3072
	s_add_u32 s20, s20, s10
	s_addc_u32 s21, s21, 0
	s_mov_b32 m0, s38
	v_lshl_add_u64 v[208:209], s[20:21], 0, v[48:49]
	ds_read_b128 v[176:179], v172 offset:32768
	ds_read_b128 v[180:183], v172 offset:33792
	ds_read_b128 v[184:187], v172 offset:34816
	ds_read_b128 v[188:191], v172 offset:35840
	ds_read_b128 v[192:195], v172 offset:36864
	ds_read_b128 v[196:199], v172 offset:37888
	ds_read_b128 v[200:203], v172 offset:38912
	ds_read_b128 v[204:207], v172 offset:39936
	global_load_lds_dwordx4 v[208:209], off
	s_mov_b32 m0, s39
	v_lshl_add_u64 v[208:209], s[20:21], 0, v[146:147]
	global_load_lds_dwordx4 v[208:209], off
	s_waitcnt lgkmcnt(8)
	s_barrier
	s_waitcnt lgkmcnt(7)
	v_mfma_f32_16x16x32_bf16 v[126:129], v[130:133], v[176:179], v[126:129]
	v_mfma_f32_16x16x32_bf16 v[122:125], v[138:141], v[176:179], v[122:125]
	s_waitcnt lgkmcnt(3)
	v_mfma_f32_16x16x32_bf16 v[114:117], v[130:133], v[184:187], v[114:117]
	v_mfma_f32_16x16x32_bf16 v[110:113], v[138:141], v[184:187], v[110:113]
	v_mfma_f32_16x16x32_bf16 v[98:101], v[130:133], v[192:195], v[98:101]
	v_mfma_f32_16x16x32_bf16 v[94:97], v[138:141], v[192:195], v[94:97]
	s_waitcnt lgkmcnt(0)
	v_mfma_f32_16x16x32_bf16 v[82:85], v[130:133], v[200:203], v[82:85]
	v_mfma_f32_16x16x32_bf16 v[78:81], v[138:141], v[200:203], v[78:81]
	v_mfma_f32_16x16x32_bf16 v[126:129], v[134:137], v[180:183], v[126:129]
	v_mfma_f32_16x16x32_bf16 v[122:125], v[142:145], v[180:183], v[122:125]
	v_mfma_f32_16x16x32_bf16 v[114:117], v[134:137], v[188:191], v[114:117]
	v_mfma_f32_16x16x32_bf16 v[110:113], v[142:145], v[188:191], v[110:113]
	v_mfma_f32_16x16x32_bf16 v[98:101], v[134:137], v[196:199], v[98:101]
	v_mfma_f32_16x16x32_bf16 v[94:97], v[142:145], v[196:199], v[94:97]
	v_mfma_f32_16x16x32_bf16 v[82:85], v[134:137], v[204:207], v[82:85]
	v_mfma_f32_16x16x32_bf16 v[78:81], v[142:145], v[204:207], v[78:81]
	s_barrier
	s_add_i32 s20, 0, 0x1c000
	s_add_i32 s21, s22, s35
	v_add_u32_e32 v173, s20, v170
	v_lshl_add_u64 v[168:169], v[168:169], 0, s[0:1]
	s_mov_b32 m0, s21
	ds_read_b128 v[208:211], v173
	ds_read_b128 v[212:215], v173 offset:1024
	ds_read_b128 v[216:219], v173 offset:2048
	ds_read_b128 v[234:237], v173 offset:3072
	global_load_lds_dwordx4 v[168:169], off
	s_add_i32 m0, s21, 0x2000
	v_lshl_add_u64 v[168:169], v[224:225], 0, s[0:1]
	global_load_lds_dwordx4 v[168:169], off
	s_barrier
	s_waitcnt lgkmcnt(3)
	v_mfma_f32_16x16x32_bf16 v[118:121], v[208:211], v[176:179], v[118:121]
	s_waitcnt lgkmcnt(0)
	v_mfma_f32_16x16x32_bf16 v[106:109], v[216:219], v[176:179], v[106:109]
	v_mfma_f32_16x16x32_bf16 v[102:105], v[208:211], v[184:187], v[102:105]
	v_mfma_f32_16x16x32_bf16 v[90:93], v[216:219], v[184:187], v[90:93]
	v_mfma_f32_16x16x32_bf16 v[86:89], v[208:211], v[192:195], v[86:89]
	v_mfma_f32_16x16x32_bf16 v[74:77], v[216:219], v[192:195], v[74:77]
	v_mfma_f32_16x16x32_bf16 v[70:73], v[208:211], v[200:203], v[70:73]
	v_mfma_f32_16x16x32_bf16 v[66:69], v[216:219], v[200:203], v[66:69]
	v_mfma_f32_16x16x32_bf16 v[118:121], v[212:215], v[180:183], v[118:121]
	v_mfma_f32_16x16x32_bf16 v[106:109], v[234:237], v[180:183], v[106:109]
	v_mfma_f32_16x16x32_bf16 v[102:105], v[212:215], v[188:191], v[102:105]
	v_mfma_f32_16x16x32_bf16 v[90:93], v[234:237], v[188:191], v[90:93]
	v_mfma_f32_16x16x32_bf16 v[86:89], v[212:215], v[196:199], v[86:89]
	v_mfma_f32_16x16x32_bf16 v[74:77], v[234:237], v[196:199], v[74:77]
	v_mfma_f32_16x16x32_bf16 v[70:73], v[212:215], v[204:207], v[70:73]
	v_mfma_f32_16x16x32_bf16 v[66:69], v[234:237], v[204:207], v[66:69]
	s_mov_b32 m0, s64
	v_lshl_add_u64 v[168:169], v[228:229], 0, s[0:1]
	s_barrier
	ds_read_b128 v[176:179], v172 offset:49152
	ds_read_b128 v[180:183], v172 offset:50176
	ds_read_b128 v[184:187], v172 offset:51200
	ds_read_b128 v[188:191], v172 offset:52224
	ds_read_b128 v[192:195], v172 offset:53248
	ds_read_b128 v[196:199], v172 offset:54272
	ds_read_b128 v[200:203], v172 offset:55296
	ds_read_b128 v[204:207], v172 offset:56320
	global_load_lds_dwordx4 v[168:169], off
	s_mov_b32 m0, s65
	v_lshl_add_u64 v[168:169], v[238:239], 0, s[0:1]
	global_load_lds_dwordx4 v[168:169], off
	s_barrier
; #define PG8_STAGE(bufoff, gbase, voff) do { _Pragma("unroll") for (int _i = 0; _i < 2; ++_i) \
;         __builtin_amdgcn_global_load_lds((const unsigned*)((const char*)(gbase) + (voff)[_i]), (PG8_LAS unsigned*)(lds + (bufoff) + ldsw + _i * 8192), 16, 0, 0); } while (0)
; #define PG8_LDA(dst, b, h) do { _Pragma("unroll") for (int m = 0; m < 4; ++m) _Pragma("unroll") for (int k = 0; k < 2; ++k) dst[m][k] = *(const PG8_LAS bf16x8*)(lds + PG8_SA(b, h) + aoff + m * 2048 + k * 1024); } while (0)
; #define PG8_LDB(dst, b, h) do { _Pragma("unroll") for (int n = 0; n < 2; ++n) _Pragma("unroll") for (int k = 0; k < 2; ++k) dst[n][k] = *(const PG8_LAS bf16x8*)(lds + PG8_SB(b, h) + boff + n * 2048 + k * 1024); } while (0)
; #define PG8_WAIT_V(n) asm volatile("s_waitcnt vmcnt(" #n ")" ::: "memory")
; #define PG8_WAIT_L(n) asm volatile("s_waitcnt lgkmcnt(" #n ")" ::: "memory")
; #define PG8_BAR __builtin_amdgcn_s_barrier()
; #define PG8_SCHED __builtin_amdgcn_sched_barrier(0)
; template <class Epi, class Sched>
; __device__ __forceinline__ void gemm_phase(PG8_LAS unsigned char* lds, const Gemm g, const Sched& S, const Epi& E) {
;     ...
;             PG8_LDB(B0, 0, 0); PG8_SCHED; PG8_LDA(At, 0, 0); PG8_STAGE(PG8_SA(1, 1), a1 + hstep, voffA);
;             PG8_WAIT_L(8); PG8_BAR; PG8_WAIT_L(0); PG8_MMA(0, 0, At, B0); PG8_BAR; PG8_SCHED;
;             PG8_LDB(B1, 0, 1); PG8_STAGE(PG8_SB(0, 0), b2, voffB);
;             PG8_BAR; PG8_WAIT_L(0); PG8_MMA(0, 1, At, B1); PG8_BAR;
;             PG8_LDA(At, 0, 1); PG8_STAGE(PG8_SA(0, 0), a2, voffA);
;             PG8_BAR; PG8_WAIT_L(0); PG8_MMA(1, 0, At, B0); PG8_BAR; PG8_SCHED;
;             PG8_STAGE(PG8_SB(0, 1), b2 + hstep, voffB);
;             PG8_WAIT_V(6); PG8_BAR; PG8_MMA(1, 1, At, B1); PG8_BAR;
;             PG8_LDB(B0, 1, 0); PG8_SCHED; PG8_LDA(At, 1, 0); PG8_STAGE(PG8_SA(0, 1), a2 + hstep, voffA);
;             PG8_WAIT_L(8); PG8_BAR; PG8_WAIT_L(0); PG8_MMA(0, 0, At, B0); PG8_BAR; PG8_SCHED;
;             PG8_LDB(B1, 1, 1); PG8_STAGE(PG8_SB(1, 0), b3, voffB);
;             PG8_BAR; PG8_WAIT_L(0); PG8_MMA(0, 1, At, B1); PG8_BAR;
;             PG8_LDA(At, 1, 1); PG8_STAGE(PG8_SA(1, 0), a3, voffA);
;             PG8_BAR; PG8_WAIT_L(0); PG8_MMA(1, 0, At, B0); PG8_BAR; PG8_SCHED;
;             PG8_STAGE(PG8_SB(1, 1), b3 + hstep, voffB);
;             PG8_WAIT_V(6); PG8_BAR; PG8_MMA(1, 1, At, B1); PG8_BAR;
	s_waitcnt lgkmcnt(7)
	v_mfma_f32_16x16x32_bf16 v[62:65], v[130:133], v[176:179], v[62:65]
	v_mfma_f32_16x16x32_bf16 v[58:61], v[138:141], v[176:179], v[58:61]
	s_waitcnt lgkmcnt(3)
	v_mfma_f32_16x16x32_bf16 v[50:53], v[130:133], v[184:187], v[50:53]
	v_mfma_f32_16x16x32_bf16 v[44:47], v[138:141], v[184:187], v[44:47]
	v_mfma_f32_16x16x32_bf16 v[32:35], v[130:133], v[192:195], v[32:35]
	v_mfma_f32_16x16x32_bf16 v[28:31], v[138:141], v[192:195], v[28:31]
	s_waitcnt lgkmcnt(0)
	v_mfma_f32_16x16x32_bf16 v[16:19], v[130:133], v[200:203], v[16:19]
	v_mfma_f32_16x16x32_bf16 v[12:15], v[138:141], v[200:203], v[12:15]
	v_mfma_f32_16x16x32_bf16 v[62:65], v[134:137], v[180:183], v[62:65]
	v_mfma_f32_16x16x32_bf16 v[58:61], v[142:145], v[180:183], v[58:61]
	v_mfma_f32_16x16x32_bf16 v[50:53], v[134:137], v[188:191], v[50:53]
	v_mfma_f32_16x16x32_bf16 v[44:47], v[142:145], v[188:191], v[44:47]
	v_mfma_f32_16x16x32_bf16 v[32:35], v[134:137], v[196:199], v[32:35]
	v_mfma_f32_16x16x32_bf16 v[28:31], v[142:145], v[196:199], v[28:31]
	v_mfma_f32_16x16x32_bf16 v[16:19], v[134:137], v[204:207], v[16:19]
	v_mfma_f32_16x16x32_bf16 v[12:15], v[142:145], v[204:207], v[12:15]
	s_barrier
	s_add_i32 s20, s20, s35
	s_mov_b32 m0, s20
	v_lshl_add_u64 v[130:131], v[240:241], 0, s[0:1]
	global_load_lds_dwordx4 v[130:131], off
	s_add_i32 m0, s20, 0x2000
	v_lshl_add_u64 v[130:131], v[242:243], 0, s[0:1]
	global_load_lds_dwordx4 v[130:131], off
	s_waitcnt vmcnt(6)
	s_barrier
	v_mfma_f32_16x16x32_bf16 v[54:57], v[208:211], v[176:179], v[54:57]
	v_mfma_f32_16x16x32_bf16 v[40:43], v[216:219], v[176:179], v[40:43]
	v_mfma_f32_16x16x32_bf16 v[36:39], v[208:211], v[184:187], v[36:39]
	v_mfma_f32_16x16x32_bf16 v[24:27], v[216:219], v[184:187], v[24:27]
	v_mfma_f32_16x16x32_bf16 v[20:23], v[208:211], v[192:195], v[20:23]
	v_mfma_f32_16x16x32_bf16 v[8:11], v[216:219], v[192:195], v[8:11]
	v_mfma_f32_16x16x32_bf16 v[4:7], v[208:211], v[200:203], v[4:7]
	v_mfma_f32_16x16x32_bf16 v[0:3], v[216:219], v[200:203], v[0:3]
	v_mfma_f32_16x16x32_bf16 v[54:57], v[212:215], v[180:183], v[54:57]
	v_mfma_f32_16x16x32_bf16 v[40:43], v[234:237], v[180:183], v[40:43]
	v_mfma_f32_16x16x32_bf16 v[36:39], v[212:215], v[188:191], v[36:39]
	v_mfma_f32_16x16x32_bf16 v[24:27], v[234:237], v[188:191], v[24:27]
	v_mfma_f32_16x16x32_bf16 v[20:23], v[212:215], v[196:199], v[20:23]
	v_mfma_f32_16x16x32_bf16 v[8:11], v[234:237], v[196:199], v[8:11]
	v_mfma_f32_16x16x32_bf16 v[4:7], v[212:215], v[204:207], v[4:7]
	v_mfma_f32_16x16x32_bf16 v[0:3], v[234:237], v[204:207], v[0:3]
	s_add_u32 s16, s16, 0x100
	s_addc_u32 s17, s17, 0
	s_add_u32 s24, s24, 0x100
	s_addc_u32 s25, s25, 0
	s_cmp_ge_u32 s42, s54
	s_mov_b32 s20, s42
	s_barrier
	s_cbranch_scc1 .Lkpeel_exit_268
.LBB0_268:
	s_add_i32 s42, s20, 2
	s_add_u32 s22, s16, 0x80
	s_addc_u32 s21, s17, 0
	s_add_i32 s43, 0, 0x10000
	v_add_u32_e32 v142, s43, v170
	ds_read_b128 v[130:133], v142
	ds_read_b128 v[134:137], v142 offset:1024
	ds_read_b128 v[138:141], v142 offset:2048
	ds_read_b128 v[142:145], v142 offset:3072
	s_cmp_eq_u32 s66, s20
	s_cselect_b32 s20, s2, s22
	s_cselect_b32 s21, s3, s21
	s_cselect_b32 s23, s13, s25
	s_cselect_b32 s22, s12, s24
	v_lshl_add_u64 v[168:169], s[16:17], 0, v[164:165]
	s_add_i32 m0, s36, 0xc000
	ds_read_b128 v[176:179], v172
	ds_read_b128 v[180:183], v172 offset:1024
	ds_read_b128 v[184:187], v172 offset:2048
	ds_read_b128 v[188:191], v172 offset:3072
	ds_read_b128 v[192:195], v172 offset:4096
	ds_read_b128 v[196:199], v172 offset:5120
	ds_read_b128 v[200:203], v172 offset:6144
	ds_read_b128 v[204:207], v172 offset:7168
	global_load_lds_dwordx4 v[168:169], off
	s_add_i32 m0, s36, 0xe000
	v_lshl_add_u64 v[168:169], s[16:17], 0, v[166:167]
	global_load_lds_dwordx4 v[168:169], off
	s_waitcnt lgkmcnt(8)
	s_barrier
	s_waitcnt lgkmcnt(7)
	v_mfma_f32_16x16x32_bf16 v[126:129], v[130:133], v[176:179], v[126:129]
	v_mfma_f32_16x16x32_bf16 v[122:125], v[138:141], v[176:179], v[122:125]
	s_waitcnt lgkmcnt(3)
	v_mfma_f32_16x16x32_bf16 v[114:117], v[130:133], v[184:187], v[114:117]
	v_mfma_f32_16x16x32_bf16 v[110:113], v[138:141], v[184:187], v[110:113]
	v_mfma_f32_16x16x32_bf16 v[98:101], v[130:133], v[192:195], v[98:101]
	v_mfma_f32_16x16x32_bf16 v[94:97], v[138:141], v[192:195], v[94:97]
	s_waitcnt lgkmcnt(0)
	v_mfma_f32_16x16x32_bf16 v[82:85], v[130:133], v[200:203], v[82:85]
	v_mfma_f32_16x16x32_bf16 v[78:81], v[138:141], v[200:203], v[78:81]
	v_mfma_f32_16x16x32_bf16 v[126:129], v[134:137], v[180:183], v[126:129]
	v_mfma_f32_16x16x32_bf16 v[122:125], v[142:145], v[180:183], v[122:125]
	v_mfma_f32_16x16x32_bf16 v[114:117], v[134:137], v[188:191], v[114:117]
	v_mfma_f32_16x16x32_bf16 v[110:113], v[142:145], v[188:191], v[110:113]
	v_mfma_f32_16x16x32_bf16 v[98:101], v[134:137], v[196:199], v[98:101]
	v_mfma_f32_16x16x32_bf16 v[94:97], v[142:145], v[196:199], v[94:97]
	v_mfma_f32_16x16x32_bf16 v[82:85], v[134:137], v[204:207], v[82:85]
	v_mfma_f32_16x16x32_bf16 v[78:81], v[142:145], v[204:207], v[78:81]
	s_barrier
	s_add_i32 s44, 0, 0x14000
	v_add_u32_e32 v168, s44, v170
	s_add_i32 s43, s43, s35
	ds_read_b128 v[208:211], v168
	ds_read_b128 v[212:215], v168 offset:1024
	ds_read_b128 v[216:219], v168 offset:2048
	ds_read_b128 v[234:237], v168 offset:3072
	v_lshl_add_u64 v[168:169], s[22:23], 0, v[48:49]
	s_mov_b32 m0, s43
	v_lshl_add_u64 v[224:225], s[22:23], 0, v[146:147]
	global_load_lds_dwordx4 v[168:169], off
	s_add_i32 m0, s43, 0x2000
	s_nop 0
	global_load_lds_dwordx4 v[224:225], off
	s_barrier
; #define PG8_STAGE(bufoff, gbase, voff) do { _Pragma("unroll") for (int _i = 0; _i < 2; ++_i) \
;         __builtin_amdgcn_global_load_lds((const unsigned*)((const char*)(gbase) + (voff)[_i]), (PG8_LAS unsigned*)(lds + (bufoff) + ldsw + _i * 8192), 16, 0, 0); } while (0)
; #define PG8_LDA(dst, b, h) do { _Pragma("unroll") for (int m = 0; m < 4; ++m) _Pragma("unroll") for (int k = 0; k < 2; ++k) dst[m][k] = *(const PG8_LAS bf16x8*)(lds + PG8_SA(b, h) + aoff + m * 2048 + k * 1024); } while (0)
; #define PG8_LDB(dst, b, h) do { _Pragma("unroll") for (int n = 0; n < 2; ++n) _Pragma("unroll") for (int k = 0; k < 2; ++k) dst[n][k] = *(const PG8_LAS bf16x8*)(lds + PG8_SB(b, h) + boff + n * 2048 + k * 1024); } while (0)
; #define PG8_MMA(ai, bj, At, Bt) do { __builtin_amdgcn_s_setprio(1); _Pragma("unroll") for (int m = 0; m < 4; ++m) _Pragma("unroll") for (int n = 0; n < 2; ++n) _Pragma("unroll") for (int k = 0; k < 2; ++k) \
;         acc[ai][bj][m][n] = __builtin_amdgcn_mfma_f32_16x16x32_bf16(Bt[n][k], At[m][k], acc[ai][bj][m][n], 0, 0, 0); __builtin_amdgcn_s_setprio(0); } while (0)
; #define PG8_WAIT_V(n) asm volatile("s_waitcnt vmcnt(" #n ")" ::: "memory")
; #define PG8_WAIT_L(n) asm volatile("s_waitcnt lgkmcnt(" #n ")" ::: "memory")
; #define PG8_BAR __builtin_amdgcn_s_barrier()
; #define PG8_SCHED __builtin_amdgcn_sched_barrier(0)
; template <class Epi, class Sched>
; __device__ __forceinline__ void gemm_phase(PG8_LAS unsigned char* lds, const Gemm g, const Sched& S, const Epi& E) {
;     ...
;             PG8_LDB(B1, 0, 1); PG8_STAGE(PG8_SB(0, 0), b2, voffB);
;             PG8_BAR; PG8_WAIT_L(0); PG8_MMA(0, 1, At, B1); PG8_BAR;
;             PG8_LDA(At, 0, 1); PG8_STAGE(PG8_SA(0, 0), a2, voffA);
;             PG8_BAR; PG8_WAIT_L(0); PG8_MMA(1, 0, At, B0); PG8_BAR; PG8_SCHED;
;             PG8_STAGE(PG8_SB(0, 1), b2 + hstep, voffB);
;             PG8_WAIT_V(6); PG8_BAR; PG8_MMA(1, 1, At, B1); PG8_BAR;
;             PG8_LDB(B0, 1, 0); PG8_SCHED; PG8_LDA(At, 1, 0); PG8_STAGE(PG8_SA(0, 1), a2 + hstep, voffA);
;             PG8_WAIT_L(8); PG8_BAR; PG8_WAIT_L(0); PG8_MMA(0, 0, At, B0); PG8_BAR; PG8_SCHED;
	s_waitcnt lgkmcnt(3)
	v_mfma_f32_16x16x32_bf16 v[118:121], v[208:211], v[176:179], v[118:121]
	s_waitcnt lgkmcnt(0)
	v_mfma_f32_16x16x32_bf16 v[106:109], v[216:219], v[176:179], v[106:109]
	v_mfma_f32_16x16x32_bf16 v[102:105], v[208:211], v[184:187], v[102:105]
	v_mfma_f32_16x16x32_bf16 v[90:93], v[216:219], v[184:187], v[90:93]
	v_mfma_f32_16x16x32_bf16 v[86:89], v[208:211], v[192:195], v[86:89]
	v_mfma_f32_16x16x32_bf16 v[74:77], v[216:219], v[192:195], v[74:77]
	v_mfma_f32_16x16x32_bf16 v[70:73], v[208:211], v[200:203], v[70:73]
	v_mfma_f32_16x16x32_bf16 v[66:69], v[216:219], v[200:203], v[66:69]
	v_mfma_f32_16x16x32_bf16 v[118:121], v[212:215], v[180:183], v[118:121]
	v_mfma_f32_16x16x32_bf16 v[106:109], v[234:237], v[180:183], v[106:109]
	v_mfma_f32_16x16x32_bf16 v[102:105], v[212:215], v[188:191], v[102:105]
	v_mfma_f32_16x16x32_bf16 v[90:93], v[234:237], v[188:191], v[90:93]
	v_mfma_f32_16x16x32_bf16 v[86:89], v[212:215], v[196:199], v[86:89]
	v_mfma_f32_16x16x32_bf16 v[74:77], v[234:237], v[196:199], v[74:77]
	v_mfma_f32_16x16x32_bf16 v[70:73], v[212:215], v[204:207], v[70:73]
	v_mfma_f32_16x16x32_bf16 v[66:69], v[234:237], v[204:207], v[66:69]
	s_mov_b32 m0, s36
	v_lshl_add_u64 v[228:229], s[20:21], 0, v[48:49]
	s_barrier
	ds_read_b128 v[176:179], v172 offset:16384
	ds_read_b128 v[180:183], v172 offset:17408
	ds_read_b128 v[184:187], v172 offset:18432
	ds_read_b128 v[188:191], v172 offset:19456
	ds_read_b128 v[192:195], v172 offset:20480
	ds_read_b128 v[196:199], v172 offset:21504
	ds_read_b128 v[200:203], v172 offset:22528
	ds_read_b128 v[204:207], v172 offset:23552
	global_load_lds_dwordx4 v[228:229], off
	s_mov_b32 m0, s37
	v_lshl_add_u64 v[238:239], s[20:21], 0, v[146:147]
	global_load_lds_dwordx4 v[238:239], off
	s_barrier
	s_waitcnt lgkmcnt(7)
	v_mfma_f32_16x16x32_bf16 v[62:65], v[130:133], v[176:179], v[62:65]
	v_mfma_f32_16x16x32_bf16 v[58:61], v[138:141], v[176:179], v[58:61]
	s_waitcnt lgkmcnt(3)
	v_mfma_f32_16x16x32_bf16 v[50:53], v[130:133], v[184:187], v[50:53]
	v_mfma_f32_16x16x32_bf16 v[44:47], v[138:141], v[184:187], v[44:47]
	v_mfma_f32_16x16x32_bf16 v[32:35], v[130:133], v[192:195], v[32:35]
	v_mfma_f32_16x16x32_bf16 v[28:31], v[138:141], v[192:195], v[28:31]
	s_waitcnt lgkmcnt(0)
	v_mfma_f32_16x16x32_bf16 v[16:19], v[130:133], v[200:203], v[16:19]
	v_mfma_f32_16x16x32_bf16 v[12:15], v[138:141], v[200:203], v[12:15]
	v_mfma_f32_16x16x32_bf16 v[62:65], v[134:137], v[180:183], v[62:65]
	v_mfma_f32_16x16x32_bf16 v[58:61], v[142:145], v[180:183], v[58:61]
	v_mfma_f32_16x16x32_bf16 v[50:53], v[134:137], v[188:191], v[50:53]
	v_mfma_f32_16x16x32_bf16 v[44:47], v[142:145], v[188:191], v[44:47]
	v_mfma_f32_16x16x32_bf16 v[32:35], v[134:137], v[196:199], v[32:35]
	v_mfma_f32_16x16x32_bf16 v[28:31], v[142:145], v[196:199], v[28:31]
	v_mfma_f32_16x16x32_bf16 v[16:19], v[134:137], v[204:207], v[16:19]
	v_mfma_f32_16x16x32_bf16 v[12:15], v[142:145], v[204:207], v[12:15]
	s_barrier
	s_add_u32 s22, s22, s10
	s_addc_u32 s23, s23, 0
	s_add_i32 s43, s44, s35
	v_lshl_add_u64 v[240:241], s[22:23], 0, v[48:49]
	s_mov_b32 m0, s43
	v_lshl_add_u64 v[242:243], s[22:23], 0, v[146:147]
	global_load_lds_dwordx4 v[240:241], off
	s_add_i32 m0, s43, 0x2000
	s_nop 0
	global_load_lds_dwordx4 v[242:243], off
	s_waitcnt vmcnt(6)
	s_barrier
	v_mfma_f32_16x16x32_bf16 v[54:57], v[208:211], v[176:179], v[54:57]
	v_mfma_f32_16x16x32_bf16 v[40:43], v[216:219], v[176:179], v[40:43]
	v_mfma_f32_16x16x32_bf16 v[36:39], v[208:211], v[184:187], v[36:39]
	v_mfma_f32_16x16x32_bf16 v[24:27], v[216:219], v[184:187], v[24:27]
	v_mfma_f32_16x16x32_bf16 v[20:23], v[208:211], v[192:195], v[20:23]
	v_mfma_f32_16x16x32_bf16 v[8:11], v[216:219], v[192:195], v[8:11]
	v_mfma_f32_16x16x32_bf16 v[4:7], v[208:211], v[200:203], v[4:7]
	v_mfma_f32_16x16x32_bf16 v[0:3], v[216:219], v[200:203], v[0:3]
	v_mfma_f32_16x16x32_bf16 v[54:57], v[212:215], v[180:183], v[54:57]
	v_mfma_f32_16x16x32_bf16 v[40:43], v[234:237], v[180:183], v[40:43]
	v_mfma_f32_16x16x32_bf16 v[36:39], v[212:215], v[188:191], v[36:39]
	v_mfma_f32_16x16x32_bf16 v[24:27], v[234:237], v[188:191], v[24:27]
	v_mfma_f32_16x16x32_bf16 v[20:23], v[212:215], v[196:199], v[20:23]
	v_mfma_f32_16x16x32_bf16 v[8:11], v[234:237], v[196:199], v[8:11]
	v_mfma_f32_16x16x32_bf16 v[4:7], v[212:215], v[204:207], v[4:7]
	v_mfma_f32_16x16x32_bf16 v[0:3], v[234:237], v[204:207], v[0:3]
	s_add_i32 s22, 0, 0x18000
	v_add_u32_e32 v142, s22, v170
	s_barrier
	ds_read_b128 v[130:133], v142
	ds_read_b128 v[134:137], v142 offset:1024
	ds_read_b128 v[138:141], v142 offset:2048
	ds_read_b128 v[142:145], v142 offset:3072
	s_add_u32 s20, s20, s10
	s_addc_u32 s21, s21, 0
	s_mov_b32 m0, s38
	v_lshl_add_u64 v[208:209], s[20:21], 0, v[48:49]
	ds_read_b128 v[176:179], v172 offset:32768
	ds_read_b128 v[180:183], v172 offset:33792
	ds_read_b128 v[184:187], v172 offset:34816
	ds_read_b128 v[188:191], v172 offset:35840
	ds_read_b128 v[192:195], v172 offset:36864
	ds_read_b128 v[196:199], v172 offset:37888
	ds_read_b128 v[200:203], v172 offset:38912
	ds_read_b128 v[204:207], v172 offset:39936
	global_load_lds_dwordx4 v[208:209], off
	s_mov_b32 m0, s39
	v_lshl_add_u64 v[208:209], s[20:21], 0, v[146:147]
	global_load_lds_dwordx4 v[208:209], off
	s_waitcnt lgkmcnt(8)
	s_barrier
; #define PG8_STAGE(bufoff, gbase, voff) do { _Pragma("unroll") for (int _i = 0; _i < 2; ++_i) \
;         __builtin_amdgcn_global_load_lds((const unsigned*)((const char*)(gbase) + (voff)[_i]), (PG8_LAS unsigned*)(lds + (bufoff) + ldsw + _i * 8192), 16, 0, 0); } while (0)
; #define PG8_LDA(dst, b, h) do { _Pragma("unroll") for (int m = 0; m < 4; ++m) _Pragma("unroll") for (int k = 0; k < 2; ++k) dst[m][k] = *(const PG8_LAS bf16x8*)(lds + PG8_SA(b, h) + aoff + m * 2048 + k * 1024); } while (0)
; #define PG8_LDB(dst, b, h) do { _Pragma("unroll") for (int n = 0; n < 2; ++n) _Pragma("unroll") for (int k = 0; k < 2; ++k) dst[n][k] = *(const PG8_LAS bf16x8*)(lds + PG8_SB(b, h) + boff + n * 2048 + k * 1024); } while (0)
; #define PG8_MMA(ai, bj, At, Bt) do { __builtin_amdgcn_s_setprio(1); _Pragma("unroll") for (int m = 0; m < 4; ++m) _Pragma("unroll") for (int n = 0; n < 2; ++n) _Pragma("unroll") for (int k = 0; k < 2; ++k) \
;         acc[ai][bj][m][n] = __builtin_amdgcn_mfma_f32_16x16x32_bf16(Bt[n][k], At[m][k], acc[ai][bj][m][n], 0, 0, 0); __builtin_amdgcn_s_setprio(0); } while (0)
; #define PG8_WAIT_V(n) asm volatile("s_waitcnt vmcnt(" #n ")" ::: "memory")
; #define PG8_WAIT_L(n) asm volatile("s_waitcnt lgkmcnt(" #n ")" ::: "memory")
; #define PG8_BAR __builtin_amdgcn_s_barrier()
; #define PG8_SCHED __builtin_amdgcn_sched_barrier(0)
; template <class Epi, class Sched>
; __device__ __forceinline__ void gemm_phase(PG8_LAS unsigned char* lds, const Gemm g, const Sched& S, const Epi& E) {
;     ...
;             PG8_WAIT_L(8); PG8_BAR; PG8_WAIT_L(0); PG8_MMA(0, 0, At, B0); PG8_BAR; PG8_SCHED;
;             PG8_LDB(B1, 1, 1); PG8_STAGE(PG8_SB(1, 0), b3, voffB);
;             PG8_BAR; PG8_WAIT_L(0); PG8_MMA(0, 1, At, B1); PG8_BAR;
;             PG8_LDA(At, 1, 1); PG8_STAGE(PG8_SA(1, 0), a3, voffA);
;             PG8_BAR; PG8_WAIT_L(0); PG8_MMA(1, 0, At, B0); PG8_BAR; PG8_SCHED;
;             PG8_STAGE(PG8_SB(1, 1), b3 + hstep, voffB);
;             PG8_WAIT_V(6); PG8_BAR; PG8_MMA(1, 1, At, B1); PG8_BAR;
;         }
	s_waitcnt lgkmcnt(7)
	v_mfma_f32_16x16x32_bf16 v[126:129], v[130:133], v[176:179], v[126:129]
	v_mfma_f32_16x16x32_bf16 v[122:125], v[138:141], v[176:179], v[122:125]
	s_waitcnt lgkmcnt(3)
	v_mfma_f32_16x16x32_bf16 v[114:117], v[130:133], v[184:187], v[114:117]
	v_mfma_f32_16x16x32_bf16 v[110:113], v[138:141], v[184:187], v[110:113]
	v_mfma_f32_16x16x32_bf16 v[98:101], v[130:133], v[192:195], v[98:101]
	v_mfma_f32_16x16x32_bf16 v[94:97], v[138:141], v[192:195], v[94:97]
	s_waitcnt lgkmcnt(0)
	v_mfma_f32_16x16x32_bf16 v[82:85], v[130:133], v[200:203], v[82:85]
	v_mfma_f32_16x16x32_bf16 v[78:81], v[138:141], v[200:203], v[78:81]
	v_mfma_f32_16x16x32_bf16 v[126:129], v[134:137], v[180:183], v[126:129]
	v_mfma_f32_16x16x32_bf16 v[122:125], v[142:145], v[180:183], v[122:125]
	v_mfma_f32_16x16x32_bf16 v[114:117], v[134:137], v[188:191], v[114:117]
	v_mfma_f32_16x16x32_bf16 v[110:113], v[142:145], v[188:191], v[110:113]
	v_mfma_f32_16x16x32_bf16 v[98:101], v[134:137], v[196:199], v[98:101]
	v_mfma_f32_16x16x32_bf16 v[94:97], v[142:145], v[196:199], v[94:97]
	v_mfma_f32_16x16x32_bf16 v[82:85], v[134:137], v[204:207], v[82:85]
	v_mfma_f32_16x16x32_bf16 v[78:81], v[142:145], v[204:207], v[78:81]
	s_barrier
	s_add_i32 s20, 0, 0x1c000
	s_add_i32 s21, s22, s35
	v_add_u32_e32 v173, s20, v170
	v_lshl_add_u64 v[168:169], v[168:169], 0, s[0:1]
	s_mov_b32 m0, s21
	ds_read_b128 v[208:211], v173
	ds_read_b128 v[212:215], v173 offset:1024
	ds_read_b128 v[216:219], v173 offset:2048
	ds_read_b128 v[234:237], v173 offset:3072
	global_load_lds_dwordx4 v[168:169], off
	s_add_i32 m0, s21, 0x2000
	v_lshl_add_u64 v[168:169], v[224:225], 0, s[0:1]
	global_load_lds_dwordx4 v[168:169], off
	s_barrier
	s_waitcnt lgkmcnt(3)
	v_mfma_f32_16x16x32_bf16 v[118:121], v[208:211], v[176:179], v[118:121]
	s_waitcnt lgkmcnt(0)
	v_mfma_f32_16x16x32_bf16 v[106:109], v[216:219], v[176:179], v[106:109]
	v_mfma_f32_16x16x32_bf16 v[102:105], v[208:211], v[184:187], v[102:105]
	v_mfma_f32_16x16x32_bf16 v[90:93], v[216:219], v[184:187], v[90:93]
	v_mfma_f32_16x16x32_bf16 v[86:89], v[208:211], v[192:195], v[86:89]
	v_mfma_f32_16x16x32_bf16 v[74:77], v[216:219], v[192:195], v[74:77]
	v_mfma_f32_16x16x32_bf16 v[70:73], v[208:211], v[200:203], v[70:73]
	v_mfma_f32_16x16x32_bf16 v[66:69], v[216:219], v[200:203], v[66:69]
	v_mfma_f32_16x16x32_bf16 v[118:121], v[212:215], v[180:183], v[118:121]
	v_mfma_f32_16x16x32_bf16 v[106:109], v[234:237], v[180:183], v[106:109]
	v_mfma_f32_16x16x32_bf16 v[102:105], v[212:215], v[188:191], v[102:105]
	v_mfma_f32_16x16x32_bf16 v[90:93], v[234:237], v[188:191], v[90:93]
	v_mfma_f32_16x16x32_bf16 v[86:89], v[212:215], v[196:199], v[86:89]
	v_mfma_f32_16x16x32_bf16 v[74:77], v[234:237], v[196:199], v[74:77]
	v_mfma_f32_16x16x32_bf16 v[70:73], v[212:215], v[204:207], v[70:73]
	v_mfma_f32_16x16x32_bf16 v[66:69], v[234:237], v[204:207], v[66:69]
	s_mov_b32 m0, s64
	v_lshl_add_u64 v[168:169], v[228:229], 0, s[0:1]
	s_barrier
	ds_read_b128 v[176:179], v172 offset:49152
	ds_read_b128 v[180:183], v172 offset:50176
	ds_read_b128 v[184:187], v172 offset:51200
	ds_read_b128 v[188:191], v172 offset:52224
	ds_read_b128 v[192:195], v172 offset:53248
	ds_read_b128 v[196:199], v172 offset:54272
	ds_read_b128 v[200:203], v172 offset:55296
	ds_read_b128 v[204:207], v172 offset:56320
	global_load_lds_dwordx4 v[168:169], off
	s_mov_b32 m0, s65
	v_lshl_add_u64 v[168:169], v[238:239], 0, s[0:1]
	global_load_lds_dwordx4 v[168:169], off
	s_barrier
	s_waitcnt lgkmcnt(7)
	v_mfma_f32_16x16x32_bf16 v[62:65], v[130:133], v[176:179], v[62:65]
	v_mfma_f32_16x16x32_bf16 v[58:61], v[138:141], v[176:179], v[58:61]
	s_waitcnt lgkmcnt(3)
	v_mfma_f32_16x16x32_bf16 v[50:53], v[130:133], v[184:187], v[50:53]
	v_mfma_f32_16x16x32_bf16 v[44:47], v[138:141], v[184:187], v[44:47]
	v_mfma_f32_16x16x32_bf16 v[32:35], v[130:133], v[192:195], v[32:35]
	v_mfma_f32_16x16x32_bf16 v[28:31], v[138:141], v[192:195], v[28:31]
	s_waitcnt lgkmcnt(0)
	v_mfma_f32_16x16x32_bf16 v[16:19], v[130:133], v[200:203], v[16:19]
	v_mfma_f32_16x16x32_bf16 v[12:15], v[138:141], v[200:203], v[12:15]
	v_mfma_f32_16x16x32_bf16 v[62:65], v[134:137], v[180:183], v[62:65]
	v_mfma_f32_16x16x32_bf16 v[58:61], v[142:145], v[180:183], v[58:61]
	v_mfma_f32_16x16x32_bf16 v[50:53], v[134:137], v[188:191], v[50:53]
	v_mfma_f32_16x16x32_bf16 v[44:47], v[142:145], v[188:191], v[44:47]
	v_mfma_f32_16x16x32_bf16 v[32:35], v[134:137], v[196:199], v[32:35]
	v_mfma_f32_16x16x32_bf16 v[28:31], v[142:145], v[196:199], v[28:31]
	v_mfma_f32_16x16x32_bf16 v[16:19], v[134:137], v[204:207], v[16:19]
	v_mfma_f32_16x16x32_bf16 v[12:15], v[142:145], v[204:207], v[12:15]
	s_barrier
	s_add_i32 s20, s20, s35
	s_mov_b32 m0, s20
	v_lshl_add_u64 v[130:131], v[240:241], 0, s[0:1]
	global_load_lds_dwordx4 v[130:131], off
	s_add_i32 m0, s20, 0x2000
	v_lshl_add_u64 v[130:131], v[242:243], 0, s[0:1]
	global_load_lds_dwordx4 v[130:131], off
	s_waitcnt vmcnt(6)
	s_barrier
	v_mfma_f32_16x16x32_bf16 v[54:57], v[208:211], v[176:179], v[54:57]
	v_mfma_f32_16x16x32_bf16 v[40:43], v[216:219], v[176:179], v[40:43]
	v_mfma_f32_16x16x32_bf16 v[36:39], v[208:211], v[184:187], v[36:39]
	v_mfma_f32_16x16x32_bf16 v[24:27], v[216:219], v[184:187], v[24:27]
	v_mfma_f32_16x16x32_bf16 v[20:23], v[208:211], v[192:195], v[20:23]
	v_mfma_f32_16x16x32_bf16 v[8:11], v[216:219], v[192:195], v[8:11]
	v_mfma_f32_16x16x32_bf16 v[4:7], v[208:211], v[200:203], v[4:7]
	v_mfma_f32_16x16x32_bf16 v[0:3], v[216:219], v[200:203], v[0:3]
	v_mfma_f32_16x16x32_bf16 v[54:57], v[212:215], v[180:183], v[54:57]
	v_mfma_f32_16x16x32_bf16 v[40:43], v[234:237], v[180:183], v[40:43]
	v_mfma_f32_16x16x32_bf16 v[36:39], v[212:215], v[188:191], v[36:39]
	v_mfma_f32_16x16x32_bf16 v[24:27], v[234:237], v[188:191], v[24:27]
	v_mfma_f32_16x16x32_bf16 v[20:23], v[212:215], v[196:199], v[20:23]
	v_mfma_f32_16x16x32_bf16 v[8:11], v[234:237], v[196:199], v[8:11]
	v_mfma_f32_16x16x32_bf16 v[4:7], v[212:215], v[204:207], v[4:7]
	v_mfma_f32_16x16x32_bf16 v[0:3], v[234:237], v[204:207], v[0:3]
	s_add_u32 s16, s16, 0x100
	s_addc_u32 s17, s17, 0
	s_add_u32 s24, s24, 0x100
	s_addc_u32 s25, s25, 0
	s_cmp_ge_u32 s42, s54
	s_mov_b32 s20, s42
	s_barrier
	s_cbranch_scc0 .LBB0_268

; #define PG8_STAGE(bufoff, gbase, voff) do { _Pragma("unroll") for (int _i = 0; _i < 2; ++_i) \
;         __builtin_amdgcn_global_load_lds((const unsigned*)((const char*)(gbase) + (voff)[_i]), (PG8_LAS unsigned*)(lds + (bufoff) + ldsw + _i * 8192), 16, 0, 0); } while (0)
; #define PG8_LDA(dst, b, h) do { _Pragma("unroll") for (int m = 0; m < 4; ++m) _Pragma("unroll") for (int k = 0; k < 2; ++k) dst[m][k] = *(const PG8_LAS bf16x8*)(lds + PG8_SA(b, h) + aoff + m * 2048 + k * 1024); } while (0)
; #define PG8_LDB(dst, b, h) do { _Pragma("unroll") for (int n = 0; n < 2; ++n) _Pragma("unroll") for (int k = 0; k < 2; ++k) dst[n][k] = *(const PG8_LAS bf16x8*)(lds + PG8_SB(b, h) + boff + n * 2048 + k * 1024); } while (0)
; #define PG8_MMA(ai, bj, At, Bt) do { __builtin_amdgcn_s_setprio(1); _Pragma("unroll") for (int m = 0; m < 4; ++m) _Pragma("unroll") for (int n = 0; n < 2; ++n) _Pragma("unroll") for (int k = 0; k < 2; ++k) \
;         acc[ai][bj][m][n] = __builtin_amdgcn_mfma_f32_16x16x32_bf16(Bt[n][k], At[m][k], acc[ai][bj][m][n], 0, 0, 0); __builtin_amdgcn_s_setprio(0); } while (0)
; #define PG8_WAIT_L(n) asm volatile("s_waitcnt lgkmcnt(" #n ")" ::: "memory")
; #define PG8_BAR __builtin_amdgcn_s_barrier()
; #define PG8_SCHED __builtin_amdgcn_sched_barrier(0)
; template <class Epi, class Sched>
; __device__ __forceinline__ void gemm_phase(PG8_LAS unsigned char* lds, const Gemm g, const Sched& S, const Epi& E) {
;     ...
;             const char* a2 = last ? nA : cA + (size_t)(t + 2) * kstep; const char* b2 = last ? nB : cB + (size_t)(t + 2) * kstep;
;             const char* a3 = a2 + kstep; const char* b3 = b2 + kstep;
;             if (last && has_next) S.a_ready(nxt);
;             PG8_LDB(B0, 0, 0); PG8_SCHED; PG8_LDA(At, 0, 0); PG8_STAGE(PG8_SA(1, 1), a1 + hstep, voffA);
;             PG8_WAIT_L(8); PG8_BAR; PG8_WAIT_L(0); PG8_MMA(0, 0, At, B0); PG8_BAR; PG8_SCHED;
;             PG8_LDB(B1, 0, 1); PG8_STAGE(PG8_SB(0, 0), b2, voffB);
;             PG8_BAR; PG8_WAIT_L(0); PG8_MMA(0, 1, At, B1); PG8_BAR;
;             PG8_LDA(At, 0, 1); PG8_STAGE(PG8_SA(0, 0), a2, voffA);
;             PG8_BAR; PG8_WAIT_L(0); PG8_MMA(1, 0, At, B0); PG8_BAR; PG8_SCHED;
.LBB0_287:
	s_add_u32 s20, s20, 0x80
	s_addc_u32 s21, s21, 0
	s_add_u32 s3, s22, 0x100
	s_addc_u32 s40, s23, 0
	s_mov_b32 s22, 0
	s_add_i32 s41, s22, 2
	s_add_u32 s24, s20, 0x80
	s_addc_u32 s23, s21, 0
	s_add_i32 s63, 0, 0x10000
	v_add_u32_e32 v155, s63, v152
	ds_read_b128 v[156:159], v155
	ds_read_b128 v[160:163], v155 offset:1024
	ds_read_b128 v[164:167], v155 offset:2048
	ds_read_b128 v[168:171], v155 offset:3072
	s_cmp_eq_u32 s55, s22
	s_cselect_b32 s22, s12, s24
	s_cselect_b32 s23, s13, s23
	s_cselect_b32 s25, s17, s40
	s_cselect_b32 s24, s16, s3
	v_lshl_add_u64 v[172:173], s[20:21], 0, v[148:149]
	s_add_i32 m0, s43, 0xc000
	ds_read_b128 v[176:179], v154
	ds_read_b128 v[180:183], v154 offset:1024
	ds_read_b128 v[184:187], v154 offset:2048
	ds_read_b128 v[188:191], v154 offset:3072
	ds_read_b128 v[192:195], v154 offset:4096
	ds_read_b128 v[196:199], v154 offset:5120
	ds_read_b128 v[200:203], v154 offset:6144
	ds_read_b128 v[204:207], v154 offset:7168
	global_load_lds_dwordx4 v[172:173], off
	s_add_i32 m0, s43, 0xe000
	v_lshl_add_u64 v[172:173], s[20:21], 0, v[150:151]
	global_load_lds_dwordx4 v[172:173], off
	s_waitcnt lgkmcnt(8)
	s_barrier
	s_waitcnt lgkmcnt(7)
	v_mfma_f32_16x16x32_bf16 v[126:129], v[156:159], v[176:179], 0
	v_mfma_f32_16x16x32_bf16 v[122:125], v[164:167], v[176:179], 0
	s_waitcnt lgkmcnt(3)
	v_mfma_f32_16x16x32_bf16 v[118:121], v[156:159], v[184:187], 0
	v_mfma_f32_16x16x32_bf16 v[114:117], v[164:167], v[184:187], 0
	v_mfma_f32_16x16x32_bf16 v[110:113], v[156:159], v[192:195], 0
	v_mfma_f32_16x16x32_bf16 v[106:109], v[164:167], v[192:195], 0
	s_waitcnt lgkmcnt(0)
	v_mfma_f32_16x16x32_bf16 v[98:101], v[156:159], v[200:203], 0
	v_mfma_f32_16x16x32_bf16 v[90:93], v[164:167], v[200:203], 0
	v_mfma_f32_16x16x32_bf16 v[126:129], v[160:163], v[180:183], v[126:129]
	v_mfma_f32_16x16x32_bf16 v[122:125], v[168:171], v[180:183], v[122:125]
	v_mfma_f32_16x16x32_bf16 v[118:121], v[160:163], v[188:191], v[118:121]
	v_mfma_f32_16x16x32_bf16 v[114:117], v[168:171], v[188:191], v[114:117]
	v_mfma_f32_16x16x32_bf16 v[110:113], v[160:163], v[196:199], v[110:113]
	v_mfma_f32_16x16x32_bf16 v[106:109], v[168:171], v[196:199], v[106:109]
	v_mfma_f32_16x16x32_bf16 v[98:101], v[160:163], v[204:207], v[98:101]
	v_mfma_f32_16x16x32_bf16 v[90:93], v[168:171], v[204:207], v[90:93]
	s_barrier
	s_add_i32 s64, 0, 0x14000
	s_add_i32 s63, s63, s37
	v_add_u32_e32 v155, s64, v152
	v_lshl_add_u64 v[172:173], s[24:25], 0, v[48:49]
	s_mov_b32 m0, s63
	ds_read_b128 v[208:211], v155
	ds_read_b128 v[212:215], v155 offset:1024
	ds_read_b128 v[216:219], v155 offset:2048
	ds_read_b128 v[234:237], v155 offset:3072
	global_load_lds_dwordx4 v[172:173], off
	s_add_i32 m0, s63, 0x2000
	v_lshl_add_u64 v[224:225], s[24:25], 0, v[130:131]
	global_load_lds_dwordx4 v[224:225], off
	s_barrier
	s_waitcnt lgkmcnt(3)
	v_mfma_f32_16x16x32_bf16 v[102:105], v[208:211], v[176:179], 0
	s_waitcnt lgkmcnt(0)
	v_mfma_f32_16x16x32_bf16 v[94:97], v[216:219], v[176:179], 0
	v_mfma_f32_16x16x32_bf16 v[86:89], v[208:211], v[184:187], 0
	v_mfma_f32_16x16x32_bf16 v[82:85], v[216:219], v[184:187], 0
	v_mfma_f32_16x16x32_bf16 v[78:81], v[208:211], v[192:195], 0
	v_mfma_f32_16x16x32_bf16 v[74:77], v[216:219], v[192:195], 0
	v_mfma_f32_16x16x32_bf16 v[70:73], v[208:211], v[200:203], 0
	v_mfma_f32_16x16x32_bf16 v[66:69], v[216:219], v[200:203], 0
	v_mfma_f32_16x16x32_bf16 v[102:105], v[212:215], v[180:183], v[102:105]
	v_mfma_f32_16x16x32_bf16 v[94:97], v[234:237], v[180:183], v[94:97]
	v_mfma_f32_16x16x32_bf16 v[86:89], v[212:215], v[188:191], v[86:89]
	v_mfma_f32_16x16x32_bf16 v[82:85], v[234:237], v[188:191], v[82:85]
	v_mfma_f32_16x16x32_bf16 v[78:81], v[212:215], v[196:199], v[78:81]
	v_mfma_f32_16x16x32_bf16 v[74:77], v[234:237], v[196:199], v[74:77]
	v_mfma_f32_16x16x32_bf16 v[70:73], v[212:215], v[204:207], v[70:73]
	v_mfma_f32_16x16x32_bf16 v[66:69], v[234:237], v[204:207], v[66:69]
	s_mov_b32 m0, s43
	v_lshl_add_u64 v[228:229], s[22:23], 0, v[48:49]
	s_barrier
	ds_read_b128 v[176:179], v154 offset:16384
	ds_read_b128 v[180:183], v154 offset:17408
	ds_read_b128 v[184:187], v154 offset:18432
	ds_read_b128 v[188:191], v154 offset:19456
	ds_read_b128 v[192:195], v154 offset:20480
	ds_read_b128 v[196:199], v154 offset:21504
	ds_read_b128 v[200:203], v154 offset:22528
	ds_read_b128 v[204:207], v154 offset:23552
	global_load_lds_dwordx4 v[228:229], off
	s_mov_b32 m0, s44
	v_lshl_add_u64 v[238:239], s[22:23], 0, v[130:131]
	global_load_lds_dwordx4 v[238:239], off
	s_barrier
	s_waitcnt lgkmcnt(7)
	v_mfma_f32_16x16x32_bf16 v[62:65], v[156:159], v[176:179], 0
	v_mfma_f32_16x16x32_bf16 v[58:61], v[164:167], v[176:179], 0
	s_waitcnt lgkmcnt(3)
	v_mfma_f32_16x16x32_bf16 v[54:57], v[156:159], v[184:187], 0
	v_mfma_f32_16x16x32_bf16 v[50:53], v[164:167], v[184:187], 0
	v_mfma_f32_16x16x32_bf16 v[44:47], v[156:159], v[192:195], 0
	v_mfma_f32_16x16x32_bf16 v[40:43], v[164:167], v[192:195], 0
	s_waitcnt lgkmcnt(0)
	v_mfma_f32_16x16x32_bf16 v[32:35], v[156:159], v[200:203], 0
	v_mfma_f32_16x16x32_bf16 v[24:27], v[164:167], v[200:203], 0
	v_mfma_f32_16x16x32_bf16 v[62:65], v[160:163], v[180:183], v[62:65]
	v_mfma_f32_16x16x32_bf16 v[58:61], v[168:171], v[180:183], v[58:61]
	v_mfma_f32_16x16x32_bf16 v[54:57], v[160:163], v[188:191], v[54:57]
	v_mfma_f32_16x16x32_bf16 v[50:53], v[168:171], v[188:191], v[50:53]
	v_mfma_f32_16x16x32_bf16 v[44:47], v[160:163], v[196:199], v[44:47]
	v_mfma_f32_16x16x32_bf16 v[40:43], v[168:171], v[196:199], v[40:43]
	v_mfma_f32_16x16x32_bf16 v[32:35], v[160:163], v[204:207], v[32:35]
	v_mfma_f32_16x16x32_bf16 v[24:27], v[168:171], v[204:207], v[24:27]
	s_barrier
; #define PG8_STAGE(bufoff, gbase, voff) do { _Pragma("unroll") for (int _i = 0; _i < 2; ++_i) \
;         __builtin_amdgcn_global_load_lds((const unsigned*)((const char*)(gbase) + (voff)[_i]), (PG8_LAS unsigned*)(lds + (bufoff) + ldsw + _i * 8192), 16, 0, 0); } while (0)
; #define PG8_LDA(dst, b, h) do { _Pragma("unroll") for (int m = 0; m < 4; ++m) _Pragma("unroll") for (int k = 0; k < 2; ++k) dst[m][k] = *(const PG8_LAS bf16x8*)(lds + PG8_SA(b, h) + aoff + m * 2048 + k * 1024); } while (0)
; #define PG8_LDB(dst, b, h) do { _Pragma("unroll") for (int n = 0; n < 2; ++n) _Pragma("unroll") for (int k = 0; k < 2; ++k) dst[n][k] = *(const PG8_LAS bf16x8*)(lds + PG8_SB(b, h) + boff + n * 2048 + k * 1024); } while (0)
; #define PG8_MMA(ai, bj, At, Bt) do { __builtin_amdgcn_s_setprio(1); _Pragma("unroll") for (int m = 0; m < 4; ++m) _Pragma("unroll") for (int n = 0; n < 2; ++n) _Pragma("unroll") for (int k = 0; k < 2; ++k) \
;         acc[ai][bj][m][n] = __builtin_amdgcn_mfma_f32_16x16x32_bf16(Bt[n][k], At[m][k], acc[ai][bj][m][n], 0, 0, 0); __builtin_amdgcn_s_setprio(0); } while (0)
; #define PG8_WAIT_V(n) asm volatile("s_waitcnt vmcnt(" #n ")" ::: "memory")
; #define PG8_WAIT_L(n) asm volatile("s_waitcnt lgkmcnt(" #n ")" ::: "memory")
; #define PG8_BAR __builtin_amdgcn_s_barrier()
; #define PG8_SCHED __builtin_amdgcn_sched_barrier(0)
; template <class Epi, class Sched>
; __device__ __forceinline__ void gemm_phase(PG8_LAS unsigned char* lds, const Gemm g, const Sched& S, const Epi& E) {
;     ...
;             PG8_STAGE(PG8_SB(0, 1), b2 + hstep, voffB);
;             PG8_WAIT_V(6); PG8_BAR; PG8_MMA(1, 1, At, B1); PG8_BAR;
;             PG8_LDB(B0, 1, 0); PG8_SCHED; PG8_LDA(At, 1, 0); PG8_STAGE(PG8_SA(0, 1), a2 + hstep, voffA);
;             PG8_WAIT_L(8); PG8_BAR; PG8_WAIT_L(0); PG8_MMA(0, 0, At, B0); PG8_BAR; PG8_SCHED;
;             PG8_LDB(B1, 1, 1); PG8_STAGE(PG8_SB(1, 0), b3, voffB);
;             PG8_BAR; PG8_WAIT_L(0); PG8_MMA(0, 1, At, B1); PG8_BAR;
;             PG8_LDA(At, 1, 1); PG8_STAGE(PG8_SA(1, 0), a3, voffA);
	s_add_u32 s24, s24, s10
	s_addc_u32 s25, s25, 0
	s_add_i32 s63, s64, s37
	v_lshl_add_u64 v[240:241], s[24:25], 0, v[48:49]
	s_mov_b32 m0, s63
	v_lshl_add_u64 v[242:243], s[24:25], 0, v[130:131]
	global_load_lds_dwordx4 v[240:241], off
	s_add_i32 m0, s63, 0x2000
	s_nop 0
	global_load_lds_dwordx4 v[242:243], off
	s_waitcnt vmcnt(6)
	s_barrier
	v_mfma_f32_16x16x32_bf16 v[36:39], v[208:211], v[176:179], 0
	v_mfma_f32_16x16x32_bf16 v[28:31], v[216:219], v[176:179], 0
	v_mfma_f32_16x16x32_bf16 v[20:23], v[208:211], v[184:187], 0
	v_mfma_f32_16x16x32_bf16 v[16:19], v[216:219], v[184:187], 0
	v_mfma_f32_16x16x32_bf16 v[12:15], v[208:211], v[192:195], 0
	v_mfma_f32_16x16x32_bf16 v[8:11], v[216:219], v[192:195], 0
	v_mfma_f32_16x16x32_bf16 v[4:7], v[208:211], v[200:203], 0
	v_mfma_f32_16x16x32_bf16 v[0:3], v[216:219], v[200:203], 0
	v_mfma_f32_16x16x32_bf16 v[36:39], v[212:215], v[180:183], v[36:39]
	v_mfma_f32_16x16x32_bf16 v[28:31], v[234:237], v[180:183], v[28:31]
	v_mfma_f32_16x16x32_bf16 v[20:23], v[212:215], v[188:191], v[20:23]
	v_mfma_f32_16x16x32_bf16 v[16:19], v[234:237], v[188:191], v[16:19]
	v_mfma_f32_16x16x32_bf16 v[12:15], v[212:215], v[196:199], v[12:15]
	v_mfma_f32_16x16x32_bf16 v[8:11], v[234:237], v[196:199], v[8:11]
	v_mfma_f32_16x16x32_bf16 v[4:7], v[212:215], v[204:207], v[4:7]
	v_mfma_f32_16x16x32_bf16 v[0:3], v[234:237], v[204:207], v[0:3]
	s_add_i32 s24, 0, 0x18000
	v_add_u32_e32 v155, s24, v152
	s_barrier
	ds_read_b128 v[156:159], v155
	ds_read_b128 v[160:163], v155 offset:1024
	ds_read_b128 v[164:167], v155 offset:2048
	ds_read_b128 v[168:171], v155 offset:3072
	s_add_u32 s22, s22, s10
	s_addc_u32 s23, s23, 0
	s_mov_b32 m0, s46
	v_lshl_add_u64 v[208:209], s[22:23], 0, v[48:49]
	ds_read_b128 v[176:179], v154 offset:32768
	ds_read_b128 v[180:183], v154 offset:33792
	ds_read_b128 v[184:187], v154 offset:34816
	ds_read_b128 v[188:191], v154 offset:35840
	ds_read_b128 v[192:195], v154 offset:36864
	ds_read_b128 v[196:199], v154 offset:37888
	ds_read_b128 v[200:203], v154 offset:38912
	ds_read_b128 v[204:207], v154 offset:39936
	global_load_lds_dwordx4 v[208:209], off
	s_mov_b32 m0, s47
	v_lshl_add_u64 v[208:209], s[22:23], 0, v[130:131]
	global_load_lds_dwordx4 v[208:209], off
	s_waitcnt lgkmcnt(8)
	s_barrier
	s_waitcnt lgkmcnt(7)
	v_mfma_f32_16x16x32_bf16 v[126:129], v[156:159], v[176:179], v[126:129]
	v_mfma_f32_16x16x32_bf16 v[122:125], v[164:167], v[176:179], v[122:125]
	s_waitcnt lgkmcnt(3)
	v_mfma_f32_16x16x32_bf16 v[118:121], v[156:159], v[184:187], v[118:121]
	v_mfma_f32_16x16x32_bf16 v[114:117], v[164:167], v[184:187], v[114:117]
	v_mfma_f32_16x16x32_bf16 v[110:113], v[156:159], v[192:195], v[110:113]
	v_mfma_f32_16x16x32_bf16 v[106:109], v[164:167], v[192:195], v[106:109]
	s_waitcnt lgkmcnt(0)
	v_mfma_f32_16x16x32_bf16 v[98:101], v[156:159], v[200:203], v[98:101]
	v_mfma_f32_16x16x32_bf16 v[90:93], v[164:167], v[200:203], v[90:93]
	v_mfma_f32_16x16x32_bf16 v[126:129], v[160:163], v[180:183], v[126:129]
	v_mfma_f32_16x16x32_bf16 v[122:125], v[168:171], v[180:183], v[122:125]
	v_mfma_f32_16x16x32_bf16 v[118:121], v[160:163], v[188:191], v[118:121]
	v_mfma_f32_16x16x32_bf16 v[114:117], v[168:171], v[188:191], v[114:117]
	v_mfma_f32_16x16x32_bf16 v[110:113], v[160:163], v[196:199], v[110:113]
	v_mfma_f32_16x16x32_bf16 v[106:109], v[168:171], v[196:199], v[106:109]
	v_mfma_f32_16x16x32_bf16 v[98:101], v[160:163], v[204:207], v[98:101]
	v_mfma_f32_16x16x32_bf16 v[90:93], v[168:171], v[204:207], v[90:93]
	s_barrier
	s_add_i32 s22, 0, 0x1c000
	s_add_i32 s23, s24, s37
	v_add_u32_e32 v155, s22, v152
	v_lshl_add_u64 v[172:173], v[172:173], 0, s[0:1]
	s_mov_b32 m0, s23
	ds_read_b128 v[208:211], v155
	ds_read_b128 v[212:215], v155 offset:1024
	ds_read_b128 v[216:219], v155 offset:2048
	ds_read_b128 v[234:237], v155 offset:3072
	global_load_lds_dwordx4 v[172:173], off
	s_add_i32 m0, s23, 0x2000
	v_lshl_add_u64 v[172:173], v[224:225], 0, s[0:1]
	global_load_lds_dwordx4 v[172:173], off
	s_barrier
	s_waitcnt lgkmcnt(3)
	v_mfma_f32_16x16x32_bf16 v[102:105], v[208:211], v[176:179], v[102:105]
	s_waitcnt lgkmcnt(0)
	v_mfma_f32_16x16x32_bf16 v[94:97], v[216:219], v[176:179], v[94:97]
	v_mfma_f32_16x16x32_bf16 v[86:89], v[208:211], v[184:187], v[86:89]
	v_mfma_f32_16x16x32_bf16 v[82:85], v[216:219], v[184:187], v[82:85]
	v_mfma_f32_16x16x32_bf16 v[78:81], v[208:211], v[192:195], v[78:81]
	v_mfma_f32_16x16x32_bf16 v[74:77], v[216:219], v[192:195], v[74:77]
	v_mfma_f32_16x16x32_bf16 v[70:73], v[208:211], v[200:203], v[70:73]
	v_mfma_f32_16x16x32_bf16 v[66:69], v[216:219], v[200:203], v[66:69]
	v_mfma_f32_16x16x32_bf16 v[102:105], v[212:215], v[180:183], v[102:105]
	v_mfma_f32_16x16x32_bf16 v[94:97], v[234:237], v[180:183], v[94:97]
	v_mfma_f32_16x16x32_bf16 v[86:89], v[212:215], v[188:191], v[86:89]
	v_mfma_f32_16x16x32_bf16 v[82:85], v[234:237], v[188:191], v[82:85]
	v_mfma_f32_16x16x32_bf16 v[78:81], v[212:215], v[196:199], v[78:81]
	v_mfma_f32_16x16x32_bf16 v[74:77], v[234:237], v[196:199], v[74:77]
	v_mfma_f32_16x16x32_bf16 v[70:73], v[212:215], v[204:207], v[70:73]
	v_mfma_f32_16x16x32_bf16 v[66:69], v[234:237], v[204:207], v[66:69]
	s_mov_b32 m0, s50
	v_lshl_add_u64 v[172:173], v[228:229], 0, s[0:1]
	s_barrier
	ds_read_b128 v[176:179], v154 offset:49152
	ds_read_b128 v[180:183], v154 offset:50176
	ds_read_b128 v[184:187], v154 offset:51200
	ds_read_b128 v[188:191], v154 offset:52224
	ds_read_b128 v[192:195], v154 offset:53248
	ds_read_b128 v[196:199], v154 offset:54272
	ds_read_b128 v[200:203], v154 offset:55296
	ds_read_b128 v[204:207], v154 offset:56320
	global_load_lds_dwordx4 v[172:173], off
	s_mov_b32 m0, s51
	v_lshl_add_u64 v[172:173], v[238:239], 0, s[0:1]
	global_load_lds_dwordx4 v[172:173], off
	s_barrier
; #define PG8_STAGE(bufoff, gbase, voff) do { _Pragma("unroll") for (int _i = 0; _i < 2; ++_i) \
;         __builtin_amdgcn_global_load_lds((const unsigned*)((const char*)(gbase) + (voff)[_i]), (PG8_LAS unsigned*)(lds + (bufoff) + ldsw + _i * 8192), 16, 0, 0); } while (0)
; #define PG8_LDA(dst, b, h) do { _Pragma("unroll") for (int m = 0; m < 4; ++m) _Pragma("unroll") for (int k = 0; k < 2; ++k) dst[m][k] = *(const PG8_LAS bf16x8*)(lds + PG8_SA(b, h) + aoff + m * 2048 + k * 1024); } while (0)
; #define PG8_LDB(dst, b, h) do { _Pragma("unroll") for (int n = 0; n < 2; ++n) _Pragma("unroll") for (int k = 0; k < 2; ++k) dst[n][k] = *(const PG8_LAS bf16x8*)(lds + PG8_SB(b, h) + boff + n * 2048 + k * 1024); } while (0)
; #define PG8_MMA(ai, bj, At, Bt) do { __builtin_amdgcn_s_setprio(1); _Pragma("unroll") for (int m = 0; m < 4; ++m) _Pragma("unroll") for (int n = 0; n < 2; ++n) _Pragma("unroll") for (int k = 0; k < 2; ++k) \
;         acc[ai][bj][m][n] = __builtin_amdgcn_mfma_f32_16x16x32_bf16(Bt[n][k], At[m][k], acc[ai][bj][m][n], 0, 0, 0); __builtin_amdgcn_s_setprio(0); } while (0)
; #define PG8_WAIT_V(n) asm volatile("s_waitcnt vmcnt(" #n ")" ::: "memory")
; #define PG8_WAIT_L(n) asm volatile("s_waitcnt lgkmcnt(" #n ")" ::: "memory")
; #define PG8_BAR __builtin_amdgcn_s_barrier()
; #define PG8_SCHED __builtin_amdgcn_sched_barrier(0)
; template <class Epi, class Sched>
; __device__ __forceinline__ void gemm_phase(PG8_LAS unsigned char* lds, const Gemm g, const Sched& S, const Epi& E) {
;     ...
;             const bool last = (t == nt - 2);
;             const char* a1 = cA + (size_t)(t + 1) * kstep;
;             const char* a2 = last ? nA : cA + (size_t)(t + 2) * kstep; const char* b2 = last ? nB : cB + (size_t)(t + 2) * kstep;
;             const char* a3 = a2 + kstep; const char* b3 = b2 + kstep;
;             if (last && has_next) S.a_ready(nxt);
;             PG8_LDB(B0, 0, 0); PG8_SCHED; PG8_LDA(At, 0, 0); PG8_STAGE(PG8_SA(1, 1), a1 + hstep, voffA);
;             PG8_WAIT_L(8); PG8_BAR; PG8_WAIT_L(0); PG8_MMA(0, 0, At, B0); PG8_BAR; PG8_SCHED;
;             PG8_LDB(B1, 0, 1); PG8_STAGE(PG8_SB(0, 0), b2, voffB);
;     ...
;             PG8_BAR; PG8_WAIT_L(0); PG8_MMA(1, 0, At, B0); PG8_BAR; PG8_SCHED;
;             PG8_STAGE(PG8_SB(1, 1), b3 + hstep, voffB);
;             PG8_WAIT_V(6); PG8_BAR; PG8_MMA(1, 1, At, B1); PG8_BAR;
;         }
	s_waitcnt lgkmcnt(7)
	v_mfma_f32_16x16x32_bf16 v[62:65], v[156:159], v[176:179], v[62:65]
	v_mfma_f32_16x16x32_bf16 v[58:61], v[164:167], v[176:179], v[58:61]
	s_waitcnt lgkmcnt(3)
	v_mfma_f32_16x16x32_bf16 v[54:57], v[156:159], v[184:187], v[54:57]
	v_mfma_f32_16x16x32_bf16 v[50:53], v[164:167], v[184:187], v[50:53]
	v_mfma_f32_16x16x32_bf16 v[44:47], v[156:159], v[192:195], v[44:47]
	v_mfma_f32_16x16x32_bf16 v[40:43], v[164:167], v[192:195], v[40:43]
	s_waitcnt lgkmcnt(0)
	v_mfma_f32_16x16x32_bf16 v[32:35], v[156:159], v[200:203], v[32:35]
	v_mfma_f32_16x16x32_bf16 v[24:27], v[164:167], v[200:203], v[24:27]
	v_mfma_f32_16x16x32_bf16 v[62:65], v[160:163], v[180:183], v[62:65]
	v_mfma_f32_16x16x32_bf16 v[58:61], v[168:171], v[180:183], v[58:61]
	v_mfma_f32_16x16x32_bf16 v[54:57], v[160:163], v[188:191], v[54:57]
	v_mfma_f32_16x16x32_bf16 v[50:53], v[168:171], v[188:191], v[50:53]
	v_mfma_f32_16x16x32_bf16 v[44:47], v[160:163], v[196:199], v[44:47]
	v_mfma_f32_16x16x32_bf16 v[40:43], v[168:171], v[196:199], v[40:43]
	v_mfma_f32_16x16x32_bf16 v[32:35], v[160:163], v[204:207], v[32:35]
	v_mfma_f32_16x16x32_bf16 v[24:27], v[168:171], v[204:207], v[24:27]
	s_barrier
	s_add_i32 s22, s22, s37
	s_mov_b32 m0, s22
	v_lshl_add_u64 v[156:157], v[240:241], 0, s[0:1]
	global_load_lds_dwordx4 v[156:157], off
	s_add_i32 m0, s22, 0x2000
	v_lshl_add_u64 v[156:157], v[242:243], 0, s[0:1]
	global_load_lds_dwordx4 v[156:157], off
	s_waitcnt vmcnt(6)
	s_barrier
	v_mfma_f32_16x16x32_bf16 v[36:39], v[208:211], v[176:179], v[36:39]
	v_mfma_f32_16x16x32_bf16 v[28:31], v[216:219], v[176:179], v[28:31]
	v_mfma_f32_16x16x32_bf16 v[20:23], v[208:211], v[184:187], v[20:23]
	v_mfma_f32_16x16x32_bf16 v[16:19], v[216:219], v[184:187], v[16:19]
	v_mfma_f32_16x16x32_bf16 v[12:15], v[208:211], v[192:195], v[12:15]
	v_mfma_f32_16x16x32_bf16 v[8:11], v[216:219], v[192:195], v[8:11]
	v_mfma_f32_16x16x32_bf16 v[4:7], v[208:211], v[200:203], v[4:7]
	v_mfma_f32_16x16x32_bf16 v[0:3], v[216:219], v[200:203], v[0:3]
	v_mfma_f32_16x16x32_bf16 v[36:39], v[212:215], v[180:183], v[36:39]
	v_mfma_f32_16x16x32_bf16 v[28:31], v[234:237], v[180:183], v[28:31]
	v_mfma_f32_16x16x32_bf16 v[20:23], v[212:215], v[188:191], v[20:23]
	v_mfma_f32_16x16x32_bf16 v[16:19], v[234:237], v[188:191], v[16:19]
	v_mfma_f32_16x16x32_bf16 v[12:15], v[212:215], v[196:199], v[12:15]
	v_mfma_f32_16x16x32_bf16 v[8:11], v[234:237], v[196:199], v[8:11]
	v_mfma_f32_16x16x32_bf16 v[4:7], v[212:215], v[204:207], v[4:7]
	v_mfma_f32_16x16x32_bf16 v[0:3], v[234:237], v[204:207], v[0:3]
	s_add_u32 s20, s20, 0x100
	s_addc_u32 s21, s21, 0
	s_add_u32 s3, s3, 0x100
	s_addc_u32 s40, s40, 0
	s_cmp_ge_u32 s41, s54
	s_mov_b32 s22, s41
	s_barrier
	s_cbranch_scc1 .Lkpeel_exit_288
.LBB0_288:
	s_add_i32 s41, s22, 2
	s_add_u32 s24, s20, 0x80
	s_addc_u32 s23, s21, 0
	s_add_i32 s63, 0, 0x10000
	v_add_u32_e32 v155, s63, v152
	ds_read_b128 v[156:159], v155
	ds_read_b128 v[160:163], v155 offset:1024
	ds_read_b128 v[164:167], v155 offset:2048
	ds_read_b128 v[168:171], v155 offset:3072
	s_cmp_eq_u32 s55, s22
	s_cselect_b32 s22, s12, s24
	s_cselect_b32 s23, s13, s23
	s_cselect_b32 s25, s17, s40
	s_cselect_b32 s24, s16, s3
	v_lshl_add_u64 v[172:173], s[20:21], 0, v[148:149]
	s_add_i32 m0, s43, 0xc000
	ds_read_b128 v[176:179], v154
	ds_read_b128 v[180:183], v154 offset:1024
	ds_read_b128 v[184:187], v154 offset:2048
	ds_read_b128 v[188:191], v154 offset:3072
	ds_read_b128 v[192:195], v154 offset:4096
	ds_read_b128 v[196:199], v154 offset:5120
	ds_read_b128 v[200:203], v154 offset:6144
	ds_read_b128 v[204:207], v154 offset:7168
	global_load_lds_dwordx4 v[172:173], off
	s_add_i32 m0, s43, 0xe000
	v_lshl_add_u64 v[172:173], s[20:21], 0, v[150:151]
	global_load_lds_dwordx4 v[172:173], off
	s_waitcnt lgkmcnt(8)
	s_barrier
	s_waitcnt lgkmcnt(7)
	v_mfma_f32_16x16x32_bf16 v[126:129], v[156:159], v[176:179], v[126:129]
	v_mfma_f32_16x16x32_bf16 v[122:125], v[164:167], v[176:179], v[122:125]
	s_waitcnt lgkmcnt(3)
	v_mfma_f32_16x16x32_bf16 v[118:121], v[156:159], v[184:187], v[118:121]
	v_mfma_f32_16x16x32_bf16 v[114:117], v[164:167], v[184:187], v[114:117]
	v_mfma_f32_16x16x32_bf16 v[110:113], v[156:159], v[192:195], v[110:113]
	v_mfma_f32_16x16x32_bf16 v[106:109], v[164:167], v[192:195], v[106:109]
	s_waitcnt lgkmcnt(0)
	v_mfma_f32_16x16x32_bf16 v[98:101], v[156:159], v[200:203], v[98:101]
	v_mfma_f32_16x16x32_bf16 v[90:93], v[164:167], v[200:203], v[90:93]
	v_mfma_f32_16x16x32_bf16 v[126:129], v[160:163], v[180:183], v[126:129]
	v_mfma_f32_16x16x32_bf16 v[122:125], v[168:171], v[180:183], v[122:125]
	v_mfma_f32_16x16x32_bf16 v[118:121], v[160:163], v[188:191], v[118:121]
	v_mfma_f32_16x16x32_bf16 v[114:117], v[168:171], v[188:191], v[114:117]
	v_mfma_f32_16x16x32_bf16 v[110:113], v[160:163], v[196:199], v[110:113]
	v_mfma_f32_16x16x32_bf16 v[106:109], v[168:171], v[196:199], v[106:109]
	v_mfma_f32_16x16x32_bf16 v[98:101], v[160:163], v[204:207], v[98:101]
	v_mfma_f32_16x16x32_bf16 v[90:93], v[168:171], v[204:207], v[90:93]
	s_barrier
	s_add_i32 s64, 0, 0x14000
	s_add_i32 s63, s63, s37
	v_add_u32_e32 v155, s64, v152
	v_lshl_add_u64 v[172:173], s[24:25], 0, v[48:49]
	s_mov_b32 m0, s63
	ds_read_b128 v[208:211], v155
	ds_read_b128 v[212:215], v155 offset:1024
	ds_read_b128 v[216:219], v155 offset:2048
	ds_read_b128 v[234:237], v155 offset:3072
	global_load_lds_dwordx4 v[172:173], off
	s_add_i32 m0, s63, 0x2000
	v_lshl_add_u64 v[224:225], s[24:25], 0, v[130:131]
	global_load_lds_dwordx4 v[224:225], off
	s_barrier
; #define PG8_STAGE(bufoff, gbase, voff) do { _Pragma("unroll") for (int _i = 0; _i < 2; ++_i) \
;         __builtin_amdgcn_global_load_lds((const unsigned*)((const char*)(gbase) + (voff)[_i]), (PG8_LAS unsigned*)(lds + (bufoff) + ldsw + _i * 8192), 16, 0, 0); } while (0)
; #define PG8_LDA(dst, b, h) do { _Pragma("unroll") for (int m = 0; m < 4; ++m) _Pragma("unroll") for (int k = 0; k < 2; ++k) dst[m][k] = *(const PG8_LAS bf16x8*)(lds + PG8_SA(b, h) + aoff + m * 2048 + k * 1024); } while (0)
; #define PG8_LDB(dst, b, h) do { _Pragma("unroll") for (int n = 0; n < 2; ++n) _Pragma("unroll") for (int k = 0; k < 2; ++k) dst[n][k] = *(const PG8_LAS bf16x8*)(lds + PG8_SB(b, h) + boff + n * 2048 + k * 1024); } while (0)
; #define PG8_MMA(ai, bj, At, Bt) do { __builtin_amdgcn_s_setprio(1); _Pragma("unroll") for (int m = 0; m < 4; ++m) _Pragma("unroll") for (int n = 0; n < 2; ++n) _Pragma("unroll") for (int k = 0; k < 2; ++k) \
;         acc[ai][bj][m][n] = __builtin_amdgcn_mfma_f32_16x16x32_bf16(Bt[n][k], At[m][k], acc[ai][bj][m][n], 0, 0, 0); __builtin_amdgcn_s_setprio(0); } while (0)
; #define PG8_WAIT_V(n) asm volatile("s_waitcnt vmcnt(" #n ")" ::: "memory")
; #define PG8_WAIT_L(n) asm volatile("s_waitcnt lgkmcnt(" #n ")" ::: "memory")
; #define PG8_BAR __builtin_amdgcn_s_barrier()
; #define PG8_SCHED __builtin_amdgcn_sched_barrier(0)
; template <class Epi, class Sched>
; __device__ __forceinline__ void gemm_phase(PG8_LAS unsigned char* lds, const Gemm g, const Sched& S, const Epi& E) {
;     ...
;             PG8_BAR; PG8_WAIT_L(0); PG8_MMA(0, 1, At, B1); PG8_BAR;
;             PG8_LDA(At, 0, 1); PG8_STAGE(PG8_SA(0, 0), a2, voffA);
;             PG8_BAR; PG8_WAIT_L(0); PG8_MMA(1, 0, At, B0); PG8_BAR; PG8_SCHED;
;             PG8_STAGE(PG8_SB(0, 1), b2 + hstep, voffB);
;             PG8_WAIT_V(6); PG8_BAR; PG8_MMA(1, 1, At, B1); PG8_BAR;
;             PG8_LDB(B0, 1, 0); PG8_SCHED; PG8_LDA(At, 1, 0); PG8_STAGE(PG8_SA(0, 1), a2 + hstep, voffA);
;             PG8_WAIT_L(8); PG8_BAR; PG8_WAIT_L(0); PG8_MMA(0, 0, At, B0); PG8_BAR; PG8_SCHED;
	s_waitcnt lgkmcnt(3)
	v_mfma_f32_16x16x32_bf16 v[102:105], v[208:211], v[176:179], v[102:105]
	s_waitcnt lgkmcnt(0)
	v_mfma_f32_16x16x32_bf16 v[94:97], v[216:219], v[176:179], v[94:97]
	v_mfma_f32_16x16x32_bf16 v[86:89], v[208:211], v[184:187], v[86:89]
	v_mfma_f32_16x16x32_bf16 v[82:85], v[216:219], v[184:187], v[82:85]
	v_mfma_f32_16x16x32_bf16 v[78:81], v[208:211], v[192:195], v[78:81]
	v_mfma_f32_16x16x32_bf16 v[74:77], v[216:219], v[192:195], v[74:77]
	v_mfma_f32_16x16x32_bf16 v[70:73], v[208:211], v[200:203], v[70:73]
	v_mfma_f32_16x16x32_bf16 v[66:69], v[216:219], v[200:203], v[66:69]
	v_mfma_f32_16x16x32_bf16 v[102:105], v[212:215], v[180:183], v[102:105]
	v_mfma_f32_16x16x32_bf16 v[94:97], v[234:237], v[180:183], v[94:97]
	v_mfma_f32_16x16x32_bf16 v[86:89], v[212:215], v[188:191], v[86:89]
	v_mfma_f32_16x16x32_bf16 v[82:85], v[234:237], v[188:191], v[82:85]
	v_mfma_f32_16x16x32_bf16 v[78:81], v[212:215], v[196:199], v[78:81]
	v_mfma_f32_16x16x32_bf16 v[74:77], v[234:237], v[196:199], v[74:77]
	v_mfma_f32_16x16x32_bf16 v[70:73], v[212:215], v[204:207], v[70:73]
	v_mfma_f32_16x16x32_bf16 v[66:69], v[234:237], v[204:207], v[66:69]
	s_mov_b32 m0, s43
	v_lshl_add_u64 v[228:229], s[22:23], 0, v[48:49]
	s_barrier
	ds_read_b128 v[176:179], v154 offset:16384
	ds_read_b128 v[180:183], v154 offset:17408
	ds_read_b128 v[184:187], v154 offset:18432
	ds_read_b128 v[188:191], v154 offset:19456
	ds_read_b128 v[192:195], v154 offset:20480
	ds_read_b128 v[196:199], v154 offset:21504
	ds_read_b128 v[200:203], v154 offset:22528
	ds_read_b128 v[204:207], v154 offset:23552
	global_load_lds_dwordx4 v[228:229], off
	s_mov_b32 m0, s44
	v_lshl_add_u64 v[238:239], s[22:23], 0, v[130:131]
	global_load_lds_dwordx4 v[238:239], off
	s_barrier
	s_waitcnt lgkmcnt(7)
	v_mfma_f32_16x16x32_bf16 v[62:65], v[156:159], v[176:179], v[62:65]
	v_mfma_f32_16x16x32_bf16 v[58:61], v[164:167], v[176:179], v[58:61]
	s_waitcnt lgkmcnt(3)
	v_mfma_f32_16x16x32_bf16 v[54:57], v[156:159], v[184:187], v[54:57]
	v_mfma_f32_16x16x32_bf16 v[50:53], v[164:167], v[184:187], v[50:53]
	v_mfma_f32_16x16x32_bf16 v[44:47], v[156:159], v[192:195], v[44:47]
	v_mfma_f32_16x16x32_bf16 v[40:43], v[164:167], v[192:195], v[40:43]
	s_waitcnt lgkmcnt(0)
	v_mfma_f32_16x16x32_bf16 v[32:35], v[156:159], v[200:203], v[32:35]
	v_mfma_f32_16x16x32_bf16 v[24:27], v[164:167], v[200:203], v[24:27]
	v_mfma_f32_16x16x32_bf16 v[62:65], v[160:163], v[180:183], v[62:65]
	v_mfma_f32_16x16x32_bf16 v[58:61], v[168:171], v[180:183], v[58:61]
	v_mfma_f32_16x16x32_bf16 v[54:57], v[160:163], v[188:191], v[54:57]
	v_mfma_f32_16x16x32_bf16 v[50:53], v[168:171], v[188:191], v[50:53]
	v_mfma_f32_16x16x32_bf16 v[44:47], v[160:163], v[196:199], v[44:47]
	v_mfma_f32_16x16x32_bf16 v[40:43], v[168:171], v[196:199], v[40:43]
	v_mfma_f32_16x16x32_bf16 v[32:35], v[160:163], v[204:207], v[32:35]
	v_mfma_f32_16x16x32_bf16 v[24:27], v[168:171], v[204:207], v[24:27]
	s_barrier
	s_add_u32 s24, s24, s10
	s_addc_u32 s25, s25, 0
	s_add_i32 s63, s64, s37
	v_lshl_add_u64 v[240:241], s[24:25], 0, v[48:49]
	s_mov_b32 m0, s63
	v_lshl_add_u64 v[242:243], s[24:25], 0, v[130:131]
	global_load_lds_dwordx4 v[240:241], off
	s_add_i32 m0, s63, 0x2000
	s_nop 0
	global_load_lds_dwordx4 v[242:243], off
	s_waitcnt vmcnt(6)
	s_barrier
	v_mfma_f32_16x16x32_bf16 v[36:39], v[208:211], v[176:179], v[36:39]
	v_mfma_f32_16x16x32_bf16 v[28:31], v[216:219], v[176:179], v[28:31]
	v_mfma_f32_16x16x32_bf16 v[20:23], v[208:211], v[184:187], v[20:23]
	v_mfma_f32_16x16x32_bf16 v[16:19], v[216:219], v[184:187], v[16:19]
	v_mfma_f32_16x16x32_bf16 v[12:15], v[208:211], v[192:195], v[12:15]
	v_mfma_f32_16x16x32_bf16 v[8:11], v[216:219], v[192:195], v[8:11]
	v_mfma_f32_16x16x32_bf16 v[4:7], v[208:211], v[200:203], v[4:7]
	v_mfma_f32_16x16x32_bf16 v[0:3], v[216:219], v[200:203], v[0:3]
	v_mfma_f32_16x16x32_bf16 v[36:39], v[212:215], v[180:183], v[36:39]
	v_mfma_f32_16x16x32_bf16 v[28:31], v[234:237], v[180:183], v[28:31]
	v_mfma_f32_16x16x32_bf16 v[20:23], v[212:215], v[188:191], v[20:23]
	v_mfma_f32_16x16x32_bf16 v[16:19], v[234:237], v[188:191], v[16:19]
	v_mfma_f32_16x16x32_bf16 v[12:15], v[212:215], v[196:199], v[12:15]
	v_mfma_f32_16x16x32_bf16 v[8:11], v[234:237], v[196:199], v[8:11]
	v_mfma_f32_16x16x32_bf16 v[4:7], v[212:215], v[204:207], v[4:7]
	v_mfma_f32_16x16x32_bf16 v[0:3], v[234:237], v[204:207], v[0:3]
	s_add_i32 s24, 0, 0x18000
	v_add_u32_e32 v155, s24, v152
	s_barrier
	ds_read_b128 v[156:159], v155
	ds_read_b128 v[160:163], v155 offset:1024
	ds_read_b128 v[164:167], v155 offset:2048
	ds_read_b128 v[168:171], v155 offset:3072
	s_add_u32 s22, s22, s10
	s_addc_u32 s23, s23, 0
	s_mov_b32 m0, s46
	v_lshl_add_u64 v[208:209], s[22:23], 0, v[48:49]
	ds_read_b128 v[176:179], v154 offset:32768
	ds_read_b128 v[180:183], v154 offset:33792
	ds_read_b128 v[184:187], v154 offset:34816
	ds_read_b128 v[188:191], v154 offset:35840
	ds_read_b128 v[192:195], v154 offset:36864
	ds_read_b128 v[196:199], v154 offset:37888
	ds_read_b128 v[200:203], v154 offset:38912
	ds_read_b128 v[204:207], v154 offset:39936
	global_load_lds_dwordx4 v[208:209], off
	s_mov_b32 m0, s47
	v_lshl_add_u64 v[208:209], s[22:23], 0, v[130:131]
	global_load_lds_dwordx4 v[208:209], off
	s_waitcnt lgkmcnt(8)
	s_barrier
; #define PG8_STAGE(bufoff, gbase, voff) do { _Pragma("unroll") for (int _i = 0; _i < 2; ++_i) \
;         __builtin_amdgcn_global_load_lds((const unsigned*)((const char*)(gbase) + (voff)[_i]), (PG8_LAS unsigned*)(lds + (bufoff) + ldsw + _i * 8192), 16, 0, 0); } while (0)
; #define PG8_LDA(dst, b, h) do { _Pragma("unroll") for (int m = 0; m < 4; ++m) _Pragma("unroll") for (int k = 0; k < 2; ++k) dst[m][k] = *(const PG8_LAS bf16x8*)(lds + PG8_SA(b, h) + aoff + m * 2048 + k * 1024); } while (0)
; #define PG8_LDB(dst, b, h) do { _Pragma("unroll") for (int n = 0; n < 2; ++n) _Pragma("unroll") for (int k = 0; k < 2; ++k) dst[n][k] = *(const PG8_LAS bf16x8*)(lds + PG8_SB(b, h) + boff + n * 2048 + k * 1024); } while (0)
; #define PG8_MMA(ai, bj, At, Bt) do { __builtin_amdgcn_s_setprio(1); _Pragma("unroll") for (int m = 0; m < 4; ++m) _Pragma("unroll") for (int n = 0; n < 2; ++n) _Pragma("unroll") for (int k = 0; k < 2; ++k) \
;         acc[ai][bj][m][n] = __builtin_amdgcn_mfma_f32_16x16x32_bf16(Bt[n][k], At[m][k], acc[ai][bj][m][n], 0, 0, 0); __builtin_amdgcn_s_setprio(0); } while (0)
; #define PG8_WAIT_V(n) asm volatile("s_waitcnt vmcnt(" #n ")" ::: "memory")
; #define PG8_WAIT_L(n) asm volatile("s_waitcnt lgkmcnt(" #n ")" ::: "memory")
; #define PG8_BAR __builtin_amdgcn_s_barrier()
; #define PG8_SCHED __builtin_amdgcn_sched_barrier(0)
; template <class Epi, class Sched>
; __device__ __forceinline__ void gemm_phase(PG8_LAS unsigned char* lds, const Gemm g, const Sched& S, const Epi& E) {
;     ...
;             PG8_WAIT_L(8); PG8_BAR; PG8_WAIT_L(0); PG8_MMA(0, 0, At, B0); PG8_BAR; PG8_SCHED;
;             PG8_LDB(B1, 1, 1); PG8_STAGE(PG8_SB(1, 0), b3, voffB);
;             PG8_BAR; PG8_WAIT_L(0); PG8_MMA(0, 1, At, B1); PG8_BAR;
;             PG8_LDA(At, 1, 1); PG8_STAGE(PG8_SA(1, 0), a3, voffA);
;             PG8_BAR; PG8_WAIT_L(0); PG8_MMA(1, 0, At, B0); PG8_BAR; PG8_SCHED;
;             PG8_STAGE(PG8_SB(1, 1), b3 + hstep, voffB);
;             PG8_WAIT_V(6); PG8_BAR; PG8_MMA(1, 1, At, B1); PG8_BAR;
;         }
	s_waitcnt lgkmcnt(7)
	v_mfma_f32_16x16x32_bf16 v[126:129], v[156:159], v[176:179], v[126:129]
	v_mfma_f32_16x16x32_bf16 v[122:125], v[164:167], v[176:179], v[122:125]
	s_waitcnt lgkmcnt(3)
	v_mfma_f32_16x16x32_bf16 v[118:121], v[156:159], v[184:187], v[118:121]
	v_mfma_f32_16x16x32_bf16 v[114:117], v[164:167], v[184:187], v[114:117]
	v_mfma_f32_16x16x32_bf16 v[110:113], v[156:159], v[192:195], v[110:113]
	v_mfma_f32_16x16x32_bf16 v[106:109], v[164:167], v[192:195], v[106:109]
	s_waitcnt lgkmcnt(0)
	v_mfma_f32_16x16x32_bf16 v[98:101], v[156:159], v[200:203], v[98:101]
	v_mfma_f32_16x16x32_bf16 v[90:93], v[164:167], v[200:203], v[90:93]
	v_mfma_f32_16x16x32_bf16 v[126:129], v[160:163], v[180:183], v[126:129]
	v_mfma_f32_16x16x32_bf16 v[122:125], v[168:171], v[180:183], v[122:125]
	v_mfma_f32_16x16x32_bf16 v[118:121], v[160:163], v[188:191], v[118:121]
	v_mfma_f32_16x16x32_bf16 v[114:117], v[168:171], v[188:191], v[114:117]
	v_mfma_f32_16x16x32_bf16 v[110:113], v[160:163], v[196:199], v[110:113]
	v_mfma_f32_16x16x32_bf16 v[106:109], v[168:171], v[196:199], v[106:109]
	v_mfma_f32_16x16x32_bf16 v[98:101], v[160:163], v[204:207], v[98:101]
	v_mfma_f32_16x16x32_bf16 v[90:93], v[168:171], v[204:207], v[90:93]
	s_barrier
	s_add_i32 s22, 0, 0x1c000
	s_add_i32 s23, s24, s37
	v_add_u32_e32 v155, s22, v152
	v_lshl_add_u64 v[172:173], v[172:173], 0, s[0:1]
	s_mov_b32 m0, s23
	ds_read_b128 v[208:211], v155
	ds_read_b128 v[212:215], v155 offset:1024
	ds_read_b128 v[216:219], v155 offset:2048
	ds_read_b128 v[234:237], v155 offset:3072
	global_load_lds_dwordx4 v[172:173], off
	s_add_i32 m0, s23, 0x2000
	v_lshl_add_u64 v[172:173], v[224:225], 0, s[0:1]
	global_load_lds_dwordx4 v[172:173], off
	s_barrier
	s_waitcnt lgkmcnt(3)
	v_mfma_f32_16x16x32_bf16 v[102:105], v[208:211], v[176:179], v[102:105]
	s_waitcnt lgkmcnt(0)
	v_mfma_f32_16x16x32_bf16 v[94:97], v[216:219], v[176:179], v[94:97]
	v_mfma_f32_16x16x32_bf16 v[86:89], v[208:211], v[184:187], v[86:89]
	v_mfma_f32_16x16x32_bf16 v[82:85], v[216:219], v[184:187], v[82:85]
	v_mfma_f32_16x16x32_bf16 v[78:81], v[208:211], v[192:195], v[78:81]
	v_mfma_f32_16x16x32_bf16 v[74:77], v[216:219], v[192:195], v[74:77]
	v_mfma_f32_16x16x32_bf16 v[70:73], v[208:211], v[200:203], v[70:73]
	v_mfma_f32_16x16x32_bf16 v[66:69], v[216:219], v[200:203], v[66:69]
	v_mfma_f32_16x16x32_bf16 v[102:105], v[212:215], v[180:183], v[102:105]
	v_mfma_f32_16x16x32_bf16 v[94:97], v[234:237], v[180:183], v[94:97]
	v_mfma_f32_16x16x32_bf16 v[86:89], v[212:215], v[188:191], v[86:89]
	v_mfma_f32_16x16x32_bf16 v[82:85], v[234:237], v[188:191], v[82:85]
	v_mfma_f32_16x16x32_bf16 v[78:81], v[212:215], v[196:199], v[78:81]
	v_mfma_f32_16x16x32_bf16 v[74:77], v[234:237], v[196:199], v[74:77]
	v_mfma_f32_16x16x32_bf16 v[70:73], v[212:215], v[204:207], v[70:73]
	v_mfma_f32_16x16x32_bf16 v[66:69], v[234:237], v[204:207], v[66:69]
	s_mov_b32 m0, s50
	v_lshl_add_u64 v[172:173], v[228:229], 0, s[0:1]
	s_barrier
	ds_read_b128 v[176:179], v154 offset:49152
	ds_read_b128 v[180:183], v154 offset:50176
	ds_read_b128 v[184:187], v154 offset:51200
	ds_read_b128 v[188:191], v154 offset:52224
	ds_read_b128 v[192:195], v154 offset:53248
	ds_read_b128 v[196:199], v154 offset:54272
	ds_read_b128 v[200:203], v154 offset:55296
	ds_read_b128 v[204:207], v154 offset:56320
	global_load_lds_dwordx4 v[172:173], off
	s_mov_b32 m0, s51
	v_lshl_add_u64 v[172:173], v[238:239], 0, s[0:1]
	global_load_lds_dwordx4 v[172:173], off
	s_barrier
	s_waitcnt lgkmcnt(7)
	v_mfma_f32_16x16x32_bf16 v[62:65], v[156:159], v[176:179], v[62:65]
	v_mfma_f32_16x16x32_bf16 v[58:61], v[164:167], v[176:179], v[58:61]
	s_waitcnt lgkmcnt(3)
	v_mfma_f32_16x16x32_bf16 v[54:57], v[156:159], v[184:187], v[54:57]
	v_mfma_f32_16x16x32_bf16 v[50:53], v[164:167], v[184:187], v[50:53]
	v_mfma_f32_16x16x32_bf16 v[44:47], v[156:159], v[192:195], v[44:47]
	v_mfma_f32_16x16x32_bf16 v[40:43], v[164:167], v[192:195], v[40:43]
	s_waitcnt lgkmcnt(0)
	v_mfma_f32_16x16x32_bf16 v[32:35], v[156:159], v[200:203], v[32:35]
	v_mfma_f32_16x16x32_bf16 v[24:27], v[164:167], v[200:203], v[24:27]
	v_mfma_f32_16x16x32_bf16 v[62:65], v[160:163], v[180:183], v[62:65]
	v_mfma_f32_16x16x32_bf16 v[58:61], v[168:171], v[180:183], v[58:61]
	v_mfma_f32_16x16x32_bf16 v[54:57], v[160:163], v[188:191], v[54:57]
	v_mfma_f32_16x16x32_bf16 v[50:53], v[168:171], v[188:191], v[50:53]
	v_mfma_f32_16x16x32_bf16 v[44:47], v[160:163], v[196:199], v[44:47]
	v_mfma_f32_16x16x32_bf16 v[40:43], v[168:171], v[196:199], v[40:43]
	v_mfma_f32_16x16x32_bf16 v[32:35], v[160:163], v[204:207], v[32:35]
	v_mfma_f32_16x16x32_bf16 v[24:27], v[168:171], v[204:207], v[24:27]
	s_barrier
	s_add_i32 s22, s22, s37
	s_mov_b32 m0, s22
	v_lshl_add_u64 v[156:157], v[240:241], 0, s[0:1]
	global_load_lds_dwordx4 v[156:157], off
	s_add_i32 m0, s22, 0x2000
	v_lshl_add_u64 v[156:157], v[242:243], 0, s[0:1]
	global_load_lds_dwordx4 v[156:157], off
	s_waitcnt vmcnt(6)
	s_barrier
	v_mfma_f32_16x16x32_bf16 v[36:39], v[208:211], v[176:179], v[36:39]
	v_mfma_f32_16x16x32_bf16 v[28:31], v[216:219], v[176:179], v[28:31]
	v_mfma_f32_16x16x32_bf16 v[20:23], v[208:211], v[184:187], v[20:23]
	v_mfma_f32_16x16x32_bf16 v[16:19], v[216:219], v[184:187], v[16:19]
	v_mfma_f32_16x16x32_bf16 v[12:15], v[208:211], v[192:195], v[12:15]
	v_mfma_f32_16x16x32_bf16 v[8:11], v[216:219], v[192:195], v[8:11]
	v_mfma_f32_16x16x32_bf16 v[4:7], v[208:211], v[200:203], v[4:7]
	v_mfma_f32_16x16x32_bf16 v[0:3], v[216:219], v[200:203], v[0:3]
	v_mfma_f32_16x16x32_bf16 v[36:39], v[212:215], v[180:183], v[36:39]
	v_mfma_f32_16x16x32_bf16 v[28:31], v[234:237], v[180:183], v[28:31]
	v_mfma_f32_16x16x32_bf16 v[20:23], v[212:215], v[188:191], v[20:23]
	v_mfma_f32_16x16x32_bf16 v[16:19], v[234:237], v[188:191], v[16:19]
	v_mfma_f32_16x16x32_bf16 v[12:15], v[212:215], v[196:199], v[12:15]
	v_mfma_f32_16x16x32_bf16 v[8:11], v[234:237], v[196:199], v[8:11]
	v_mfma_f32_16x16x32_bf16 v[4:7], v[212:215], v[204:207], v[4:7]
	v_mfma_f32_16x16x32_bf16 v[0:3], v[234:237], v[204:207], v[0:3]
	s_add_u32 s20, s20, 0x100
	s_addc_u32 s21, s21, 0
	s_add_u32 s3, s3, 0x100
	s_addc_u32 s40, s40, 0
	s_cmp_ge_u32 s41, s54
	s_mov_b32 s22, s41
	s_barrier
	s_cbranch_scc0 .LBB0_288

; #define PG8_STAGE(bufoff, gbase, voff) do { _Pragma("unroll") for (int _i = 0; _i < 2; ++_i) \
;         __builtin_amdgcn_global_load_lds((const unsigned*)((const char*)(gbase) + (voff)[_i]), (PG8_LAS unsigned*)(lds + (bufoff) + ldsw + _i * 8192), 16, 0, 0); } while (0)
; #define PG8_LDA(dst, b, h) do { _Pragma("unroll") for (int m = 0; m < 4; ++m) _Pragma("unroll") for (int k = 0; k < 2; ++k) dst[m][k] = *(const PG8_LAS bf16x8*)(lds + PG8_SA(b, h) + aoff + m * 2048 + k * 1024); } while (0)
; #define PG8_LDB(dst, b, h) do { _Pragma("unroll") for (int n = 0; n < 2; ++n) _Pragma("unroll") for (int k = 0; k < 2; ++k) dst[n][k] = *(const PG8_LAS bf16x8*)(lds + PG8_SB(b, h) + boff + n * 2048 + k * 1024); } while (0)
; #define PG8_WAIT_L(n) asm volatile("s_waitcnt lgkmcnt(" #n ")" ::: "memory")
; #define PG8_BAR __builtin_amdgcn_s_barrier()
; #define PG8_SCHED __builtin_amdgcn_sched_barrier(0)
; template <class Epi, class Sched>
; __device__ __forceinline__ void gemm_phase(PG8_LAS unsigned char* lds, const Gemm g, const Sched& S, const Epi& E) {
;     ...
;         const bool has_next = S.next(ui + 1, nxt);
;         const char* nA = has_next ? (const char*)g.A + (size_t)nxt.pm * tstepA + (size_t)nxt.kc * cstep : cA; const char* nB = has_next ? (const char*)g.Bt + (size_t)nxt.pn * tstep + (size_t)nxt.kc * cstep : cB;
;         for (int t = 0; t < nt; t += 2) {
;             const bool last = (t == nt - 2);
;             const char* a1 = cA + (size_t)(t + 1) * kstep;
;             const char* a2 = last ? nA : cA + (size_t)(t + 2) * kstep; const char* b2 = last ? nB : cB + (size_t)(t + 2) * kstep;
;             const char* a3 = a2 + kstep; const char* b3 = b2 + kstep;
;             if (last && has_next) S.a_ready(nxt);
;             PG8_LDB(B0, 0, 0); PG8_SCHED; PG8_LDA(At, 0, 0); PG8_STAGE(PG8_SA(1, 1), a1 + hstep, voffA);
;             PG8_WAIT_L(8); PG8_BAR; PG8_WAIT_L(0); PG8_MMA(0, 0, At, B0); PG8_BAR; PG8_SCHED;
;             PG8_LDB(B1, 0, 1); PG8_STAGE(PG8_SB(0, 0), b2, voffB);
;             PG8_BAR; PG8_WAIT_L(0); PG8_MMA(0, 1, At, B1); PG8_BAR;
;             PG8_LDA(At, 0, 1); PG8_STAGE(PG8_SA(0, 0), a2, voffA);
;             PG8_BAR; PG8_WAIT_L(0); PG8_MMA(1, 0, At, B0); PG8_BAR; PG8_SCHED;
.LBB0_319:
	v_mov_b64_e32 v[0:1], s[56:57]
	s_ashr_i32 s25, s24, 31
	v_cmp_lt_i64_e32 vcc, s[26:27], v[0:1]
	s_lshl_b64 s[26:27], s[24:25], 19
	s_add_u32 s26, s8, s26
	s_addc_u32 s27, s9, s27
	s_and_b64 s[28:29], vcc, exec
	s_cselect_b32 s25, s27, s31
	s_cselect_b32 s56, s26, s30
	s_ashr_i32 s23, s22, 31
	s_lshl_b64 s[28:29], s[22:23], 19
	s_add_u32 s28, s6, s28
	s_addc_u32 s29, s7, s29
	s_and_b64 s[36:37], vcc, exec
	s_cselect_b32 s23, s29, s35
	s_cselect_b32 s57, s28, s34
	s_add_u32 s30, s30, 0x40080
	s_addc_u32 s31, s31, 0
	s_add_u32 s59, s34, 0x100
	s_addc_u32 s63, s35, 0
	s_mov_b32 s64, -2
	s_add_u32 s34, s30, 0xfffc0080
	s_addc_u32 s35, s31, -1
	s_add_i32 s65, 0, 0x10000
	v_add_u32_e32 v140, s65, v143
	ds_read_b128 v[146:149], v140
	ds_read_b128 v[150:153], v140 offset:1024
	ds_read_b128 v[154:157], v140 offset:2048
	ds_read_b128 v[158:161], v140 offset:3072
	s_cmp_eq_u32 s64, 12
	s_cselect_b32 s37, s25, s35
	s_cselect_b32 s36, s56, s34
	s_cselect_b32 s35, s23, s63
	s_cselect_b32 s34, s57, s59
	v_lshl_add_u64 v[140:141], s[30:31], 0, v[136:137]
	s_add_i32 m0, s21, 0xc000
	ds_read_b128 v[162:165], v145
	ds_read_b128 v[166:169], v145 offset:1024
	ds_read_b128 v[170:173], v145 offset:2048
	ds_read_b128 v[176:179], v145 offset:3072
	ds_read_b128 v[180:183], v145 offset:4096
	ds_read_b128 v[184:187], v145 offset:5120
	ds_read_b128 v[188:191], v145 offset:6144
	ds_read_b128 v[192:195], v145 offset:7168
	global_load_lds_dwordx4 v[140:141], off
	s_add_i32 m0, s21, 0xe000
	v_lshl_add_u64 v[140:141], s[30:31], 0, v[138:139]
	global_load_lds_dwordx4 v[140:141], off
	s_waitcnt lgkmcnt(8)
	s_barrier
	s_waitcnt lgkmcnt(7)
	v_mfma_f32_16x16x32_bf16 v[126:129], v[146:149], v[162:165], 0
	v_mfma_f32_16x16x32_bf16 v[122:125], v[154:157], v[162:165], 0
	s_waitcnt lgkmcnt(3)
	v_mfma_f32_16x16x32_bf16 v[118:121], v[146:149], v[170:173], 0
	v_mfma_f32_16x16x32_bf16 v[110:113], v[154:157], v[170:173], 0
	v_mfma_f32_16x16x32_bf16 v[102:105], v[146:149], v[180:183], 0
	v_mfma_f32_16x16x32_bf16 v[94:97], v[154:157], v[180:183], 0
	s_waitcnt lgkmcnt(0)
	v_mfma_f32_16x16x32_bf16 v[86:89], v[146:149], v[188:191], 0
	v_mfma_f32_16x16x32_bf16 v[78:81], v[154:157], v[188:191], 0
	v_mfma_f32_16x16x32_bf16 v[126:129], v[150:153], v[166:169], v[126:129]
	v_mfma_f32_16x16x32_bf16 v[122:125], v[158:161], v[166:169], v[122:125]
	v_mfma_f32_16x16x32_bf16 v[118:121], v[150:153], v[176:179], v[118:121]
	v_mfma_f32_16x16x32_bf16 v[110:113], v[158:161], v[176:179], v[110:113]
	v_mfma_f32_16x16x32_bf16 v[102:105], v[150:153], v[184:187], v[102:105]
	v_mfma_f32_16x16x32_bf16 v[94:97], v[158:161], v[184:187], v[94:97]
	v_mfma_f32_16x16x32_bf16 v[86:89], v[150:153], v[192:195], v[86:89]
	v_mfma_f32_16x16x32_bf16 v[78:81], v[158:161], v[192:195], v[78:81]
	s_barrier
	s_add_i32 s68, 0, 0x14000
	v_add_u32_e32 v140, s68, v143
	s_add_i32 s65, s65, s13
	ds_read_b128 v[196:199], v140
	ds_read_b128 v[200:203], v140 offset:1024
	ds_read_b128 v[204:207], v140 offset:2048
	ds_read_b128 v[208:211], v140 offset:3072
	v_lshl_add_u64 v[140:141], s[34:35], 0, v[48:49]
	s_mov_b32 m0, s65
	v_lshl_add_u64 v[212:213], s[34:35], 0, v[130:131]
	global_load_lds_dwordx4 v[140:141], off
	s_add_i32 m0, s65, 0x2000
	s_nop 0
	global_load_lds_dwordx4 v[212:213], off
	s_barrier
	s_waitcnt lgkmcnt(3)
	v_mfma_f32_16x16x32_bf16 v[114:117], v[196:199], v[162:165], 0
	s_waitcnt lgkmcnt(0)
	v_mfma_f32_16x16x32_bf16 v[106:109], v[204:207], v[162:165], 0
	v_mfma_f32_16x16x32_bf16 v[98:101], v[196:199], v[170:173], 0
	v_mfma_f32_16x16x32_bf16 v[90:93], v[204:207], v[170:173], 0
	v_mfma_f32_16x16x32_bf16 v[82:85], v[196:199], v[180:183], 0
	v_mfma_f32_16x16x32_bf16 v[74:77], v[204:207], v[180:183], 0
	v_mfma_f32_16x16x32_bf16 v[70:73], v[196:199], v[188:191], 0
	v_mfma_f32_16x16x32_bf16 v[66:69], v[204:207], v[188:191], 0
	v_mfma_f32_16x16x32_bf16 v[114:117], v[200:203], v[166:169], v[114:117]
	v_mfma_f32_16x16x32_bf16 v[106:109], v[208:211], v[166:169], v[106:109]
	v_mfma_f32_16x16x32_bf16 v[98:101], v[200:203], v[176:179], v[98:101]
	v_mfma_f32_16x16x32_bf16 v[90:93], v[208:211], v[176:179], v[90:93]
	v_mfma_f32_16x16x32_bf16 v[82:85], v[200:203], v[184:187], v[82:85]
	v_mfma_f32_16x16x32_bf16 v[74:77], v[208:211], v[184:187], v[74:77]
	v_mfma_f32_16x16x32_bf16 v[70:73], v[200:203], v[192:195], v[70:73]
	v_mfma_f32_16x16x32_bf16 v[66:69], v[208:211], v[192:195], v[66:69]
	s_mov_b32 m0, s21
	v_lshl_add_u64 v[214:215], s[36:37], 0, v[134:135]
	s_barrier
	ds_read_b128 v[162:165], v145 offset:16384
	ds_read_b128 v[166:169], v145 offset:17408
	ds_read_b128 v[170:173], v145 offset:18432
	ds_read_b128 v[176:179], v145 offset:19456
	ds_read_b128 v[180:183], v145 offset:20480
	ds_read_b128 v[184:187], v145 offset:21504
	ds_read_b128 v[188:191], v145 offset:22528
	ds_read_b128 v[192:195], v145 offset:23552
	global_load_lds_dwordx4 v[214:215], off
	s_mov_b32 m0, s46
	v_lshl_add_u64 v[216:217], s[36:37], 0, v[132:133]
	global_load_lds_dwordx4 v[216:217], off
	s_barrier
	s_waitcnt lgkmcnt(7)
	v_mfma_f32_16x16x32_bf16 v[62:65], v[146:149], v[162:165], 0
	v_mfma_f32_16x16x32_bf16 v[58:61], v[154:157], v[162:165], 0
	s_waitcnt lgkmcnt(3)
	v_mfma_f32_16x16x32_bf16 v[54:57], v[146:149], v[170:173], 0
	v_mfma_f32_16x16x32_bf16 v[44:47], v[154:157], v[170:173], 0
	v_mfma_f32_16x16x32_bf16 v[36:39], v[146:149], v[180:183], 0
	v_mfma_f32_16x16x32_bf16 v[28:31], v[154:157], v[180:183], 0
	s_waitcnt lgkmcnt(0)
	v_mfma_f32_16x16x32_bf16 v[20:23], v[146:149], v[188:191], 0
	v_mfma_f32_16x16x32_bf16 v[12:15], v[154:157], v[188:191], 0
	v_mfma_f32_16x16x32_bf16 v[62:65], v[150:153], v[166:169], v[62:65]
	v_mfma_f32_16x16x32_bf16 v[58:61], v[158:161], v[166:169], v[58:61]
	v_mfma_f32_16x16x32_bf16 v[54:57], v[150:153], v[176:179], v[54:57]
	v_mfma_f32_16x16x32_bf16 v[44:47], v[158:161], v[176:179], v[44:47]
	v_mfma_f32_16x16x32_bf16 v[36:39], v[150:153], v[184:187], v[36:39]
	v_mfma_f32_16x16x32_bf16 v[28:31], v[158:161], v[184:187], v[28:31]
	v_mfma_f32_16x16x32_bf16 v[20:23], v[150:153], v[192:195], v[20:23]
	v_mfma_f32_16x16x32_bf16 v[12:15], v[158:161], v[192:195], v[12:15]
	s_barrier
; #define PG8_STAGE(bufoff, gbase, voff) do { _Pragma("unroll") for (int _i = 0; _i < 2; ++_i) \
;         __builtin_amdgcn_global_load_lds((const unsigned*)((const char*)(gbase) + (voff)[_i]), (PG8_LAS unsigned*)(lds + (bufoff) + ldsw + _i * 8192), 16, 0, 0); } while (0)
; #define PG8_LDA(dst, b, h) do { _Pragma("unroll") for (int m = 0; m < 4; ++m) _Pragma("unroll") for (int k = 0; k < 2; ++k) dst[m][k] = *(const PG8_LAS bf16x8*)(lds + PG8_SA(b, h) + aoff + m * 2048 + k * 1024); } while (0)
; #define PG8_LDB(dst, b, h) do { _Pragma("unroll") for (int n = 0; n < 2; ++n) _Pragma("unroll") for (int k = 0; k < 2; ++k) dst[n][k] = *(const PG8_LAS bf16x8*)(lds + PG8_SB(b, h) + boff + n * 2048 + k * 1024); } while (0)
; #define PG8_MMA(ai, bj, At, Bt) do { __builtin_amdgcn_s_setprio(1); _Pragma("unroll") for (int m = 0; m < 4; ++m) _Pragma("unroll") for (int n = 0; n < 2; ++n) _Pragma("unroll") for (int k = 0; k < 2; ++k) \
;         acc[ai][bj][m][n] = __builtin_amdgcn_mfma_f32_16x16x32_bf16(Bt[n][k], At[m][k], acc[ai][bj][m][n], 0, 0, 0); __builtin_amdgcn_s_setprio(0); } while (0)
; #define PG8_WAIT_V(n) asm volatile("s_waitcnt vmcnt(" #n ")" ::: "memory")
; #define PG8_WAIT_L(n) asm volatile("s_waitcnt lgkmcnt(" #n ")" ::: "memory")
; #define PG8_BAR __builtin_amdgcn_s_barrier()
; #define PG8_SCHED __builtin_amdgcn_sched_barrier(0)
; template <class Epi, class Sched>
; __device__ __forceinline__ void gemm_phase(PG8_LAS unsigned char* lds, const Gemm g, const Sched& S, const Epi& E) {
;     ...
;             PG8_STAGE(PG8_SB(0, 1), b2 + hstep, voffB);
;             PG8_WAIT_V(6); PG8_BAR; PG8_MMA(1, 1, At, B1); PG8_BAR;
;             PG8_LDB(B0, 1, 0); PG8_SCHED; PG8_LDA(At, 1, 0); PG8_STAGE(PG8_SA(0, 1), a2 + hstep, voffA);
;             PG8_WAIT_L(8); PG8_BAR; PG8_WAIT_L(0); PG8_MMA(0, 0, At, B0); PG8_BAR; PG8_SCHED;
;             PG8_LDB(B1, 1, 1); PG8_STAGE(PG8_SB(1, 0), b3, voffB);
;             PG8_BAR; PG8_WAIT_L(0); PG8_MMA(0, 1, At, B1); PG8_BAR;
;             PG8_LDA(At, 1, 1); PG8_STAGE(PG8_SA(1, 0), a3, voffA);
	s_add_u32 s66, s34, 0x40000
	s_addc_u32 s67, s35, 0
	s_add_i32 s65, s68, s13
	s_mov_b32 m0, s65
	v_lshl_add_u64 v[146:147], s[66:67], 0, v[48:49]
	global_load_lds_dwordx4 v[146:147], off
	s_add_i32 m0, s65, 0x2000
	v_lshl_add_u64 v[146:147], s[66:67], 0, v[130:131]
	global_load_lds_dwordx4 v[146:147], off
	s_waitcnt vmcnt(6)
	s_barrier
	v_mfma_f32_16x16x32_bf16 v[50:53], v[196:199], v[162:165], 0
	v_mfma_f32_16x16x32_bf16 v[40:43], v[204:207], v[162:165], 0
	v_mfma_f32_16x16x32_bf16 v[32:35], v[196:199], v[170:173], 0
	v_mfma_f32_16x16x32_bf16 v[24:27], v[204:207], v[170:173], 0
	v_mfma_f32_16x16x32_bf16 v[16:19], v[196:199], v[180:183], 0
	v_mfma_f32_16x16x32_bf16 v[8:11], v[204:207], v[180:183], 0
	v_mfma_f32_16x16x32_bf16 v[4:7], v[196:199], v[188:191], 0
	v_mfma_f32_16x16x32_bf16 v[0:3], v[204:207], v[188:191], 0
	v_mfma_f32_16x16x32_bf16 v[50:53], v[200:203], v[166:169], v[50:53]
	v_mfma_f32_16x16x32_bf16 v[40:43], v[208:211], v[166:169], v[40:43]
	v_mfma_f32_16x16x32_bf16 v[32:35], v[200:203], v[176:179], v[32:35]
	v_mfma_f32_16x16x32_bf16 v[24:27], v[208:211], v[176:179], v[24:27]
	v_mfma_f32_16x16x32_bf16 v[16:19], v[200:203], v[184:187], v[16:19]
	v_mfma_f32_16x16x32_bf16 v[8:11], v[208:211], v[184:187], v[8:11]
	v_mfma_f32_16x16x32_bf16 v[4:7], v[200:203], v[192:195], v[4:7]
	v_mfma_f32_16x16x32_bf16 v[0:3], v[208:211], v[192:195], v[0:3]
	s_add_i32 s65, 0, 0x18000
	v_add_u32_e32 v158, s65, v143
	s_barrier
	ds_read_b128 v[146:149], v158
	ds_read_b128 v[150:153], v158 offset:1024
	ds_read_b128 v[154:157], v158 offset:2048
	ds_read_b128 v[158:161], v158 offset:3072
	s_add_u32 s36, s36, 0x40000
	s_addc_u32 s37, s37, 0
	s_mov_b32 m0, s47
	v_lshl_add_u64 v[196:197], s[36:37], 0, v[134:135]
	ds_read_b128 v[162:165], v145 offset:32768
	ds_read_b128 v[166:169], v145 offset:33792
	ds_read_b128 v[170:173], v145 offset:34816
	ds_read_b128 v[176:179], v145 offset:35840
	ds_read_b128 v[180:183], v145 offset:36864
	ds_read_b128 v[184:187], v145 offset:37888
	ds_read_b128 v[188:191], v145 offset:38912
	ds_read_b128 v[192:195], v145 offset:39936
	global_load_lds_dwordx4 v[196:197], off
	s_mov_b32 m0, s48
	v_lshl_add_u64 v[196:197], s[36:37], 0, v[132:133]
	global_load_lds_dwordx4 v[196:197], off
	s_waitcnt lgkmcnt(8)
	s_barrier
	s_waitcnt lgkmcnt(7)
	v_mfma_f32_16x16x32_bf16 v[126:129], v[146:149], v[162:165], v[126:129]
	v_mfma_f32_16x16x32_bf16 v[122:125], v[154:157], v[162:165], v[122:125]
	s_waitcnt lgkmcnt(3)
	v_mfma_f32_16x16x32_bf16 v[118:121], v[146:149], v[170:173], v[118:121]
	v_mfma_f32_16x16x32_bf16 v[110:113], v[154:157], v[170:173], v[110:113]
	v_mfma_f32_16x16x32_bf16 v[102:105], v[146:149], v[180:183], v[102:105]
	v_mfma_f32_16x16x32_bf16 v[94:97], v[154:157], v[180:183], v[94:97]
	s_waitcnt lgkmcnt(0)
	v_mfma_f32_16x16x32_bf16 v[86:89], v[146:149], v[188:191], v[86:89]
	v_mfma_f32_16x16x32_bf16 v[78:81], v[154:157], v[188:191], v[78:81]
	v_mfma_f32_16x16x32_bf16 v[126:129], v[150:153], v[166:169], v[126:129]
	v_mfma_f32_16x16x32_bf16 v[122:125], v[158:161], v[166:169], v[122:125]
	v_mfma_f32_16x16x32_bf16 v[118:121], v[150:153], v[176:179], v[118:121]
	v_mfma_f32_16x16x32_bf16 v[110:113], v[158:161], v[176:179], v[110:113]
	v_mfma_f32_16x16x32_bf16 v[102:105], v[150:153], v[184:187], v[102:105]
	v_mfma_f32_16x16x32_bf16 v[94:97], v[158:161], v[184:187], v[94:97]
	v_mfma_f32_16x16x32_bf16 v[86:89], v[150:153], v[192:195], v[86:89]
	v_mfma_f32_16x16x32_bf16 v[78:81], v[158:161], v[192:195], v[78:81]
	s_barrier
	s_add_i32 s36, 0, 0x1c000
	s_add_i32 s37, s65, s13
	v_add_u32_e32 v175, s36, v143
	v_lshl_add_u64 v[140:141], v[140:141], 0, s[0:1]
	s_mov_b32 m0, s37
	ds_read_b128 v[196:199], v175
	ds_read_b128 v[200:203], v175 offset:1024
	ds_read_b128 v[204:207], v175 offset:2048
	ds_read_b128 v[208:211], v175 offset:3072
	global_load_lds_dwordx4 v[140:141], off
	s_add_i32 m0, s37, 0x2000
	v_lshl_add_u64 v[140:141], v[212:213], 0, s[0:1]
	global_load_lds_dwordx4 v[140:141], off
	s_barrier
	s_waitcnt lgkmcnt(3)
	v_mfma_f32_16x16x32_bf16 v[114:117], v[196:199], v[162:165], v[114:117]
	s_waitcnt lgkmcnt(0)
	v_mfma_f32_16x16x32_bf16 v[106:109], v[204:207], v[162:165], v[106:109]
	v_mfma_f32_16x16x32_bf16 v[98:101], v[196:199], v[170:173], v[98:101]
	v_mfma_f32_16x16x32_bf16 v[90:93], v[204:207], v[170:173], v[90:93]
	v_mfma_f32_16x16x32_bf16 v[82:85], v[196:199], v[180:183], v[82:85]
	v_mfma_f32_16x16x32_bf16 v[74:77], v[204:207], v[180:183], v[74:77]
	v_mfma_f32_16x16x32_bf16 v[70:73], v[196:199], v[188:191], v[70:73]
	v_mfma_f32_16x16x32_bf16 v[66:69], v[204:207], v[188:191], v[66:69]
	v_mfma_f32_16x16x32_bf16 v[114:117], v[200:203], v[166:169], v[114:117]
	v_mfma_f32_16x16x32_bf16 v[106:109], v[208:211], v[166:169], v[106:109]
	v_mfma_f32_16x16x32_bf16 v[98:101], v[200:203], v[176:179], v[98:101]
	v_mfma_f32_16x16x32_bf16 v[90:93], v[208:211], v[176:179], v[90:93]
	v_mfma_f32_16x16x32_bf16 v[82:85], v[200:203], v[184:187], v[82:85]
	v_mfma_f32_16x16x32_bf16 v[74:77], v[208:211], v[184:187], v[74:77]
	v_mfma_f32_16x16x32_bf16 v[70:73], v[200:203], v[192:195], v[70:73]
	v_mfma_f32_16x16x32_bf16 v[66:69], v[208:211], v[192:195], v[66:69]
	s_mov_b32 m0, s49
	v_lshl_add_u64 v[140:141], v[214:215], 0, s[0:1]
	s_barrier
	ds_read_b128 v[162:165], v145 offset:49152
	ds_read_b128 v[166:169], v145 offset:50176
	ds_read_b128 v[170:173], v145 offset:51200
	ds_read_b128 v[176:179], v145 offset:52224
	ds_read_b128 v[180:183], v145 offset:53248
	ds_read_b128 v[184:187], v145 offset:54272
	ds_read_b128 v[188:191], v145 offset:55296
	ds_read_b128 v[192:195], v145 offset:56320
	global_load_lds_dwordx4 v[140:141], off
	s_mov_b32 m0, s50
	v_lshl_add_u64 v[140:141], v[216:217], 0, s[0:1]
	global_load_lds_dwordx4 v[140:141], off
	s_barrier
; #define PG8_STAGE(bufoff, gbase, voff) do { _Pragma("unroll") for (int _i = 0; _i < 2; ++_i) \
;         __builtin_amdgcn_global_load_lds((const unsigned*)((const char*)(gbase) + (voff)[_i]), (PG8_LAS unsigned*)(lds + (bufoff) + ldsw + _i * 8192), 16, 0, 0); } while (0)
; #define PG8_LDA(dst, b, h) do { _Pragma("unroll") for (int m = 0; m < 4; ++m) _Pragma("unroll") for (int k = 0; k < 2; ++k) dst[m][k] = *(const PG8_LAS bf16x8*)(lds + PG8_SA(b, h) + aoff + m * 2048 + k * 1024); } while (0)
; #define PG8_LDB(dst, b, h) do { _Pragma("unroll") for (int n = 0; n < 2; ++n) _Pragma("unroll") for (int k = 0; k < 2; ++k) dst[n][k] = *(const PG8_LAS bf16x8*)(lds + PG8_SB(b, h) + boff + n * 2048 + k * 1024); } while (0)
; #define PG8_MMA(ai, bj, At, Bt) do { __builtin_amdgcn_s_setprio(1); _Pragma("unroll") for (int m = 0; m < 4; ++m) _Pragma("unroll") for (int n = 0; n < 2; ++n) _Pragma("unroll") for (int k = 0; k < 2; ++k) \
;         acc[ai][bj][m][n] = __builtin_amdgcn_mfma_f32_16x16x32_bf16(Bt[n][k], At[m][k], acc[ai][bj][m][n], 0, 0, 0); __builtin_amdgcn_s_setprio(0); } while (0)
; #define PG8_WAIT_V(n) asm volatile("s_waitcnt vmcnt(" #n ")" ::: "memory")
; #define PG8_WAIT_L(n) asm volatile("s_waitcnt lgkmcnt(" #n ")" ::: "memory")
; #define PG8_BAR __builtin_amdgcn_s_barrier()
; #define PG8_SCHED __builtin_amdgcn_sched_barrier(0)
; template <class Epi, class Sched>
; __device__ __forceinline__ void gemm_phase(PG8_LAS unsigned char* lds, const Gemm g, const Sched& S, const Epi& E) {
;     ...
;             const bool last = (t == nt - 2);
;             const char* a1 = cA + (size_t)(t + 1) * kstep;
;             const char* a2 = last ? nA : cA + (size_t)(t + 2) * kstep; const char* b2 = last ? nB : cB + (size_t)(t + 2) * kstep;
;             const char* a3 = a2 + kstep; const char* b3 = b2 + kstep;
;             if (last && has_next) S.a_ready(nxt);
;             PG8_LDB(B0, 0, 0); PG8_SCHED; PG8_LDA(At, 0, 0); PG8_STAGE(PG8_SA(1, 1), a1 + hstep, voffA);
;             PG8_WAIT_L(8); PG8_BAR; PG8_WAIT_L(0); PG8_MMA(0, 0, At, B0); PG8_BAR; PG8_SCHED;
;             PG8_LDB(B1, 0, 1); PG8_STAGE(PG8_SB(0, 0), b2, voffB);
;     ...
;             PG8_BAR; PG8_WAIT_L(0); PG8_MMA(1, 0, At, B0); PG8_BAR; PG8_SCHED;
;             PG8_STAGE(PG8_SB(1, 1), b3 + hstep, voffB);
;             PG8_WAIT_V(6); PG8_BAR; PG8_MMA(1, 1, At, B1); PG8_BAR;
;         }
	s_waitcnt lgkmcnt(7)
	v_mfma_f32_16x16x32_bf16 v[62:65], v[146:149], v[162:165], v[62:65]
	v_mfma_f32_16x16x32_bf16 v[58:61], v[154:157], v[162:165], v[58:61]
	s_waitcnt lgkmcnt(3)
	v_mfma_f32_16x16x32_bf16 v[54:57], v[146:149], v[170:173], v[54:57]
	v_mfma_f32_16x16x32_bf16 v[44:47], v[154:157], v[170:173], v[44:47]
	v_mfma_f32_16x16x32_bf16 v[36:39], v[146:149], v[180:183], v[36:39]
	v_mfma_f32_16x16x32_bf16 v[28:31], v[154:157], v[180:183], v[28:31]
	s_waitcnt lgkmcnt(0)
	v_mfma_f32_16x16x32_bf16 v[20:23], v[146:149], v[188:191], v[20:23]
	v_mfma_f32_16x16x32_bf16 v[12:15], v[154:157], v[188:191], v[12:15]
	v_mfma_f32_16x16x32_bf16 v[62:65], v[150:153], v[166:169], v[62:65]
	v_mfma_f32_16x16x32_bf16 v[58:61], v[158:161], v[166:169], v[58:61]
	v_mfma_f32_16x16x32_bf16 v[54:57], v[150:153], v[176:179], v[54:57]
	v_mfma_f32_16x16x32_bf16 v[44:47], v[158:161], v[176:179], v[44:47]
	v_mfma_f32_16x16x32_bf16 v[36:39], v[150:153], v[184:187], v[36:39]
	v_mfma_f32_16x16x32_bf16 v[28:31], v[158:161], v[184:187], v[28:31]
	v_mfma_f32_16x16x32_bf16 v[20:23], v[150:153], v[192:195], v[20:23]
	v_mfma_f32_16x16x32_bf16 v[12:15], v[158:161], v[192:195], v[12:15]
	s_barrier
	s_add_u32 s34, s34, 0x40080
	s_addc_u32 s35, s35, 0
	s_add_i32 s36, s36, s13
	s_mov_b32 m0, s36
	v_lshl_add_u64 v[140:141], s[34:35], 0, v[48:49]
	global_load_lds_dwordx4 v[140:141], off
	s_add_i32 m0, s36, 0x2000
	v_lshl_add_u64 v[140:141], s[34:35], 0, v[130:131]
	global_load_lds_dwordx4 v[140:141], off
	s_waitcnt vmcnt(6)
	s_barrier
	v_mfma_f32_16x16x32_bf16 v[50:53], v[196:199], v[162:165], v[50:53]
	v_mfma_f32_16x16x32_bf16 v[40:43], v[204:207], v[162:165], v[40:43]
	v_mfma_f32_16x16x32_bf16 v[32:35], v[196:199], v[170:173], v[32:35]
	v_mfma_f32_16x16x32_bf16 v[24:27], v[204:207], v[170:173], v[24:27]
	v_mfma_f32_16x16x32_bf16 v[16:19], v[196:199], v[180:183], v[16:19]
	v_mfma_f32_16x16x32_bf16 v[8:11], v[204:207], v[180:183], v[8:11]
	v_mfma_f32_16x16x32_bf16 v[4:7], v[196:199], v[188:191], v[4:7]
	v_mfma_f32_16x16x32_bf16 v[0:3], v[204:207], v[188:191], v[0:3]
	v_mfma_f32_16x16x32_bf16 v[50:53], v[200:203], v[166:169], v[50:53]
	v_mfma_f32_16x16x32_bf16 v[40:43], v[208:211], v[166:169], v[40:43]
	v_mfma_f32_16x16x32_bf16 v[32:35], v[200:203], v[176:179], v[32:35]
	v_mfma_f32_16x16x32_bf16 v[24:27], v[208:211], v[176:179], v[24:27]
	v_mfma_f32_16x16x32_bf16 v[16:19], v[200:203], v[184:187], v[16:19]
	v_mfma_f32_16x16x32_bf16 v[8:11], v[208:211], v[184:187], v[8:11]
	v_mfma_f32_16x16x32_bf16 v[4:7], v[200:203], v[192:195], v[4:7]
	v_mfma_f32_16x16x32_bf16 v[0:3], v[208:211], v[192:195], v[0:3]
	s_add_i32 s64, s64, 2
	s_add_u32 s30, s30, 0x100
	s_addc_u32 s31, s31, 0
	s_add_u32 s59, s59, 0x100
	s_addc_u32 s63, s63, 0
	s_cmp_gt_u32 s64, 13
	s_barrier
	s_cbranch_scc1 .Lkpeel_exit_320
.LBB0_320:
	s_add_u32 s34, s30, 0xfffc0080
	s_addc_u32 s35, s31, -1
	s_add_i32 s65, 0, 0x10000
	v_add_u32_e32 v140, s65, v143
	ds_read_b128 v[146:149], v140
	ds_read_b128 v[150:153], v140 offset:1024
	ds_read_b128 v[154:157], v140 offset:2048
	ds_read_b128 v[158:161], v140 offset:3072
	s_cmp_eq_u32 s64, 12
	s_cselect_b32 s37, s25, s35
	s_cselect_b32 s36, s56, s34
	s_cselect_b32 s35, s23, s63
	s_cselect_b32 s34, s57, s59
	v_lshl_add_u64 v[140:141], s[30:31], 0, v[136:137]
	s_add_i32 m0, s21, 0xc000
	ds_read_b128 v[162:165], v145
	ds_read_b128 v[166:169], v145 offset:1024
	ds_read_b128 v[170:173], v145 offset:2048
	ds_read_b128 v[176:179], v145 offset:3072
	ds_read_b128 v[180:183], v145 offset:4096
	ds_read_b128 v[184:187], v145 offset:5120
	ds_read_b128 v[188:191], v145 offset:6144
	ds_read_b128 v[192:195], v145 offset:7168
	global_load_lds_dwordx4 v[140:141], off
	s_add_i32 m0, s21, 0xe000
	v_lshl_add_u64 v[140:141], s[30:31], 0, v[138:139]
	global_load_lds_dwordx4 v[140:141], off
	s_waitcnt lgkmcnt(8)
	s_barrier
	s_waitcnt lgkmcnt(7)
	v_mfma_f32_16x16x32_bf16 v[126:129], v[146:149], v[162:165], v[126:129]
	v_mfma_f32_16x16x32_bf16 v[122:125], v[154:157], v[162:165], v[122:125]
	s_waitcnt lgkmcnt(3)
	v_mfma_f32_16x16x32_bf16 v[118:121], v[146:149], v[170:173], v[118:121]
	v_mfma_f32_16x16x32_bf16 v[110:113], v[154:157], v[170:173], v[110:113]
	v_mfma_f32_16x16x32_bf16 v[102:105], v[146:149], v[180:183], v[102:105]
	v_mfma_f32_16x16x32_bf16 v[94:97], v[154:157], v[180:183], v[94:97]
	s_waitcnt lgkmcnt(0)
	v_mfma_f32_16x16x32_bf16 v[86:89], v[146:149], v[188:191], v[86:89]
	v_mfma_f32_16x16x32_bf16 v[78:81], v[154:157], v[188:191], v[78:81]
	v_mfma_f32_16x16x32_bf16 v[126:129], v[150:153], v[166:169], v[126:129]
	v_mfma_f32_16x16x32_bf16 v[122:125], v[158:161], v[166:169], v[122:125]
	v_mfma_f32_16x16x32_bf16 v[118:121], v[150:153], v[176:179], v[118:121]
	v_mfma_f32_16x16x32_bf16 v[110:113], v[158:161], v[176:179], v[110:113]
	v_mfma_f32_16x16x32_bf16 v[102:105], v[150:153], v[184:187], v[102:105]
	v_mfma_f32_16x16x32_bf16 v[94:97], v[158:161], v[184:187], v[94:97]
	v_mfma_f32_16x16x32_bf16 v[86:89], v[150:153], v[192:195], v[86:89]
	v_mfma_f32_16x16x32_bf16 v[78:81], v[158:161], v[192:195], v[78:81]
	s_barrier
	s_add_i32 s68, 0, 0x14000
	v_add_u32_e32 v140, s68, v143
	s_add_i32 s65, s65, s13
	ds_read_b128 v[196:199], v140
	ds_read_b128 v[200:203], v140 offset:1024
	ds_read_b128 v[204:207], v140 offset:2048
	ds_read_b128 v[208:211], v140 offset:3072
	v_lshl_add_u64 v[140:141], s[34:35], 0, v[48:49]
	s_mov_b32 m0, s65
	v_lshl_add_u64 v[212:213], s[34:35], 0, v[130:131]
	global_load_lds_dwordx4 v[140:141], off
	s_add_i32 m0, s65, 0x2000
	s_nop 0
	global_load_lds_dwordx4 v[212:213], off
	s_barrier
; #define PG8_STAGE(bufoff, gbase, voff) do { _Pragma("unroll") for (int _i = 0; _i < 2; ++_i) \
;         __builtin_amdgcn_global_load_lds((const unsigned*)((const char*)(gbase) + (voff)[_i]), (PG8_LAS unsigned*)(lds + (bufoff) + ldsw + _i * 8192), 16, 0, 0); } while (0)
; #define PG8_LDA(dst, b, h) do { _Pragma("unroll") for (int m = 0; m < 4; ++m) _Pragma("unroll") for (int k = 0; k < 2; ++k) dst[m][k] = *(const PG8_LAS bf16x8*)(lds + PG8_SA(b, h) + aoff + m * 2048 + k * 1024); } while (0)
; #define PG8_LDB(dst, b, h) do { _Pragma("unroll") for (int n = 0; n < 2; ++n) _Pragma("unroll") for (int k = 0; k < 2; ++k) dst[n][k] = *(const PG8_LAS bf16x8*)(lds + PG8_SB(b, h) + boff + n * 2048 + k * 1024); } while (0)
; #define PG8_MMA(ai, bj, At, Bt) do { __builtin_amdgcn_s_setprio(1); _Pragma("unroll") for (int m = 0; m < 4; ++m) _Pragma("unroll") for (int n = 0; n < 2; ++n) _Pragma("unroll") for (int k = 0; k < 2; ++k) \
;         acc[ai][bj][m][n] = __builtin_amdgcn_mfma_f32_16x16x32_bf16(Bt[n][k], At[m][k], acc[ai][bj][m][n], 0, 0, 0); __builtin_amdgcn_s_setprio(0); } while (0)
; #define PG8_WAIT_V(n) asm volatile("s_waitcnt vmcnt(" #n ")" ::: "memory")
; #define PG8_WAIT_L(n) asm volatile("s_waitcnt lgkmcnt(" #n ")" ::: "memory")
; #define PG8_BAR __builtin_amdgcn_s_barrier()
; #define PG8_SCHED __builtin_amdgcn_sched_barrier(0)
; template <class Epi, class Sched>
; __device__ __forceinline__ void gemm_phase(PG8_LAS unsigned char* lds, const Gemm g, const Sched& S, const Epi& E) {
;     ...
;             PG8_BAR; PG8_WAIT_L(0); PG8_MMA(0, 1, At, B1); PG8_BAR;
;             PG8_LDA(At, 0, 1); PG8_STAGE(PG8_SA(0, 0), a2, voffA);
;             PG8_BAR; PG8_WAIT_L(0); PG8_MMA(1, 0, At, B0); PG8_BAR; PG8_SCHED;
;             PG8_STAGE(PG8_SB(0, 1), b2 + hstep, voffB);
;             PG8_WAIT_V(6); PG8_BAR; PG8_MMA(1, 1, At, B1); PG8_BAR;
;             PG8_LDB(B0, 1, 0); PG8_SCHED; PG8_LDA(At, 1, 0); PG8_STAGE(PG8_SA(0, 1), a2 + hstep, voffA);
;             PG8_WAIT_L(8); PG8_BAR; PG8_WAIT_L(0); PG8_MMA(0, 0, At, B0); PG8_BAR; PG8_SCHED;
	s_waitcnt lgkmcnt(3)
	v_mfma_f32_16x16x32_bf16 v[114:117], v[196:199], v[162:165], v[114:117]
	s_waitcnt lgkmcnt(0)
	v_mfma_f32_16x16x32_bf16 v[106:109], v[204:207], v[162:165], v[106:109]
	v_mfma_f32_16x16x32_bf16 v[98:101], v[196:199], v[170:173], v[98:101]
	v_mfma_f32_16x16x32_bf16 v[90:93], v[204:207], v[170:173], v[90:93]
	v_mfma_f32_16x16x32_bf16 v[82:85], v[196:199], v[180:183], v[82:85]
	v_mfma_f32_16x16x32_bf16 v[74:77], v[204:207], v[180:183], v[74:77]
	v_mfma_f32_16x16x32_bf16 v[70:73], v[196:199], v[188:191], v[70:73]
	v_mfma_f32_16x16x32_bf16 v[66:69], v[204:207], v[188:191], v[66:69]
	v_mfma_f32_16x16x32_bf16 v[114:117], v[200:203], v[166:169], v[114:117]
	v_mfma_f32_16x16x32_bf16 v[106:109], v[208:211], v[166:169], v[106:109]
	v_mfma_f32_16x16x32_bf16 v[98:101], v[200:203], v[176:179], v[98:101]
	v_mfma_f32_16x16x32_bf16 v[90:93], v[208:211], v[176:179], v[90:93]
	v_mfma_f32_16x16x32_bf16 v[82:85], v[200:203], v[184:187], v[82:85]
	v_mfma_f32_16x16x32_bf16 v[74:77], v[208:211], v[184:187], v[74:77]
	v_mfma_f32_16x16x32_bf16 v[70:73], v[200:203], v[192:195], v[70:73]
	v_mfma_f32_16x16x32_bf16 v[66:69], v[208:211], v[192:195], v[66:69]
	s_mov_b32 m0, s21
	v_lshl_add_u64 v[214:215], s[36:37], 0, v[134:135]
	s_barrier
	ds_read_b128 v[162:165], v145 offset:16384
	ds_read_b128 v[166:169], v145 offset:17408
	ds_read_b128 v[170:173], v145 offset:18432
	ds_read_b128 v[176:179], v145 offset:19456
	ds_read_b128 v[180:183], v145 offset:20480
	ds_read_b128 v[184:187], v145 offset:21504
	ds_read_b128 v[188:191], v145 offset:22528
	ds_read_b128 v[192:195], v145 offset:23552
	global_load_lds_dwordx4 v[214:215], off
	s_mov_b32 m0, s46
	v_lshl_add_u64 v[216:217], s[36:37], 0, v[132:133]
	global_load_lds_dwordx4 v[216:217], off
	s_barrier
	s_waitcnt lgkmcnt(7)
	v_mfma_f32_16x16x32_bf16 v[62:65], v[146:149], v[162:165], v[62:65]
	v_mfma_f32_16x16x32_bf16 v[58:61], v[154:157], v[162:165], v[58:61]
	s_waitcnt lgkmcnt(3)
	v_mfma_f32_16x16x32_bf16 v[54:57], v[146:149], v[170:173], v[54:57]
	v_mfma_f32_16x16x32_bf16 v[44:47], v[154:157], v[170:173], v[44:47]
	v_mfma_f32_16x16x32_bf16 v[36:39], v[146:149], v[180:183], v[36:39]
	v_mfma_f32_16x16x32_bf16 v[28:31], v[154:157], v[180:183], v[28:31]
	s_waitcnt lgkmcnt(0)
	v_mfma_f32_16x16x32_bf16 v[20:23], v[146:149], v[188:191], v[20:23]
	v_mfma_f32_16x16x32_bf16 v[12:15], v[154:157], v[188:191], v[12:15]
	v_mfma_f32_16x16x32_bf16 v[62:65], v[150:153], v[166:169], v[62:65]
	v_mfma_f32_16x16x32_bf16 v[58:61], v[158:161], v[166:169], v[58:61]
	v_mfma_f32_16x16x32_bf16 v[54:57], v[150:153], v[176:179], v[54:57]
	v_mfma_f32_16x16x32_bf16 v[44:47], v[158:161], v[176:179], v[44:47]
	v_mfma_f32_16x16x32_bf16 v[36:39], v[150:153], v[184:187], v[36:39]
	v_mfma_f32_16x16x32_bf16 v[28:31], v[158:161], v[184:187], v[28:31]
	v_mfma_f32_16x16x32_bf16 v[20:23], v[150:153], v[192:195], v[20:23]
	v_mfma_f32_16x16x32_bf16 v[12:15], v[158:161], v[192:195], v[12:15]
	s_barrier
	s_add_u32 s66, s34, 0x40000
	s_addc_u32 s67, s35, 0
	s_add_i32 s65, s68, s13
	s_mov_b32 m0, s65
	v_lshl_add_u64 v[146:147], s[66:67], 0, v[48:49]
	global_load_lds_dwordx4 v[146:147], off
	s_add_i32 m0, s65, 0x2000
	v_lshl_add_u64 v[146:147], s[66:67], 0, v[130:131]
	global_load_lds_dwordx4 v[146:147], off
	s_waitcnt vmcnt(6)
	s_barrier
	v_mfma_f32_16x16x32_bf16 v[50:53], v[196:199], v[162:165], v[50:53]
	v_mfma_f32_16x16x32_bf16 v[40:43], v[204:207], v[162:165], v[40:43]
	v_mfma_f32_16x16x32_bf16 v[32:35], v[196:199], v[170:173], v[32:35]
	v_mfma_f32_16x16x32_bf16 v[24:27], v[204:207], v[170:173], v[24:27]
	v_mfma_f32_16x16x32_bf16 v[16:19], v[196:199], v[180:183], v[16:19]
	v_mfma_f32_16x16x32_bf16 v[8:11], v[204:207], v[180:183], v[8:11]
	v_mfma_f32_16x16x32_bf16 v[4:7], v[196:199], v[188:191], v[4:7]
	v_mfma_f32_16x16x32_bf16 v[0:3], v[204:207], v[188:191], v[0:3]
	v_mfma_f32_16x16x32_bf16 v[50:53], v[200:203], v[166:169], v[50:53]
	v_mfma_f32_16x16x32_bf16 v[40:43], v[208:211], v[166:169], v[40:43]
	v_mfma_f32_16x16x32_bf16 v[32:35], v[200:203], v[176:179], v[32:35]
	v_mfma_f32_16x16x32_bf16 v[24:27], v[208:211], v[176:179], v[24:27]
	v_mfma_f32_16x16x32_bf16 v[16:19], v[200:203], v[184:187], v[16:19]
	v_mfma_f32_16x16x32_bf16 v[8:11], v[208:211], v[184:187], v[8:11]
	v_mfma_f32_16x16x32_bf16 v[4:7], v[200:203], v[192:195], v[4:7]
	v_mfma_f32_16x16x32_bf16 v[0:3], v[208:211], v[192:195], v[0:3]
	s_add_i32 s65, 0, 0x18000
	v_add_u32_e32 v158, s65, v143
	s_barrier
	ds_read_b128 v[146:149], v158
	ds_read_b128 v[150:153], v158 offset:1024
	ds_read_b128 v[154:157], v158 offset:2048
	ds_read_b128 v[158:161], v158 offset:3072
	s_add_u32 s36, s36, 0x40000
	s_addc_u32 s37, s37, 0
	s_mov_b32 m0, s47
	v_lshl_add_u64 v[196:197], s[36:37], 0, v[134:135]
	ds_read_b128 v[162:165], v145 offset:32768
	ds_read_b128 v[166:169], v145 offset:33792
	ds_read_b128 v[170:173], v145 offset:34816
	ds_read_b128 v[176:179], v145 offset:35840
	ds_read_b128 v[180:183], v145 offset:36864
	ds_read_b128 v[184:187], v145 offset:37888
	ds_read_b128 v[188:191], v145 offset:38912
	ds_read_b128 v[192:195], v145 offset:39936
	global_load_lds_dwordx4 v[196:197], off
	s_mov_b32 m0, s48
	v_lshl_add_u64 v[196:197], s[36:37], 0, v[132:133]
	global_load_lds_dwordx4 v[196:197], off
	s_waitcnt lgkmcnt(8)
	s_barrier
; #define PG8_STAGE(bufoff, gbase, voff) do { _Pragma("unroll") for (int _i = 0; _i < 2; ++_i) \
;         __builtin_amdgcn_global_load_lds((const unsigned*)((const char*)(gbase) + (voff)[_i]), (PG8_LAS unsigned*)(lds + (bufoff) + ldsw + _i * 8192), 16, 0, 0); } while (0)
; #define PG8_LDA(dst, b, h) do { _Pragma("unroll") for (int m = 0; m < 4; ++m) _Pragma("unroll") for (int k = 0; k < 2; ++k) dst[m][k] = *(const PG8_LAS bf16x8*)(lds + PG8_SA(b, h) + aoff + m * 2048 + k * 1024); } while (0)
; #define PG8_LDB(dst, b, h) do { _Pragma("unroll") for (int n = 0; n < 2; ++n) _Pragma("unroll") for (int k = 0; k < 2; ++k) dst[n][k] = *(const PG8_LAS bf16x8*)(lds + PG8_SB(b, h) + boff + n * 2048 + k * 1024); } while (0)
; #define PG8_MMA(ai, bj, At, Bt) do { __builtin_amdgcn_s_setprio(1); _Pragma("unroll") for (int m = 0; m < 4; ++m) _Pragma("unroll") for (int n = 0; n < 2; ++n) _Pragma("unroll") for (int k = 0; k < 2; ++k) \
;         acc[ai][bj][m][n] = __builtin_amdgcn_mfma_f32_16x16x32_bf16(Bt[n][k], At[m][k], acc[ai][bj][m][n], 0, 0, 0); __builtin_amdgcn_s_setprio(0); } while (0)
; #define PG8_WAIT_V(n) asm volatile("s_waitcnt vmcnt(" #n ")" ::: "memory")
; #define PG8_WAIT_L(n) asm volatile("s_waitcnt lgkmcnt(" #n ")" ::: "memory")
; #define PG8_BAR __builtin_amdgcn_s_barrier()
; #define PG8_SCHED __builtin_amdgcn_sched_barrier(0)
; template <class Epi, class Sched>
; __device__ __forceinline__ void gemm_phase(PG8_LAS unsigned char* lds, const Gemm g, const Sched& S, const Epi& E) {
;     ...
;             PG8_WAIT_L(8); PG8_BAR; PG8_WAIT_L(0); PG8_MMA(0, 0, At, B0); PG8_BAR; PG8_SCHED;
;             PG8_LDB(B1, 1, 1); PG8_STAGE(PG8_SB(1, 0), b3, voffB);
;             PG8_BAR; PG8_WAIT_L(0); PG8_MMA(0, 1, At, B1); PG8_BAR;
;             PG8_LDA(At, 1, 1); PG8_STAGE(PG8_SA(1, 0), a3, voffA);
;             PG8_BAR; PG8_WAIT_L(0); PG8_MMA(1, 0, At, B0); PG8_BAR; PG8_SCHED;
;             PG8_STAGE(PG8_SB(1, 1), b3 + hstep, voffB);
;             PG8_WAIT_V(6); PG8_BAR; PG8_MMA(1, 1, At, B1); PG8_BAR;
;         }
	s_waitcnt lgkmcnt(7)
	v_mfma_f32_16x16x32_bf16 v[126:129], v[146:149], v[162:165], v[126:129]
	v_mfma_f32_16x16x32_bf16 v[122:125], v[154:157], v[162:165], v[122:125]
	s_waitcnt lgkmcnt(3)
	v_mfma_f32_16x16x32_bf16 v[118:121], v[146:149], v[170:173], v[118:121]
	v_mfma_f32_16x16x32_bf16 v[110:113], v[154:157], v[170:173], v[110:113]
	v_mfma_f32_16x16x32_bf16 v[102:105], v[146:149], v[180:183], v[102:105]
	v_mfma_f32_16x16x32_bf16 v[94:97], v[154:157], v[180:183], v[94:97]
	s_waitcnt lgkmcnt(0)
	v_mfma_f32_16x16x32_bf16 v[86:89], v[146:149], v[188:191], v[86:89]
	v_mfma_f32_16x16x32_bf16 v[78:81], v[154:157], v[188:191], v[78:81]
	v_mfma_f32_16x16x32_bf16 v[126:129], v[150:153], v[166:169], v[126:129]
	v_mfma_f32_16x16x32_bf16 v[122:125], v[158:161], v[166:169], v[122:125]
	v_mfma_f32_16x16x32_bf16 v[118:121], v[150:153], v[176:179], v[118:121]
	v_mfma_f32_16x16x32_bf16 v[110:113], v[158:161], v[176:179], v[110:113]
	v_mfma_f32_16x16x32_bf16 v[102:105], v[150:153], v[184:187], v[102:105]
	v_mfma_f32_16x16x32_bf16 v[94:97], v[158:161], v[184:187], v[94:97]
	v_mfma_f32_16x16x32_bf16 v[86:89], v[150:153], v[192:195], v[86:89]
	v_mfma_f32_16x16x32_bf16 v[78:81], v[158:161], v[192:195], v[78:81]
	s_barrier
	s_add_i32 s36, 0, 0x1c000
	s_add_i32 s37, s65, s13
	v_add_u32_e32 v175, s36, v143
	v_lshl_add_u64 v[140:141], v[140:141], 0, s[0:1]
	s_mov_b32 m0, s37
	ds_read_b128 v[196:199], v175
	ds_read_b128 v[200:203], v175 offset:1024
	ds_read_b128 v[204:207], v175 offset:2048
	ds_read_b128 v[208:211], v175 offset:3072
	global_load_lds_dwordx4 v[140:141], off
	s_add_i32 m0, s37, 0x2000
	v_lshl_add_u64 v[140:141], v[212:213], 0, s[0:1]
	global_load_lds_dwordx4 v[140:141], off
	s_barrier
	s_waitcnt lgkmcnt(3)
	v_mfma_f32_16x16x32_bf16 v[114:117], v[196:199], v[162:165], v[114:117]
	s_waitcnt lgkmcnt(0)
	v_mfma_f32_16x16x32_bf16 v[106:109], v[204:207], v[162:165], v[106:109]
	v_mfma_f32_16x16x32_bf16 v[98:101], v[196:199], v[170:173], v[98:101]
	v_mfma_f32_16x16x32_bf16 v[90:93], v[204:207], v[170:173], v[90:93]
	v_mfma_f32_16x16x32_bf16 v[82:85], v[196:199], v[180:183], v[82:85]
	v_mfma_f32_16x16x32_bf16 v[74:77], v[204:207], v[180:183], v[74:77]
	v_mfma_f32_16x16x32_bf16 v[70:73], v[196:199], v[188:191], v[70:73]
	v_mfma_f32_16x16x32_bf16 v[66:69], v[204:207], v[188:191], v[66:69]
	v_mfma_f32_16x16x32_bf16 v[114:117], v[200:203], v[166:169], v[114:117]
	v_mfma_f32_16x16x32_bf16 v[106:109], v[208:211], v[166:169], v[106:109]
	v_mfma_f32_16x16x32_bf16 v[98:101], v[200:203], v[176:179], v[98:101]
	v_mfma_f32_16x16x32_bf16 v[90:93], v[208:211], v[176:179], v[90:93]
	v_mfma_f32_16x16x32_bf16 v[82:85], v[200:203], v[184:187], v[82:85]
	v_mfma_f32_16x16x32_bf16 v[74:77], v[208:211], v[184:187], v[74:77]
	v_mfma_f32_16x16x32_bf16 v[70:73], v[200:203], v[192:195], v[70:73]
	v_mfma_f32_16x16x32_bf16 v[66:69], v[208:211], v[192:195], v[66:69]
	s_mov_b32 m0, s49
	v_lshl_add_u64 v[140:141], v[214:215], 0, s[0:1]
	s_barrier
	ds_read_b128 v[162:165], v145 offset:49152
	ds_read_b128 v[166:169], v145 offset:50176
	ds_read_b128 v[170:173], v145 offset:51200
	ds_read_b128 v[176:179], v145 offset:52224
	ds_read_b128 v[180:183], v145 offset:53248
	ds_read_b128 v[184:187], v145 offset:54272
	ds_read_b128 v[188:191], v145 offset:55296
	ds_read_b128 v[192:195], v145 offset:56320
	global_load_lds_dwordx4 v[140:141], off
	s_mov_b32 m0, s50
	v_lshl_add_u64 v[140:141], v[216:217], 0, s[0:1]
	global_load_lds_dwordx4 v[140:141], off
	s_barrier
	s_waitcnt lgkmcnt(7)
	v_mfma_f32_16x16x32_bf16 v[62:65], v[146:149], v[162:165], v[62:65]
	v_mfma_f32_16x16x32_bf16 v[58:61], v[154:157], v[162:165], v[58:61]
	s_waitcnt lgkmcnt(3)
	v_mfma_f32_16x16x32_bf16 v[54:57], v[146:149], v[170:173], v[54:57]
	v_mfma_f32_16x16x32_bf16 v[44:47], v[154:157], v[170:173], v[44:47]
	v_mfma_f32_16x16x32_bf16 v[36:39], v[146:149], v[180:183], v[36:39]
	v_mfma_f32_16x16x32_bf16 v[28:31], v[154:157], v[180:183], v[28:31]
	s_waitcnt lgkmcnt(0)
	v_mfma_f32_16x16x32_bf16 v[20:23], v[146:149], v[188:191], v[20:23]
	v_mfma_f32_16x16x32_bf16 v[12:15], v[154:157], v[188:191], v[12:15]
	v_mfma_f32_16x16x32_bf16 v[62:65], v[150:153], v[166:169], v[62:65]
	v_mfma_f32_16x16x32_bf16 v[58:61], v[158:161], v[166:169], v[58:61]
	v_mfma_f32_16x16x32_bf16 v[54:57], v[150:153], v[176:179], v[54:57]
	v_mfma_f32_16x16x32_bf16 v[44:47], v[158:161], v[176:179], v[44:47]
	v_mfma_f32_16x16x32_bf16 v[36:39], v[150:153], v[184:187], v[36:39]
	v_mfma_f32_16x16x32_bf16 v[28:31], v[158:161], v[184:187], v[28:31]
	v_mfma_f32_16x16x32_bf16 v[20:23], v[150:153], v[192:195], v[20:23]
	v_mfma_f32_16x16x32_bf16 v[12:15], v[158:161], v[192:195], v[12:15]
	s_barrier
	s_add_u32 s34, s34, 0x40080
	s_addc_u32 s35, s35, 0
	s_add_i32 s36, s36, s13
	s_mov_b32 m0, s36
	v_lshl_add_u64 v[140:141], s[34:35], 0, v[48:49]
	global_load_lds_dwordx4 v[140:141], off
	s_add_i32 m0, s36, 0x2000
	v_lshl_add_u64 v[140:141], s[34:35], 0, v[130:131]
	global_load_lds_dwordx4 v[140:141], off
	s_waitcnt vmcnt(6)
	s_barrier
	v_mfma_f32_16x16x32_bf16 v[50:53], v[196:199], v[162:165], v[50:53]
	v_mfma_f32_16x16x32_bf16 v[40:43], v[204:207], v[162:165], v[40:43]
	v_mfma_f32_16x16x32_bf16 v[32:35], v[196:199], v[170:173], v[32:35]
	v_mfma_f32_16x16x32_bf16 v[24:27], v[204:207], v[170:173], v[24:27]
	v_mfma_f32_16x16x32_bf16 v[16:19], v[196:199], v[180:183], v[16:19]
	v_mfma_f32_16x16x32_bf16 v[8:11], v[204:207], v[180:183], v[8:11]
	v_mfma_f32_16x16x32_bf16 v[4:7], v[196:199], v[188:191], v[4:7]
	v_mfma_f32_16x16x32_bf16 v[0:3], v[204:207], v[188:191], v[0:3]
	v_mfma_f32_16x16x32_bf16 v[50:53], v[200:203], v[166:169], v[50:53]
	v_mfma_f32_16x16x32_bf16 v[40:43], v[208:211], v[166:169], v[40:43]
	v_mfma_f32_16x16x32_bf16 v[32:35], v[200:203], v[176:179], v[32:35]
	v_mfma_f32_16x16x32_bf16 v[24:27], v[208:211], v[176:179], v[24:27]
	v_mfma_f32_16x16x32_bf16 v[16:19], v[200:203], v[184:187], v[16:19]
	v_mfma_f32_16x16x32_bf16 v[8:11], v[208:211], v[184:187], v[8:11]
	v_mfma_f32_16x16x32_bf16 v[4:7], v[200:203], v[192:195], v[4:7]
	v_mfma_f32_16x16x32_bf16 v[0:3], v[208:211], v[192:195], v[0:3]
	s_add_i32 s64, s64, 2
	s_add_u32 s30, s30, 0x100
	s_addc_u32 s31, s31, 0
	s_add_u32 s59, s59, 0x100
	s_addc_u32 s63, s63, 0
	s_cmp_gt_u32 s64, 13
	s_barrier
	s_cbranch_scc0 .LBB0_320

; #define PG8_STAGE(bufoff, gbase, voff) do { _Pragma("unroll") for (int _i = 0; _i < 2; ++_i) \
;         __builtin_amdgcn_global_load_lds((const unsigned*)((const char*)(gbase) + (voff)[_i]), (PG8_LAS unsigned*)(lds + (bufoff) + ldsw + _i * 8192), 16, 0, 0); } while (0)
; #define PG8_LDA(dst, b, h) do { _Pragma("unroll") for (int m = 0; m < 4; ++m) _Pragma("unroll") for (int k = 0; k < 2; ++k) dst[m][k] = *(const PG8_LAS bf16x8*)(lds + PG8_SA(b, h) + aoff + m * 2048 + k * 1024); } while (0)
; #define PG8_LDB(dst, b, h) do { _Pragma("unroll") for (int n = 0; n < 2; ++n) _Pragma("unroll") for (int k = 0; k < 2; ++k) dst[n][k] = *(const PG8_LAS bf16x8*)(lds + PG8_SB(b, h) + boff + n * 2048 + k * 1024); } while (0)
; #define PG8_WAIT_L(n) asm volatile("s_waitcnt lgkmcnt(" #n ")" ::: "memory")
; #define PG8_BAR __builtin_amdgcn_s_barrier()
; #define PG8_SCHED __builtin_amdgcn_sched_barrier(0)
; template <class Epi, class Sched>
; __device__ __forceinline__ void gemm_phase(PG8_LAS unsigned char* lds, const Gemm g, const Sched& S, const Epi& E) {
;     ...
;         const bool has_next = S.next(ui + 1, nxt);
;         const char* nA = has_next ? (const char*)g.A + (size_t)nxt.pm * tstepA + (size_t)nxt.kc * cstep : cA; const char* nB = has_next ? (const char*)g.Bt + (size_t)nxt.pn * tstep + (size_t)nxt.kc * cstep : cB;
;         for (int t = 0; t < nt; t += 2) {
;             const bool last = (t == nt - 2);
;             const char* a1 = cA + (size_t)(t + 1) * kstep;
;             const char* a2 = last ? nA : cA + (size_t)(t + 2) * kstep; const char* b2 = last ? nB : cB + (size_t)(t + 2) * kstep;
;             const char* a3 = a2 + kstep; const char* b3 = b2 + kstep;
;             if (last && has_next) S.a_ready(nxt);
;             PG8_LDB(B0, 0, 0); PG8_SCHED; PG8_LDA(At, 0, 0); PG8_STAGE(PG8_SA(1, 1), a1 + hstep, voffA);
;             PG8_WAIT_L(8); PG8_BAR; PG8_WAIT_L(0); PG8_MMA(0, 0, At, B0); PG8_BAR; PG8_SCHED;
;             PG8_LDB(B1, 0, 1); PG8_STAGE(PG8_SB(0, 0), b2, voffB);
;             PG8_BAR; PG8_WAIT_L(0); PG8_MMA(0, 1, At, B1); PG8_BAR;
;             PG8_LDA(At, 0, 1); PG8_STAGE(PG8_SA(0, 0), a2, voffA);
;             PG8_BAR; PG8_WAIT_L(0); PG8_MMA(1, 0, At, B0); PG8_BAR; PG8_SCHED;
.LBB0_334:
	v_mov_b64_e32 v[0:1], 0x440
	s_ashr_i32 s23, s22, 31
	v_cmp_lt_i64_e32 vcc, s[16:17], v[0:1]
	s_lshl_b64 s[16:17], s[22:23], 19
	s_add_u32 s24, s28, s16
	s_addc_u32 s25, s29, s17
	s_and_b64 s[16:17], vcc, exec
	s_cselect_b32 s23, s25, s7
	s_cselect_b32 s50, s24, s6
	s_ashr_i32 s21, s20, 31
	s_lshl_b64 s[16:17], s[20:21], 19
	s_add_u32 s26, s30, s16
	s_addc_u32 s27, s31, s17
	s_and_b64 s[16:17], vcc, exec
	s_cselect_b32 s21, s27, s13
	s_cselect_b32 s51, s26, s12
	s_add_u32 s6, s6, 0x40080
	s_addc_u32 s7, s7, 0
	s_add_u32 s54, s12, 0x100
	s_addc_u32 s55, s13, 0
	s_mov_b32 s56, -2
	s_add_u32 s12, s6, 0xfffc0080
	s_addc_u32 s13, s7, -1
	s_add_i32 s57, 0, 0x10000
	v_add_u32_e32 v48, s57, v166
	ds_read_b128 v[144:147], v48
	ds_read_b128 v[148:151], v48 offset:1024
	ds_read_b128 v[152:155], v48 offset:2048
	ds_read_b128 v[156:159], v48 offset:3072
	s_cmp_eq_u32 s56, 12
	s_cselect_b32 s17, s23, s13
	s_cselect_b32 s16, s50, s12
	s_cselect_b32 s13, s21, s55
	s_cselect_b32 s12, s51, s54
	v_lshl_add_u64 v[164:165], s[6:7], 0, v[140:141]
	s_add_i32 m0, s3, 0xc000
	ds_read_b128 v[160:163], v167
	ds_read_b128 v[168:171], v167 offset:1024
	ds_read_b128 v[176:179], v167 offset:2048
	ds_read_b128 v[180:183], v167 offset:3072
	ds_read_b128 v[184:187], v167 offset:4096
	ds_read_b128 v[188:191], v167 offset:5120
	ds_read_b128 v[192:195], v167 offset:6144
	ds_read_b128 v[196:199], v167 offset:7168
	global_load_lds_dwordx4 v[164:165], off
	s_add_i32 m0, s3, 0xe000
	v_lshl_add_u64 v[164:165], s[6:7], 0, v[142:143]
	global_load_lds_dwordx4 v[164:165], off
	s_waitcnt lgkmcnt(8)
	s_barrier
	s_waitcnt lgkmcnt(7)
	v_mfma_f32_16x16x32_bf16 v[126:129], v[144:147], v[160:163], 0
	v_mfma_f32_16x16x32_bf16 v[122:125], v[152:155], v[160:163], 0
	s_waitcnt lgkmcnt(3)
	v_mfma_f32_16x16x32_bf16 v[110:113], v[144:147], v[176:179], 0
	v_mfma_f32_16x16x32_bf16 v[106:109], v[152:155], v[176:179], 0
	v_mfma_f32_16x16x32_bf16 v[94:97], v[144:147], v[184:187], 0
	v_mfma_f32_16x16x32_bf16 v[90:93], v[152:155], v[184:187], 0
	s_waitcnt lgkmcnt(0)
	v_mfma_f32_16x16x32_bf16 v[78:81], v[144:147], v[192:195], 0
	v_mfma_f32_16x16x32_bf16 v[74:77], v[152:155], v[192:195], 0
	v_mfma_f32_16x16x32_bf16 v[126:129], v[148:151], v[168:171], v[126:129]
	v_mfma_f32_16x16x32_bf16 v[122:125], v[156:159], v[168:171], v[122:125]
	v_mfma_f32_16x16x32_bf16 v[110:113], v[148:151], v[180:183], v[110:113]
	v_mfma_f32_16x16x32_bf16 v[106:109], v[156:159], v[180:183], v[106:109]
	v_mfma_f32_16x16x32_bf16 v[94:97], v[148:151], v[188:191], v[94:97]
	v_mfma_f32_16x16x32_bf16 v[90:93], v[156:159], v[188:191], v[90:93]
	v_mfma_f32_16x16x32_bf16 v[78:81], v[148:151], v[196:199], v[78:81]
	v_mfma_f32_16x16x32_bf16 v[74:77], v[156:159], v[196:199], v[74:77]
	s_barrier
	s_add_i32 s59, 0, 0x14000
	s_add_i32 s57, s57, s34
	v_add_u32_e32 v48, s59, v166
	v_lshl_add_u64 v[164:165], s[12:13], 0, v[134:135]
	s_mov_b32 m0, s57
	ds_read_b128 v[200:203], v48
	ds_read_b128 v[204:207], v48 offset:1024
	ds_read_b128 v[208:211], v48 offset:2048
	ds_read_b128 v[212:215], v48 offset:3072
	global_load_lds_dwordx4 v[164:165], off
	s_add_i32 m0, s57, 0x2000
	v_lshl_add_u64 v[172:173], s[12:13], 0, v[130:131]
	global_load_lds_dwordx4 v[172:173], off
	s_barrier
	s_waitcnt lgkmcnt(3)
	v_mfma_f32_16x16x32_bf16 v[118:121], v[200:203], v[160:163], 0
	s_waitcnt lgkmcnt(0)
	v_mfma_f32_16x16x32_bf16 v[114:117], v[208:211], v[160:163], 0
	v_mfma_f32_16x16x32_bf16 v[102:105], v[200:203], v[176:179], 0
	v_mfma_f32_16x16x32_bf16 v[98:101], v[208:211], v[176:179], 0
	v_mfma_f32_16x16x32_bf16 v[86:89], v[200:203], v[184:187], 0
	v_mfma_f32_16x16x32_bf16 v[82:85], v[208:211], v[184:187], 0
	v_mfma_f32_16x16x32_bf16 v[70:73], v[200:203], v[192:195], 0
	v_mfma_f32_16x16x32_bf16 v[66:69], v[208:211], v[192:195], 0
	v_mfma_f32_16x16x32_bf16 v[118:121], v[204:207], v[168:171], v[118:121]
	v_mfma_f32_16x16x32_bf16 v[114:117], v[212:215], v[168:171], v[114:117]
	v_mfma_f32_16x16x32_bf16 v[102:105], v[204:207], v[180:183], v[102:105]
	v_mfma_f32_16x16x32_bf16 v[98:101], v[212:215], v[180:183], v[98:101]
	v_mfma_f32_16x16x32_bf16 v[86:89], v[204:207], v[188:191], v[86:89]
	v_mfma_f32_16x16x32_bf16 v[82:85], v[212:215], v[188:191], v[82:85]
	v_mfma_f32_16x16x32_bf16 v[70:73], v[204:207], v[196:199], v[70:73]
	v_mfma_f32_16x16x32_bf16 v[66:69], v[212:215], v[196:199], v[66:69]
	s_mov_b32 m0, s3
	v_lshl_add_u64 v[216:217], s[16:17], 0, v[136:137]
	s_barrier
	ds_read_b128 v[160:163], v167 offset:16384
	ds_read_b128 v[168:171], v167 offset:17408
	ds_read_b128 v[176:179], v167 offset:18432
	ds_read_b128 v[180:183], v167 offset:19456
	ds_read_b128 v[184:187], v167 offset:20480
	ds_read_b128 v[188:191], v167 offset:21504
	ds_read_b128 v[192:195], v167 offset:22528
	ds_read_b128 v[196:199], v167 offset:23552
	global_load_lds_dwordx4 v[216:217], off
	s_mov_b32 m0, s36
	v_lshl_add_u64 v[218:219], s[16:17], 0, v[132:133]
	global_load_lds_dwordx4 v[218:219], off
	s_barrier
	s_waitcnt lgkmcnt(7)
	v_mfma_f32_16x16x32_bf16 v[62:65], v[144:147], v[160:163], 0
	v_mfma_f32_16x16x32_bf16 v[58:61], v[152:155], v[160:163], 0
	s_waitcnt lgkmcnt(3)
	v_mfma_f32_16x16x32_bf16 v[44:47], v[144:147], v[176:179], 0
	v_mfma_f32_16x16x32_bf16 v[40:43], v[152:155], v[176:179], 0
	v_mfma_f32_16x16x32_bf16 v[28:31], v[144:147], v[184:187], 0
	v_mfma_f32_16x16x32_bf16 v[24:27], v[152:155], v[184:187], 0
	s_waitcnt lgkmcnt(0)
	v_mfma_f32_16x16x32_bf16 v[12:15], v[144:147], v[192:195], 0
	v_mfma_f32_16x16x32_bf16 v[8:11], v[152:155], v[192:195], 0
	v_mfma_f32_16x16x32_bf16 v[62:65], v[148:151], v[168:171], v[62:65]
	v_mfma_f32_16x16x32_bf16 v[58:61], v[156:159], v[168:171], v[58:61]
	v_mfma_f32_16x16x32_bf16 v[44:47], v[148:151], v[180:183], v[44:47]
	v_mfma_f32_16x16x32_bf16 v[40:43], v[156:159], v[180:183], v[40:43]
	v_mfma_f32_16x16x32_bf16 v[28:31], v[148:151], v[188:191], v[28:31]
	v_mfma_f32_16x16x32_bf16 v[24:27], v[156:159], v[188:191], v[24:27]
	v_mfma_f32_16x16x32_bf16 v[12:15], v[148:151], v[196:199], v[12:15]
	v_mfma_f32_16x16x32_bf16 v[8:11], v[156:159], v[196:199], v[8:11]
	s_barrier
; #define PG8_STAGE(bufoff, gbase, voff) do { _Pragma("unroll") for (int _i = 0; _i < 2; ++_i) \
;         __builtin_amdgcn_global_load_lds((const unsigned*)((const char*)(gbase) + (voff)[_i]), (PG8_LAS unsigned*)(lds + (bufoff) + ldsw + _i * 8192), 16, 0, 0); } while (0)
; #define PG8_LDA(dst, b, h) do { _Pragma("unroll") for (int m = 0; m < 4; ++m) _Pragma("unroll") for (int k = 0; k < 2; ++k) dst[m][k] = *(const PG8_LAS bf16x8*)(lds + PG8_SA(b, h) + aoff + m * 2048 + k * 1024); } while (0)
; #define PG8_LDB(dst, b, h) do { _Pragma("unroll") for (int n = 0; n < 2; ++n) _Pragma("unroll") for (int k = 0; k < 2; ++k) dst[n][k] = *(const PG8_LAS bf16x8*)(lds + PG8_SB(b, h) + boff + n * 2048 + k * 1024); } while (0)
; #define PG8_MMA(ai, bj, At, Bt) do { __builtin_amdgcn_s_setprio(1); _Pragma("unroll") for (int m = 0; m < 4; ++m) _Pragma("unroll") for (int n = 0; n < 2; ++n) _Pragma("unroll") for (int k = 0; k < 2; ++k) \
;         acc[ai][bj][m][n] = __builtin_amdgcn_mfma_f32_16x16x32_bf16(Bt[n][k], At[m][k], acc[ai][bj][m][n], 0, 0, 0); __builtin_amdgcn_s_setprio(0); } while (0)
; #define PG8_WAIT_V(n) asm volatile("s_waitcnt vmcnt(" #n ")" ::: "memory")
; #define PG8_WAIT_L(n) asm volatile("s_waitcnt lgkmcnt(" #n ")" ::: "memory")
; #define PG8_BAR __builtin_amdgcn_s_barrier()
; #define PG8_SCHED __builtin_amdgcn_sched_barrier(0)
; template <class Epi, class Sched>
; __device__ __forceinline__ void gemm_phase(PG8_LAS unsigned char* lds, const Gemm g, const Sched& S, const Epi& E) {
;     ...
;             PG8_STAGE(PG8_SB(0, 1), b2 + hstep, voffB);
;             PG8_WAIT_V(6); PG8_BAR; PG8_MMA(1, 1, At, B1); PG8_BAR;
;             PG8_LDB(B0, 1, 0); PG8_SCHED; PG8_LDA(At, 1, 0); PG8_STAGE(PG8_SA(0, 1), a2 + hstep, voffA);
;             PG8_WAIT_L(8); PG8_BAR; PG8_WAIT_L(0); PG8_MMA(0, 0, At, B0); PG8_BAR; PG8_SCHED;
;             PG8_LDB(B1, 1, 1); PG8_STAGE(PG8_SB(1, 0), b3, voffB);
;             PG8_BAR; PG8_WAIT_L(0); PG8_MMA(0, 1, At, B1); PG8_BAR;
;             PG8_LDA(At, 1, 1); PG8_STAGE(PG8_SA(1, 0), a3, voffA);
	s_add_u32 s64, s12, 0x40000
	s_addc_u32 s65, s13, 0
	s_add_i32 s57, s59, s34
	s_mov_b32 m0, s57
	v_lshl_add_u64 v[144:145], s[64:65], 0, v[134:135]
	global_load_lds_dwordx4 v[144:145], off
	s_add_i32 m0, s57, 0x2000
	v_lshl_add_u64 v[144:145], s[64:65], 0, v[130:131]
	global_load_lds_dwordx4 v[144:145], off
	s_waitcnt vmcnt(6)
	s_barrier
	v_mfma_f32_16x16x32_bf16 v[54:57], v[200:203], v[160:163], 0
	v_mfma_f32_16x16x32_bf16 v[50:53], v[208:211], v[160:163], 0
	v_mfma_f32_16x16x32_bf16 v[36:39], v[200:203], v[176:179], 0
	v_mfma_f32_16x16x32_bf16 v[32:35], v[208:211], v[176:179], 0
	v_mfma_f32_16x16x32_bf16 v[20:23], v[200:203], v[184:187], 0
	v_mfma_f32_16x16x32_bf16 v[16:19], v[208:211], v[184:187], 0
	v_mfma_f32_16x16x32_bf16 v[4:7], v[200:203], v[192:195], 0
	v_mfma_f32_16x16x32_bf16 v[0:3], v[208:211], v[192:195], 0
	v_mfma_f32_16x16x32_bf16 v[54:57], v[204:207], v[168:171], v[54:57]
	v_mfma_f32_16x16x32_bf16 v[50:53], v[212:215], v[168:171], v[50:53]
	v_mfma_f32_16x16x32_bf16 v[36:39], v[204:207], v[180:183], v[36:39]
	v_mfma_f32_16x16x32_bf16 v[32:35], v[212:215], v[180:183], v[32:35]
	v_mfma_f32_16x16x32_bf16 v[20:23], v[204:207], v[188:191], v[20:23]
	v_mfma_f32_16x16x32_bf16 v[16:19], v[212:215], v[188:191], v[16:19]
	v_mfma_f32_16x16x32_bf16 v[4:7], v[204:207], v[196:199], v[4:7]
	v_mfma_f32_16x16x32_bf16 v[0:3], v[212:215], v[196:199], v[0:3]
	s_add_i32 s57, 0, 0x18000
	v_add_u32_e32 v48, s57, v166
	s_barrier
	ds_read_b128 v[144:147], v48
	ds_read_b128 v[148:151], v48 offset:1024
	ds_read_b128 v[152:155], v48 offset:2048
	ds_read_b128 v[156:159], v48 offset:3072
	s_add_u32 s16, s16, 0x40000
	s_addc_u32 s17, s17, 0
	s_mov_b32 m0, s37
	v_lshl_add_u64 v[200:201], s[16:17], 0, v[136:137]
	ds_read_b128 v[160:163], v167 offset:32768
	ds_read_b128 v[168:171], v167 offset:33792
	ds_read_b128 v[176:179], v167 offset:34816
	ds_read_b128 v[180:183], v167 offset:35840
	ds_read_b128 v[184:187], v167 offset:36864
	ds_read_b128 v[188:191], v167 offset:37888
	ds_read_b128 v[192:195], v167 offset:38912
	ds_read_b128 v[196:199], v167 offset:39936
	global_load_lds_dwordx4 v[200:201], off
	s_mov_b32 m0, s38
	v_lshl_add_u64 v[200:201], s[16:17], 0, v[132:133]
	global_load_lds_dwordx4 v[200:201], off
	s_waitcnt lgkmcnt(8)
	s_barrier
	s_waitcnt lgkmcnt(7)
	v_mfma_f32_16x16x32_bf16 v[126:129], v[144:147], v[160:163], v[126:129]
	v_mfma_f32_16x16x32_bf16 v[122:125], v[152:155], v[160:163], v[122:125]
	s_waitcnt lgkmcnt(3)
	v_mfma_f32_16x16x32_bf16 v[110:113], v[144:147], v[176:179], v[110:113]
	v_mfma_f32_16x16x32_bf16 v[106:109], v[152:155], v[176:179], v[106:109]
	v_mfma_f32_16x16x32_bf16 v[94:97], v[144:147], v[184:187], v[94:97]
	v_mfma_f32_16x16x32_bf16 v[90:93], v[152:155], v[184:187], v[90:93]
	s_waitcnt lgkmcnt(0)
	v_mfma_f32_16x16x32_bf16 v[78:81], v[144:147], v[192:195], v[78:81]
	v_mfma_f32_16x16x32_bf16 v[74:77], v[152:155], v[192:195], v[74:77]
	v_mfma_f32_16x16x32_bf16 v[126:129], v[148:151], v[168:171], v[126:129]
	v_mfma_f32_16x16x32_bf16 v[122:125], v[156:159], v[168:171], v[122:125]
	v_mfma_f32_16x16x32_bf16 v[110:113], v[148:151], v[180:183], v[110:113]
	v_mfma_f32_16x16x32_bf16 v[106:109], v[156:159], v[180:183], v[106:109]
	v_mfma_f32_16x16x32_bf16 v[94:97], v[148:151], v[188:191], v[94:97]
	v_mfma_f32_16x16x32_bf16 v[90:93], v[156:159], v[188:191], v[90:93]
	v_mfma_f32_16x16x32_bf16 v[78:81], v[148:151], v[196:199], v[78:81]
	v_mfma_f32_16x16x32_bf16 v[74:77], v[156:159], v[196:199], v[74:77]
	s_barrier
	s_add_i32 s16, 0, 0x1c000
	s_add_i32 s17, s57, s34
	v_add_u32_e32 v48, s16, v166
	v_lshl_add_u64 v[164:165], v[164:165], 0, s[0:1]
	s_mov_b32 m0, s17
	ds_read_b128 v[200:203], v48
	ds_read_b128 v[204:207], v48 offset:1024
	ds_read_b128 v[208:211], v48 offset:2048
	ds_read_b128 v[212:215], v48 offset:3072
	global_load_lds_dwordx4 v[164:165], off
	s_add_i32 m0, s17, 0x2000
	v_lshl_add_u64 v[164:165], v[172:173], 0, s[0:1]
	global_load_lds_dwordx4 v[164:165], off
	s_barrier
	s_waitcnt lgkmcnt(3)
	v_mfma_f32_16x16x32_bf16 v[118:121], v[200:203], v[160:163], v[118:121]
	s_waitcnt lgkmcnt(0)
	v_mfma_f32_16x16x32_bf16 v[114:117], v[208:211], v[160:163], v[114:117]
	v_mfma_f32_16x16x32_bf16 v[102:105], v[200:203], v[176:179], v[102:105]
	v_mfma_f32_16x16x32_bf16 v[98:101], v[208:211], v[176:179], v[98:101]
	v_mfma_f32_16x16x32_bf16 v[86:89], v[200:203], v[184:187], v[86:89]
	v_mfma_f32_16x16x32_bf16 v[82:85], v[208:211], v[184:187], v[82:85]
	v_mfma_f32_16x16x32_bf16 v[70:73], v[200:203], v[192:195], v[70:73]
	v_mfma_f32_16x16x32_bf16 v[66:69], v[208:211], v[192:195], v[66:69]
	v_mfma_f32_16x16x32_bf16 v[118:121], v[204:207], v[168:171], v[118:121]
	v_mfma_f32_16x16x32_bf16 v[114:117], v[212:215], v[168:171], v[114:117]
	v_mfma_f32_16x16x32_bf16 v[102:105], v[204:207], v[180:183], v[102:105]
	v_mfma_f32_16x16x32_bf16 v[98:101], v[212:215], v[180:183], v[98:101]
	v_mfma_f32_16x16x32_bf16 v[86:89], v[204:207], v[188:191], v[86:89]
	v_mfma_f32_16x16x32_bf16 v[82:85], v[212:215], v[188:191], v[82:85]
	v_mfma_f32_16x16x32_bf16 v[70:73], v[204:207], v[196:199], v[70:73]
	v_mfma_f32_16x16x32_bf16 v[66:69], v[212:215], v[196:199], v[66:69]
	s_mov_b32 m0, s39
	v_lshl_add_u64 v[164:165], v[216:217], 0, s[0:1]
	s_barrier
	ds_read_b128 v[160:163], v167 offset:49152
	ds_read_b128 v[168:171], v167 offset:50176
	ds_read_b128 v[176:179], v167 offset:51200
	ds_read_b128 v[180:183], v167 offset:52224
	ds_read_b128 v[184:187], v167 offset:53248
	ds_read_b128 v[188:191], v167 offset:54272
	ds_read_b128 v[192:195], v167 offset:55296
	ds_read_b128 v[196:199], v167 offset:56320
	global_load_lds_dwordx4 v[164:165], off
	s_mov_b32 m0, s42
	v_lshl_add_u64 v[164:165], v[218:219], 0, s[0:1]
	global_load_lds_dwordx4 v[164:165], off
	s_barrier
; #define PG8_STAGE(bufoff, gbase, voff) do { _Pragma("unroll") for (int _i = 0; _i < 2; ++_i) \
;         __builtin_amdgcn_global_load_lds((const unsigned*)((const char*)(gbase) + (voff)[_i]), (PG8_LAS unsigned*)(lds + (bufoff) + ldsw + _i * 8192), 16, 0, 0); } while (0)
; #define PG8_LDA(dst, b, h) do { _Pragma("unroll") for (int m = 0; m < 4; ++m) _Pragma("unroll") for (int k = 0; k < 2; ++k) dst[m][k] = *(const PG8_LAS bf16x8*)(lds + PG8_SA(b, h) + aoff + m * 2048 + k * 1024); } while (0)
; #define PG8_LDB(dst, b, h) do { _Pragma("unroll") for (int n = 0; n < 2; ++n) _Pragma("unroll") for (int k = 0; k < 2; ++k) dst[n][k] = *(const PG8_LAS bf16x8*)(lds + PG8_SB(b, h) + boff + n * 2048 + k * 1024); } while (0)
; #define PG8_MMA(ai, bj, At, Bt) do { __builtin_amdgcn_s_setprio(1); _Pragma("unroll") for (int m = 0; m < 4; ++m) _Pragma("unroll") for (int n = 0; n < 2; ++n) _Pragma("unroll") for (int k = 0; k < 2; ++k) \
;         acc[ai][bj][m][n] = __builtin_amdgcn_mfma_f32_16x16x32_bf16(Bt[n][k], At[m][k], acc[ai][bj][m][n], 0, 0, 0); __builtin_amdgcn_s_setprio(0); } while (0)
; #define PG8_WAIT_V(n) asm volatile("s_waitcnt vmcnt(" #n ")" ::: "memory")
; #define PG8_WAIT_L(n) asm volatile("s_waitcnt lgkmcnt(" #n ")" ::: "memory")
; #define PG8_BAR __builtin_amdgcn_s_barrier()
; #define PG8_SCHED __builtin_amdgcn_sched_barrier(0)
; template <class Epi, class Sched>
; __device__ __forceinline__ void gemm_phase(PG8_LAS unsigned char* lds, const Gemm g, const Sched& S, const Epi& E) {
;     ...
;             const bool last = (t == nt - 2);
;             const char* a1 = cA + (size_t)(t + 1) * kstep;
;             const char* a2 = last ? nA : cA + (size_t)(t + 2) * kstep; const char* b2 = last ? nB : cB + (size_t)(t + 2) * kstep;
;             const char* a3 = a2 + kstep; const char* b3 = b2 + kstep;
;             if (last && has_next) S.a_ready(nxt);
;             PG8_LDB(B0, 0, 0); PG8_SCHED; PG8_LDA(At, 0, 0); PG8_STAGE(PG8_SA(1, 1), a1 + hstep, voffA);
;             PG8_WAIT_L(8); PG8_BAR; PG8_WAIT_L(0); PG8_MMA(0, 0, At, B0); PG8_BAR; PG8_SCHED;
;             PG8_LDB(B1, 0, 1); PG8_STAGE(PG8_SB(0, 0), b2, voffB);
;     ...
;             PG8_BAR; PG8_WAIT_L(0); PG8_MMA(1, 0, At, B0); PG8_BAR; PG8_SCHED;
;             PG8_STAGE(PG8_SB(1, 1), b3 + hstep, voffB);
;             PG8_WAIT_V(6); PG8_BAR; PG8_MMA(1, 1, At, B1); PG8_BAR;
;         }
	s_waitcnt lgkmcnt(7)
	v_mfma_f32_16x16x32_bf16 v[62:65], v[144:147], v[160:163], v[62:65]
	v_mfma_f32_16x16x32_bf16 v[58:61], v[152:155], v[160:163], v[58:61]
	s_waitcnt lgkmcnt(3)
	v_mfma_f32_16x16x32_bf16 v[44:47], v[144:147], v[176:179], v[44:47]
	v_mfma_f32_16x16x32_bf16 v[40:43], v[152:155], v[176:179], v[40:43]
	v_mfma_f32_16x16x32_bf16 v[28:31], v[144:147], v[184:187], v[28:31]
	v_mfma_f32_16x16x32_bf16 v[24:27], v[152:155], v[184:187], v[24:27]
	s_waitcnt lgkmcnt(0)
	v_mfma_f32_16x16x32_bf16 v[12:15], v[144:147], v[192:195], v[12:15]
	v_mfma_f32_16x16x32_bf16 v[8:11], v[152:155], v[192:195], v[8:11]
	v_mfma_f32_16x16x32_bf16 v[62:65], v[148:151], v[168:171], v[62:65]
	v_mfma_f32_16x16x32_bf16 v[58:61], v[156:159], v[168:171], v[58:61]
	v_mfma_f32_16x16x32_bf16 v[44:47], v[148:151], v[180:183], v[44:47]
	v_mfma_f32_16x16x32_bf16 v[40:43], v[156:159], v[180:183], v[40:43]
	v_mfma_f32_16x16x32_bf16 v[28:31], v[148:151], v[188:191], v[28:31]
	v_mfma_f32_16x16x32_bf16 v[24:27], v[156:159], v[188:191], v[24:27]
	v_mfma_f32_16x16x32_bf16 v[12:15], v[148:151], v[196:199], v[12:15]
	v_mfma_f32_16x16x32_bf16 v[8:11], v[156:159], v[196:199], v[8:11]
	s_barrier
	s_add_u32 s12, s12, 0x40080
	s_addc_u32 s13, s13, 0
	s_add_i32 s16, s16, s34
	s_mov_b32 m0, s16
	v_lshl_add_u64 v[144:145], s[12:13], 0, v[134:135]
	global_load_lds_dwordx4 v[144:145], off
	s_add_i32 m0, s16, 0x2000
	v_lshl_add_u64 v[144:145], s[12:13], 0, v[130:131]
	global_load_lds_dwordx4 v[144:145], off
	s_waitcnt vmcnt(6)
	s_barrier
	v_mfma_f32_16x16x32_bf16 v[54:57], v[200:203], v[160:163], v[54:57]
	v_mfma_f32_16x16x32_bf16 v[50:53], v[208:211], v[160:163], v[50:53]
	v_mfma_f32_16x16x32_bf16 v[36:39], v[200:203], v[176:179], v[36:39]
	v_mfma_f32_16x16x32_bf16 v[32:35], v[208:211], v[176:179], v[32:35]
	v_mfma_f32_16x16x32_bf16 v[20:23], v[200:203], v[184:187], v[20:23]
	v_mfma_f32_16x16x32_bf16 v[16:19], v[208:211], v[184:187], v[16:19]
	v_mfma_f32_16x16x32_bf16 v[4:7], v[200:203], v[192:195], v[4:7]
	v_mfma_f32_16x16x32_bf16 v[0:3], v[208:211], v[192:195], v[0:3]
	v_mfma_f32_16x16x32_bf16 v[54:57], v[204:207], v[168:171], v[54:57]
	v_mfma_f32_16x16x32_bf16 v[50:53], v[212:215], v[168:171], v[50:53]
	v_mfma_f32_16x16x32_bf16 v[36:39], v[204:207], v[180:183], v[36:39]
	v_mfma_f32_16x16x32_bf16 v[32:35], v[212:215], v[180:183], v[32:35]
	v_mfma_f32_16x16x32_bf16 v[20:23], v[204:207], v[188:191], v[20:23]
	v_mfma_f32_16x16x32_bf16 v[16:19], v[212:215], v[188:191], v[16:19]
	v_mfma_f32_16x16x32_bf16 v[4:7], v[204:207], v[196:199], v[4:7]
	v_mfma_f32_16x16x32_bf16 v[0:3], v[212:215], v[196:199], v[0:3]
	s_add_i32 s56, s56, 2
	s_add_u32 s6, s6, 0x100
	s_addc_u32 s7, s7, 0
	s_add_u32 s54, s54, 0x100
	s_addc_u32 s55, s55, 0
	s_cmp_gt_u32 s56, 13
	s_barrier
	s_cbranch_scc1 .Lkpeel_exit_335
.LBB0_335:
	s_add_u32 s12, s6, 0xfffc0080
	s_addc_u32 s13, s7, -1
	s_add_i32 s57, 0, 0x10000
	v_add_u32_e32 v48, s57, v166
	ds_read_b128 v[144:147], v48
	ds_read_b128 v[148:151], v48 offset:1024
	ds_read_b128 v[152:155], v48 offset:2048
	ds_read_b128 v[156:159], v48 offset:3072
	s_cmp_eq_u32 s56, 12
	s_cselect_b32 s17, s23, s13
	s_cselect_b32 s16, s50, s12
	s_cselect_b32 s13, s21, s55
	s_cselect_b32 s12, s51, s54
	v_lshl_add_u64 v[164:165], s[6:7], 0, v[140:141]
	s_add_i32 m0, s3, 0xc000
	ds_read_b128 v[160:163], v167
	ds_read_b128 v[168:171], v167 offset:1024
	ds_read_b128 v[176:179], v167 offset:2048
	ds_read_b128 v[180:183], v167 offset:3072
	ds_read_b128 v[184:187], v167 offset:4096
	ds_read_b128 v[188:191], v167 offset:5120
	ds_read_b128 v[192:195], v167 offset:6144
	ds_read_b128 v[196:199], v167 offset:7168
	global_load_lds_dwordx4 v[164:165], off
	s_add_i32 m0, s3, 0xe000
	v_lshl_add_u64 v[164:165], s[6:7], 0, v[142:143]
	global_load_lds_dwordx4 v[164:165], off
	s_waitcnt lgkmcnt(8)
	s_barrier
	s_waitcnt lgkmcnt(7)
	v_mfma_f32_16x16x32_bf16 v[126:129], v[144:147], v[160:163], v[126:129]
	v_mfma_f32_16x16x32_bf16 v[122:125], v[152:155], v[160:163], v[122:125]
	s_waitcnt lgkmcnt(3)
	v_mfma_f32_16x16x32_bf16 v[110:113], v[144:147], v[176:179], v[110:113]
	v_mfma_f32_16x16x32_bf16 v[106:109], v[152:155], v[176:179], v[106:109]
	v_mfma_f32_16x16x32_bf16 v[94:97], v[144:147], v[184:187], v[94:97]
	v_mfma_f32_16x16x32_bf16 v[90:93], v[152:155], v[184:187], v[90:93]
	s_waitcnt lgkmcnt(0)
	v_mfma_f32_16x16x32_bf16 v[78:81], v[144:147], v[192:195], v[78:81]
	v_mfma_f32_16x16x32_bf16 v[74:77], v[152:155], v[192:195], v[74:77]
	v_mfma_f32_16x16x32_bf16 v[126:129], v[148:151], v[168:171], v[126:129]
	v_mfma_f32_16x16x32_bf16 v[122:125], v[156:159], v[168:171], v[122:125]
	v_mfma_f32_16x16x32_bf16 v[110:113], v[148:151], v[180:183], v[110:113]
	v_mfma_f32_16x16x32_bf16 v[106:109], v[156:159], v[180:183], v[106:109]
	v_mfma_f32_16x16x32_bf16 v[94:97], v[148:151], v[188:191], v[94:97]
	v_mfma_f32_16x16x32_bf16 v[90:93], v[156:159], v[188:191], v[90:93]
	v_mfma_f32_16x16x32_bf16 v[78:81], v[148:151], v[196:199], v[78:81]
	v_mfma_f32_16x16x32_bf16 v[74:77], v[156:159], v[196:199], v[74:77]
	s_barrier
	s_add_i32 s59, 0, 0x14000
	s_add_i32 s57, s57, s34
	v_add_u32_e32 v48, s59, v166
	v_lshl_add_u64 v[164:165], s[12:13], 0, v[134:135]
	s_mov_b32 m0, s57
	ds_read_b128 v[200:203], v48
	ds_read_b128 v[204:207], v48 offset:1024
	ds_read_b128 v[208:211], v48 offset:2048
	ds_read_b128 v[212:215], v48 offset:3072
	global_load_lds_dwordx4 v[164:165], off
	s_add_i32 m0, s57, 0x2000
	v_lshl_add_u64 v[172:173], s[12:13], 0, v[130:131]
	global_load_lds_dwordx4 v[172:173], off
	s_barrier
; #define PG8_STAGE(bufoff, gbase, voff) do { _Pragma("unroll") for (int _i = 0; _i < 2; ++_i) \
;         __builtin_amdgcn_global_load_lds((const unsigned*)((const char*)(gbase) + (voff)[_i]), (PG8_LAS unsigned*)(lds + (bufoff) + ldsw + _i * 8192), 16, 0, 0); } while (0)
; #define PG8_LDA(dst, b, h) do { _Pragma("unroll") for (int m = 0; m < 4; ++m) _Pragma("unroll") for (int k = 0; k < 2; ++k) dst[m][k] = *(const PG8_LAS bf16x8*)(lds + PG8_SA(b, h) + aoff + m * 2048 + k * 1024); } while (0)
; #define PG8_LDB(dst, b, h) do { _Pragma("unroll") for (int n = 0; n < 2; ++n) _Pragma("unroll") for (int k = 0; k < 2; ++k) dst[n][k] = *(const PG8_LAS bf16x8*)(lds + PG8_SB(b, h) + boff + n * 2048 + k * 1024); } while (0)
; #define PG8_MMA(ai, bj, At, Bt) do { __builtin_amdgcn_s_setprio(1); _Pragma("unroll") for (int m = 0; m < 4; ++m) _Pragma("unroll") for (int n = 0; n < 2; ++n) _Pragma("unroll") for (int k = 0; k < 2; ++k) \
;         acc[ai][bj][m][n] = __builtin_amdgcn_mfma_f32_16x16x32_bf16(Bt[n][k], At[m][k], acc[ai][bj][m][n], 0, 0, 0); __builtin_amdgcn_s_setprio(0); } while (0)
; #define PG8_WAIT_V(n) asm volatile("s_waitcnt vmcnt(" #n ")" ::: "memory")
; #define PG8_WAIT_L(n) asm volatile("s_waitcnt lgkmcnt(" #n ")" ::: "memory")
; #define PG8_BAR __builtin_amdgcn_s_barrier()
; #define PG8_SCHED __builtin_amdgcn_sched_barrier(0)
; template <class Epi, class Sched>
; __device__ __forceinline__ void gemm_phase(PG8_LAS unsigned char* lds, const Gemm g, const Sched& S, const Epi& E) {
;     ...
;             PG8_BAR; PG8_WAIT_L(0); PG8_MMA(0, 1, At, B1); PG8_BAR;
;             PG8_LDA(At, 0, 1); PG8_STAGE(PG8_SA(0, 0), a2, voffA);
;             PG8_BAR; PG8_WAIT_L(0); PG8_MMA(1, 0, At, B0); PG8_BAR; PG8_SCHED;
;             PG8_STAGE(PG8_SB(0, 1), b2 + hstep, voffB);
;             PG8_WAIT_V(6); PG8_BAR; PG8_MMA(1, 1, At, B1); PG8_BAR;
;             PG8_LDB(B0, 1, 0); PG8_SCHED; PG8_LDA(At, 1, 0); PG8_STAGE(PG8_SA(0, 1), a2 + hstep, voffA);
;             PG8_WAIT_L(8); PG8_BAR; PG8_WAIT_L(0); PG8_MMA(0, 0, At, B0); PG8_BAR; PG8_SCHED;
	s_waitcnt lgkmcnt(3)
	v_mfma_f32_16x16x32_bf16 v[118:121], v[200:203], v[160:163], v[118:121]
	s_waitcnt lgkmcnt(0)
	v_mfma_f32_16x16x32_bf16 v[114:117], v[208:211], v[160:163], v[114:117]
	v_mfma_f32_16x16x32_bf16 v[102:105], v[200:203], v[176:179], v[102:105]
	v_mfma_f32_16x16x32_bf16 v[98:101], v[208:211], v[176:179], v[98:101]
	v_mfma_f32_16x16x32_bf16 v[86:89], v[200:203], v[184:187], v[86:89]
	v_mfma_f32_16x16x32_bf16 v[82:85], v[208:211], v[184:187], v[82:85]
	v_mfma_f32_16x16x32_bf16 v[70:73], v[200:203], v[192:195], v[70:73]
	v_mfma_f32_16x16x32_bf16 v[66:69], v[208:211], v[192:195], v[66:69]
	v_mfma_f32_16x16x32_bf16 v[118:121], v[204:207], v[168:171], v[118:121]
	v_mfma_f32_16x16x32_bf16 v[114:117], v[212:215], v[168:171], v[114:117]
	v_mfma_f32_16x16x32_bf16 v[102:105], v[204:207], v[180:183], v[102:105]
	v_mfma_f32_16x16x32_bf16 v[98:101], v[212:215], v[180:183], v[98:101]
	v_mfma_f32_16x16x32_bf16 v[86:89], v[204:207], v[188:191], v[86:89]
	v_mfma_f32_16x16x32_bf16 v[82:85], v[212:215], v[188:191], v[82:85]
	v_mfma_f32_16x16x32_bf16 v[70:73], v[204:207], v[196:199], v[70:73]
	v_mfma_f32_16x16x32_bf16 v[66:69], v[212:215], v[196:199], v[66:69]
	s_mov_b32 m0, s3
	v_lshl_add_u64 v[216:217], s[16:17], 0, v[136:137]
	s_barrier
	ds_read_b128 v[160:163], v167 offset:16384
	ds_read_b128 v[168:171], v167 offset:17408
	ds_read_b128 v[176:179], v167 offset:18432
	ds_read_b128 v[180:183], v167 offset:19456
	ds_read_b128 v[184:187], v167 offset:20480
	ds_read_b128 v[188:191], v167 offset:21504
	ds_read_b128 v[192:195], v167 offset:22528
	ds_read_b128 v[196:199], v167 offset:23552
	global_load_lds_dwordx4 v[216:217], off
	s_mov_b32 m0, s36
	v_lshl_add_u64 v[218:219], s[16:17], 0, v[132:133]
	global_load_lds_dwordx4 v[218:219], off
	s_barrier
	s_waitcnt lgkmcnt(7)
	v_mfma_f32_16x16x32_bf16 v[62:65], v[144:147], v[160:163], v[62:65]
	v_mfma_f32_16x16x32_bf16 v[58:61], v[152:155], v[160:163], v[58:61]
	s_waitcnt lgkmcnt(3)
	v_mfma_f32_16x16x32_bf16 v[44:47], v[144:147], v[176:179], v[44:47]
	v_mfma_f32_16x16x32_bf16 v[40:43], v[152:155], v[176:179], v[40:43]
	v_mfma_f32_16x16x32_bf16 v[28:31], v[144:147], v[184:187], v[28:31]
	v_mfma_f32_16x16x32_bf16 v[24:27], v[152:155], v[184:187], v[24:27]
	s_waitcnt lgkmcnt(0)
	v_mfma_f32_16x16x32_bf16 v[12:15], v[144:147], v[192:195], v[12:15]
	v_mfma_f32_16x16x32_bf16 v[8:11], v[152:155], v[192:195], v[8:11]
	v_mfma_f32_16x16x32_bf16 v[62:65], v[148:151], v[168:171], v[62:65]
	v_mfma_f32_16x16x32_bf16 v[58:61], v[156:159], v[168:171], v[58:61]
	v_mfma_f32_16x16x32_bf16 v[44:47], v[148:151], v[180:183], v[44:47]
	v_mfma_f32_16x16x32_bf16 v[40:43], v[156:159], v[180:183], v[40:43]
	v_mfma_f32_16x16x32_bf16 v[28:31], v[148:151], v[188:191], v[28:31]
	v_mfma_f32_16x16x32_bf16 v[24:27], v[156:159], v[188:191], v[24:27]
	v_mfma_f32_16x16x32_bf16 v[12:15], v[148:151], v[196:199], v[12:15]
	v_mfma_f32_16x16x32_bf16 v[8:11], v[156:159], v[196:199], v[8:11]
	s_barrier
	s_add_u32 s64, s12, 0x40000
	s_addc_u32 s65, s13, 0
	s_add_i32 s57, s59, s34
	s_mov_b32 m0, s57
	v_lshl_add_u64 v[144:145], s[64:65], 0, v[134:135]
	global_load_lds_dwordx4 v[144:145], off
	s_add_i32 m0, s57, 0x2000
	v_lshl_add_u64 v[144:145], s[64:65], 0, v[130:131]
	global_load_lds_dwordx4 v[144:145], off
	s_waitcnt vmcnt(6)
	s_barrier
	v_mfma_f32_16x16x32_bf16 v[54:57], v[200:203], v[160:163], v[54:57]
	v_mfma_f32_16x16x32_bf16 v[50:53], v[208:211], v[160:163], v[50:53]
	v_mfma_f32_16x16x32_bf16 v[36:39], v[200:203], v[176:179], v[36:39]
	v_mfma_f32_16x16x32_bf16 v[32:35], v[208:211], v[176:179], v[32:35]
	v_mfma_f32_16x16x32_bf16 v[20:23], v[200:203], v[184:187], v[20:23]
	v_mfma_f32_16x16x32_bf16 v[16:19], v[208:211], v[184:187], v[16:19]
	v_mfma_f32_16x16x32_bf16 v[4:7], v[200:203], v[192:195], v[4:7]
	v_mfma_f32_16x16x32_bf16 v[0:3], v[208:211], v[192:195], v[0:3]
	v_mfma_f32_16x16x32_bf16 v[54:57], v[204:207], v[168:171], v[54:57]
	v_mfma_f32_16x16x32_bf16 v[50:53], v[212:215], v[168:171], v[50:53]
	v_mfma_f32_16x16x32_bf16 v[36:39], v[204:207], v[180:183], v[36:39]
	v_mfma_f32_16x16x32_bf16 v[32:35], v[212:215], v[180:183], v[32:35]
	v_mfma_f32_16x16x32_bf16 v[20:23], v[204:207], v[188:191], v[20:23]
	v_mfma_f32_16x16x32_bf16 v[16:19], v[212:215], v[188:191], v[16:19]
	v_mfma_f32_16x16x32_bf16 v[4:7], v[204:207], v[196:199], v[4:7]
	v_mfma_f32_16x16x32_bf16 v[0:3], v[212:215], v[196:199], v[0:3]
	s_add_i32 s57, 0, 0x18000
	v_add_u32_e32 v48, s57, v166
	s_barrier
	ds_read_b128 v[144:147], v48
	ds_read_b128 v[148:151], v48 offset:1024
	ds_read_b128 v[152:155], v48 offset:2048
	ds_read_b128 v[156:159], v48 offset:3072
	s_add_u32 s16, s16, 0x40000
	s_addc_u32 s17, s17, 0
	s_mov_b32 m0, s37
	v_lshl_add_u64 v[200:201], s[16:17], 0, v[136:137]
	ds_read_b128 v[160:163], v167 offset:32768
	ds_read_b128 v[168:171], v167 offset:33792
	ds_read_b128 v[176:179], v167 offset:34816
	ds_read_b128 v[180:183], v167 offset:35840
	ds_read_b128 v[184:187], v167 offset:36864
	ds_read_b128 v[188:191], v167 offset:37888
	ds_read_b128 v[192:195], v167 offset:38912
	ds_read_b128 v[196:199], v167 offset:39936
	global_load_lds_dwordx4 v[200:201], off
	s_mov_b32 m0, s38
	v_lshl_add_u64 v[200:201], s[16:17], 0, v[132:133]
	global_load_lds_dwordx4 v[200:201], off
	s_waitcnt lgkmcnt(8)
	s_barrier
; #define PG8_STAGE(bufoff, gbase, voff) do { _Pragma("unroll") for (int _i = 0; _i < 2; ++_i) \
;         __builtin_amdgcn_global_load_lds((const unsigned*)((const char*)(gbase) + (voff)[_i]), (PG8_LAS unsigned*)(lds + (bufoff) + ldsw + _i * 8192), 16, 0, 0); } while (0)
; #define PG8_LDA(dst, b, h) do { _Pragma("unroll") for (int m = 0; m < 4; ++m) _Pragma("unroll") for (int k = 0; k < 2; ++k) dst[m][k] = *(const PG8_LAS bf16x8*)(lds + PG8_SA(b, h) + aoff + m * 2048 + k * 1024); } while (0)
; #define PG8_LDB(dst, b, h) do { _Pragma("unroll") for (int n = 0; n < 2; ++n) _Pragma("unroll") for (int k = 0; k < 2; ++k) dst[n][k] = *(const PG8_LAS bf16x8*)(lds + PG8_SB(b, h) + boff + n * 2048 + k * 1024); } while (0)
; #define PG8_MMA(ai, bj, At, Bt) do { __builtin_amdgcn_s_setprio(1); _Pragma("unroll") for (int m = 0; m < 4; ++m) _Pragma("unroll") for (int n = 0; n < 2; ++n) _Pragma("unroll") for (int k = 0; k < 2; ++k) \
;         acc[ai][bj][m][n] = __builtin_amdgcn_mfma_f32_16x16x32_bf16(Bt[n][k], At[m][k], acc[ai][bj][m][n], 0, 0, 0); __builtin_amdgcn_s_setprio(0); } while (0)
; #define PG8_WAIT_V(n) asm volatile("s_waitcnt vmcnt(" #n ")" ::: "memory")
; #define PG8_WAIT_L(n) asm volatile("s_waitcnt lgkmcnt(" #n ")" ::: "memory")
; #define PG8_BAR __builtin_amdgcn_s_barrier()
; #define PG8_SCHED __builtin_amdgcn_sched_barrier(0)
; template <class Epi, class Sched>
; __device__ __forceinline__ void gemm_phase(PG8_LAS unsigned char* lds, const Gemm g, const Sched& S, const Epi& E) {
;     ...
;             PG8_WAIT_L(8); PG8_BAR; PG8_WAIT_L(0); PG8_MMA(0, 0, At, B0); PG8_BAR; PG8_SCHED;
;             PG8_LDB(B1, 1, 1); PG8_STAGE(PG8_SB(1, 0), b3, voffB);
;             PG8_BAR; PG8_WAIT_L(0); PG8_MMA(0, 1, At, B1); PG8_BAR;
;             PG8_LDA(At, 1, 1); PG8_STAGE(PG8_SA(1, 0), a3, voffA);
;             PG8_BAR; PG8_WAIT_L(0); PG8_MMA(1, 0, At, B0); PG8_BAR; PG8_SCHED;
;             PG8_STAGE(PG8_SB(1, 1), b3 + hstep, voffB);
;             PG8_WAIT_V(6); PG8_BAR; PG8_MMA(1, 1, At, B1); PG8_BAR;
;         }
	s_waitcnt lgkmcnt(7)
	v_mfma_f32_16x16x32_bf16 v[126:129], v[144:147], v[160:163], v[126:129]
	v_mfma_f32_16x16x32_bf16 v[122:125], v[152:155], v[160:163], v[122:125]
	s_waitcnt lgkmcnt(3)
	v_mfma_f32_16x16x32_bf16 v[110:113], v[144:147], v[176:179], v[110:113]
	v_mfma_f32_16x16x32_bf16 v[106:109], v[152:155], v[176:179], v[106:109]
	v_mfma_f32_16x16x32_bf16 v[94:97], v[144:147], v[184:187], v[94:97]
	v_mfma_f32_16x16x32_bf16 v[90:93], v[152:155], v[184:187], v[90:93]
	s_waitcnt lgkmcnt(0)
	v_mfma_f32_16x16x32_bf16 v[78:81], v[144:147], v[192:195], v[78:81]
	v_mfma_f32_16x16x32_bf16 v[74:77], v[152:155], v[192:195], v[74:77]
	v_mfma_f32_16x16x32_bf16 v[126:129], v[148:151], v[168:171], v[126:129]
	v_mfma_f32_16x16x32_bf16 v[122:125], v[156:159], v[168:171], v[122:125]
	v_mfma_f32_16x16x32_bf16 v[110:113], v[148:151], v[180:183], v[110:113]
	v_mfma_f32_16x16x32_bf16 v[106:109], v[156:159], v[180:183], v[106:109]
	v_mfma_f32_16x16x32_bf16 v[94:97], v[148:151], v[188:191], v[94:97]
	v_mfma_f32_16x16x32_bf16 v[90:93], v[156:159], v[188:191], v[90:93]
	v_mfma_f32_16x16x32_bf16 v[78:81], v[148:151], v[196:199], v[78:81]
	v_mfma_f32_16x16x32_bf16 v[74:77], v[156:159], v[196:199], v[74:77]
	s_barrier
	s_add_i32 s16, 0, 0x1c000
	s_add_i32 s17, s57, s34
	v_add_u32_e32 v48, s16, v166
	v_lshl_add_u64 v[164:165], v[164:165], 0, s[0:1]
	s_mov_b32 m0, s17
	ds_read_b128 v[200:203], v48
	ds_read_b128 v[204:207], v48 offset:1024
	ds_read_b128 v[208:211], v48 offset:2048
	ds_read_b128 v[212:215], v48 offset:3072
	global_load_lds_dwordx4 v[164:165], off
	s_add_i32 m0, s17, 0x2000
	v_lshl_add_u64 v[164:165], v[172:173], 0, s[0:1]
	global_load_lds_dwordx4 v[164:165], off
	s_barrier
	s_waitcnt lgkmcnt(3)
	v_mfma_f32_16x16x32_bf16 v[118:121], v[200:203], v[160:163], v[118:121]
	s_waitcnt lgkmcnt(0)
	v_mfma_f32_16x16x32_bf16 v[114:117], v[208:211], v[160:163], v[114:117]
	v_mfma_f32_16x16x32_bf16 v[102:105], v[200:203], v[176:179], v[102:105]
	v_mfma_f32_16x16x32_bf16 v[98:101], v[208:211], v[176:179], v[98:101]
	v_mfma_f32_16x16x32_bf16 v[86:89], v[200:203], v[184:187], v[86:89]
	v_mfma_f32_16x16x32_bf16 v[82:85], v[208:211], v[184:187], v[82:85]
	v_mfma_f32_16x16x32_bf16 v[70:73], v[200:203], v[192:195], v[70:73]
	v_mfma_f32_16x16x32_bf16 v[66:69], v[208:211], v[192:195], v[66:69]
	v_mfma_f32_16x16x32_bf16 v[118:121], v[204:207], v[168:171], v[118:121]
	v_mfma_f32_16x16x32_bf16 v[114:117], v[212:215], v[168:171], v[114:117]
	v_mfma_f32_16x16x32_bf16 v[102:105], v[204:207], v[180:183], v[102:105]
	v_mfma_f32_16x16x32_bf16 v[98:101], v[212:215], v[180:183], v[98:101]
	v_mfma_f32_16x16x32_bf16 v[86:89], v[204:207], v[188:191], v[86:89]
	v_mfma_f32_16x16x32_bf16 v[82:85], v[212:215], v[188:191], v[82:85]
	v_mfma_f32_16x16x32_bf16 v[70:73], v[204:207], v[196:199], v[70:73]
	v_mfma_f32_16x16x32_bf16 v[66:69], v[212:215], v[196:199], v[66:69]
	s_mov_b32 m0, s39
	v_lshl_add_u64 v[164:165], v[216:217], 0, s[0:1]
	s_barrier
	ds_read_b128 v[160:163], v167 offset:49152
	ds_read_b128 v[168:171], v167 offset:50176
	ds_read_b128 v[176:179], v167 offset:51200
	ds_read_b128 v[180:183], v167 offset:52224
	ds_read_b128 v[184:187], v167 offset:53248
	ds_read_b128 v[188:191], v167 offset:54272
	ds_read_b128 v[192:195], v167 offset:55296
	ds_read_b128 v[196:199], v167 offset:56320
	global_load_lds_dwordx4 v[164:165], off
	s_mov_b32 m0, s42
	v_lshl_add_u64 v[164:165], v[218:219], 0, s[0:1]
	global_load_lds_dwordx4 v[164:165], off
	s_barrier
	s_waitcnt lgkmcnt(7)
	v_mfma_f32_16x16x32_bf16 v[62:65], v[144:147], v[160:163], v[62:65]
	v_mfma_f32_16x16x32_bf16 v[58:61], v[152:155], v[160:163], v[58:61]
	s_waitcnt lgkmcnt(3)
	v_mfma_f32_16x16x32_bf16 v[44:47], v[144:147], v[176:179], v[44:47]
	v_mfma_f32_16x16x32_bf16 v[40:43], v[152:155], v[176:179], v[40:43]
	v_mfma_f32_16x16x32_bf16 v[28:31], v[144:147], v[184:187], v[28:31]
	v_mfma_f32_16x16x32_bf16 v[24:27], v[152:155], v[184:187], v[24:27]
	s_waitcnt lgkmcnt(0)
	v_mfma_f32_16x16x32_bf16 v[12:15], v[144:147], v[192:195], v[12:15]
	v_mfma_f32_16x16x32_bf16 v[8:11], v[152:155], v[192:195], v[8:11]
	v_mfma_f32_16x16x32_bf16 v[62:65], v[148:151], v[168:171], v[62:65]
	v_mfma_f32_16x16x32_bf16 v[58:61], v[156:159], v[168:171], v[58:61]
	v_mfma_f32_16x16x32_bf16 v[44:47], v[148:151], v[180:183], v[44:47]
	v_mfma_f32_16x16x32_bf16 v[40:43], v[156:159], v[180:183], v[40:43]
	v_mfma_f32_16x16x32_bf16 v[28:31], v[148:151], v[188:191], v[28:31]
	v_mfma_f32_16x16x32_bf16 v[24:27], v[156:159], v[188:191], v[24:27]
	v_mfma_f32_16x16x32_bf16 v[12:15], v[148:151], v[196:199], v[12:15]
	v_mfma_f32_16x16x32_bf16 v[8:11], v[156:159], v[196:199], v[8:11]
	s_barrier
	s_add_u32 s12, s12, 0x40080
	s_addc_u32 s13, s13, 0
	s_add_i32 s16, s16, s34
	s_mov_b32 m0, s16
	v_lshl_add_u64 v[144:145], s[12:13], 0, v[134:135]
	global_load_lds_dwordx4 v[144:145], off
	s_add_i32 m0, s16, 0x2000
	v_lshl_add_u64 v[144:145], s[12:13], 0, v[130:131]
	global_load_lds_dwordx4 v[144:145], off
	s_waitcnt vmcnt(6)
	s_barrier
	v_mfma_f32_16x16x32_bf16 v[54:57], v[200:203], v[160:163], v[54:57]
	v_mfma_f32_16x16x32_bf16 v[50:53], v[208:211], v[160:163], v[50:53]
	v_mfma_f32_16x16x32_bf16 v[36:39], v[200:203], v[176:179], v[36:39]
	v_mfma_f32_16x16x32_bf16 v[32:35], v[208:211], v[176:179], v[32:35]
	v_mfma_f32_16x16x32_bf16 v[20:23], v[200:203], v[184:187], v[20:23]
	v_mfma_f32_16x16x32_bf16 v[16:19], v[208:211], v[184:187], v[16:19]
	v_mfma_f32_16x16x32_bf16 v[4:7], v[200:203], v[192:195], v[4:7]
	v_mfma_f32_16x16x32_bf16 v[0:3], v[208:211], v[192:195], v[0:3]
	v_mfma_f32_16x16x32_bf16 v[54:57], v[204:207], v[168:171], v[54:57]
	v_mfma_f32_16x16x32_bf16 v[50:53], v[212:215], v[168:171], v[50:53]
	v_mfma_f32_16x16x32_bf16 v[36:39], v[204:207], v[180:183], v[36:39]
	v_mfma_f32_16x16x32_bf16 v[32:35], v[212:215], v[180:183], v[32:35]
	v_mfma_f32_16x16x32_bf16 v[20:23], v[204:207], v[188:191], v[20:23]
	v_mfma_f32_16x16x32_bf16 v[16:19], v[212:215], v[188:191], v[16:19]
	v_mfma_f32_16x16x32_bf16 v[4:7], v[204:207], v[196:199], v[4:7]
	v_mfma_f32_16x16x32_bf16 v[0:3], v[212:215], v[196:199], v[0:3]
	s_add_i32 s56, s56, 2
	s_add_u32 s6, s6, 0x100
	s_addc_u32 s7, s7, 0
	s_add_u32 s54, s54, 0x100
	s_addc_u32 s55, s55, 0
	s_cmp_gt_u32 s56, 13
	s_barrier
	s_cbranch_scc0 .LBB0_335

; #define PG8_STAGE(bufoff, gbase, voff) do { _Pragma("unroll") for (int _i = 0; _i < 2; ++_i) \
;         __builtin_amdgcn_global_load_lds((const unsigned*)((const char*)(gbase) + (voff)[_i]), (PG8_LAS unsigned*)(lds + (bufoff) + ldsw + _i * 8192), 16, 0, 0); } while (0)
; #define PG8_LDA(dst, b, h) do { _Pragma("unroll") for (int m = 0; m < 4; ++m) _Pragma("unroll") for (int k = 0; k < 2; ++k) dst[m][k] = *(const PG8_LAS bf16x8*)(lds + PG8_SA(b, h) + aoff + m * 2048 + k * 1024); } while (0)
; #define PG8_LDB(dst, b, h) do { _Pragma("unroll") for (int n = 0; n < 2; ++n) _Pragma("unroll") for (int k = 0; k < 2; ++k) dst[n][k] = *(const PG8_LAS bf16x8*)(lds + PG8_SB(b, h) + boff + n * 2048 + k * 1024); } while (0)
; #define PG8_WAIT_L(n) asm volatile("s_waitcnt lgkmcnt(" #n ")" ::: "memory")
; #define PG8_BAR __builtin_amdgcn_s_barrier()
; #define PG8_SCHED __builtin_amdgcn_sched_barrier(0)
; template <class Epi, class Sched>
; __device__ __forceinline__ void gemm_phase(PG8_LAS unsigned char* lds, const Gemm g, const Sched& S, const Epi& E) {
;     ...
;         const bool has_next = S.next(ui + 1, nxt);
;         const char* nA = has_next ? (const char*)g.A + (size_t)nxt.pm * tstepA + (size_t)nxt.kc * cstep : cA; const char* nB = has_next ? (const char*)g.Bt + (size_t)nxt.pn * tstep + (size_t)nxt.kc * cstep : cB;
;         for (int t = 0; t < nt; t += 2) {
;             const bool last = (t == nt - 2);
;             const char* a1 = cA + (size_t)(t + 1) * kstep;
;             const char* a2 = last ? nA : cA + (size_t)(t + 2) * kstep; const char* b2 = last ? nB : cB + (size_t)(t + 2) * kstep;
;             const char* a3 = a2 + kstep; const char* b3 = b2 + kstep;
;             if (last && has_next) S.a_ready(nxt);
;             PG8_LDB(B0, 0, 0); PG8_SCHED; PG8_LDA(At, 0, 0); PG8_STAGE(PG8_SA(1, 1), a1 + hstep, voffA);
;             PG8_WAIT_L(8); PG8_BAR; PG8_WAIT_L(0); PG8_MMA(0, 0, At, B0); PG8_BAR; PG8_SCHED;
;             PG8_LDB(B1, 0, 1); PG8_STAGE(PG8_SB(0, 0), b2, voffB);
;             PG8_BAR; PG8_WAIT_L(0); PG8_MMA(0, 1, At, B1); PG8_BAR;
;             PG8_LDA(At, 0, 1); PG8_STAGE(PG8_SA(0, 0), a2, voffA);
;             PG8_BAR; PG8_WAIT_L(0); PG8_MMA(1, 0, At, B0); PG8_BAR; PG8_SCHED;
.LBB0_387:
	s_ashr_i32 s39, s38, 31
	s_lshl_b64 s[16:17], s[38:39], 19
	v_readlane_b32 s3, v254, 53
	s_add_u32 s94, s3, s16
	v_readlane_b32 s3, v254, 54
	s_addc_u32 s95, s3, s17
	s_and_b64 s[16:17], s[62:63], exec
	s_cselect_b32 s3, s95, s13
	s_cselect_b32 s26, s94, s12
	s_add_u32 s6, s6, 0x40080
	s_addc_u32 s7, s7, 0
	s_add_u32 s27, s12, 0x100
	s_addc_u32 s29, s13, 0
	s_mov_b32 s30, -2
	s_add_u32 s12, s6, 0xfffc0080
	s_addc_u32 s13, s7, -1
	s_add_i32 s22, 0, 0x10000
	v_add_u32_e32 v48, s22, v250
	ds_read_b128 v[130:133], v48
	ds_read_b128 v[134:137], v48 offset:1024
	ds_read_b128 v[138:141], v48 offset:2048
	ds_read_b128 v[142:145], v48 offset:3072
	s_cmp_eq_u32 s30, 12
	s_cselect_b32 s17, s9, s13
	s_cselect_b32 s16, s8, s12
	s_cselect_b32 s13, s3, s29
	s_cselect_b32 s12, s26, s27
	v_lshl_add_u64 v[192:193], s[6:7], 0, v[184:185]
	s_add_i32 m0, s37, 0xc000
	ds_read_b128 v[146:149], v242
	ds_read_b128 v[150:153], v242 offset:1024
	ds_read_b128 v[154:157], v242 offset:2048
	ds_read_b128 v[158:161], v242 offset:3072
	ds_read_b128 v[162:165], v242 offset:4096
	ds_read_b128 v[166:169], v242 offset:5120
	ds_read_b128 v[170:173], v242 offset:6144
	ds_read_b128 v[188:191], v242 offset:7168
	global_load_lds_dwordx4 v[192:193], off
	s_add_i32 m0, s37, 0xe000
	v_lshl_add_u64 v[192:193], s[6:7], 0, v[186:187]
	global_load_lds_dwordx4 v[192:193], off
	s_waitcnt lgkmcnt(8)
	s_barrier
	s_waitcnt lgkmcnt(7)
	v_mfma_f32_16x16x32_bf16 v[126:129], v[130:133], v[146:149], 0
	v_mfma_f32_16x16x32_bf16 v[62:65], v[138:141], v[146:149], 0
	s_waitcnt lgkmcnt(3)
	v_mfma_f32_16x16x32_bf16 v[118:121], v[130:133], v[154:157], 0
	v_mfma_f32_16x16x32_bf16 v[54:57], v[138:141], v[154:157], 0
	v_mfma_f32_16x16x32_bf16 v[110:113], v[130:133], v[162:165], 0
	v_mfma_f32_16x16x32_bf16 v[44:47], v[138:141], v[162:165], 0
	s_waitcnt lgkmcnt(0)
	v_mfma_f32_16x16x32_bf16 v[102:105], v[130:133], v[170:173], 0
	v_mfma_f32_16x16x32_bf16 v[36:39], v[138:141], v[170:173], 0
	v_mfma_f32_16x16x32_bf16 v[126:129], v[134:137], v[150:153], v[126:129]
	v_mfma_f32_16x16x32_bf16 v[62:65], v[142:145], v[150:153], v[62:65]
	v_mfma_f32_16x16x32_bf16 v[118:121], v[134:137], v[158:161], v[118:121]
	v_mfma_f32_16x16x32_bf16 v[54:57], v[142:145], v[158:161], v[54:57]
	v_mfma_f32_16x16x32_bf16 v[110:113], v[134:137], v[166:169], v[110:113]
	v_mfma_f32_16x16x32_bf16 v[44:47], v[142:145], v[166:169], v[44:47]
	v_mfma_f32_16x16x32_bf16 v[102:105], v[134:137], v[188:191], v[102:105]
	v_mfma_f32_16x16x32_bf16 v[36:39], v[142:145], v[188:191], v[36:39]
	s_barrier
	s_add_i32 s31, 0, 0x14000
	s_add_i32 s22, s22, s36
	v_add_u32_e32 v48, s31, v250
	v_lshl_add_u64 v[208:209], s[12:13], 0, v[178:179]
	s_mov_b32 m0, s22
	ds_read_b128 v[192:195], v48
	ds_read_b128 v[196:199], v48 offset:1024
	ds_read_b128 v[200:203], v48 offset:2048
	ds_read_b128 v[204:207], v48 offset:3072
	global_load_lds_dwordx4 v[208:209], off
	s_add_i32 m0, s22, 0x2000
	v_lshl_add_u64 v[210:211], s[12:13], 0, v[182:183]
	global_load_lds_dwordx4 v[210:211], off
	s_barrier
	s_waitcnt lgkmcnt(3)
	v_mfma_f32_16x16x32_bf16 v[122:125], v[192:195], v[146:149], 0
	s_waitcnt lgkmcnt(0)
	v_mfma_f32_16x16x32_bf16 v[58:61], v[200:203], v[146:149], 0
	v_mfma_f32_16x16x32_bf16 v[114:117], v[192:195], v[154:157], 0
	v_mfma_f32_16x16x32_bf16 v[50:53], v[200:203], v[154:157], 0
	v_mfma_f32_16x16x32_bf16 v[106:109], v[192:195], v[162:165], 0
	v_mfma_f32_16x16x32_bf16 v[40:43], v[200:203], v[162:165], 0
	v_mfma_f32_16x16x32_bf16 v[98:101], v[192:195], v[170:173], 0
	v_mfma_f32_16x16x32_bf16 v[32:35], v[200:203], v[170:173], 0
	v_mfma_f32_16x16x32_bf16 v[122:125], v[196:199], v[150:153], v[122:125]
	v_mfma_f32_16x16x32_bf16 v[58:61], v[204:207], v[150:153], v[58:61]
	v_mfma_f32_16x16x32_bf16 v[114:117], v[196:199], v[158:161], v[114:117]
	v_mfma_f32_16x16x32_bf16 v[50:53], v[204:207], v[158:161], v[50:53]
	v_mfma_f32_16x16x32_bf16 v[106:109], v[196:199], v[166:169], v[106:109]
	v_mfma_f32_16x16x32_bf16 v[40:43], v[204:207], v[166:169], v[40:43]
	v_mfma_f32_16x16x32_bf16 v[98:101], v[196:199], v[188:191], v[98:101]
	v_mfma_f32_16x16x32_bf16 v[32:35], v[204:207], v[188:191], v[32:35]
	s_mov_b32 m0, s37
	v_lshl_add_u64 v[212:213], s[16:17], 0, v[176:177]
	s_barrier
	ds_read_b128 v[146:149], v242 offset:16384
	ds_read_b128 v[150:153], v242 offset:17408
	ds_read_b128 v[154:157], v242 offset:18432
	ds_read_b128 v[158:161], v242 offset:19456
	ds_read_b128 v[162:165], v242 offset:20480
	ds_read_b128 v[166:169], v242 offset:21504
	ds_read_b128 v[170:173], v242 offset:22528
	ds_read_b128 v[188:191], v242 offset:23552
	global_load_lds_dwordx4 v[212:213], off
	s_mov_b32 m0, s10
	v_lshl_add_u64 v[214:215], s[16:17], 0, v[180:181]
	global_load_lds_dwordx4 v[214:215], off
	s_barrier
	s_waitcnt lgkmcnt(7)
	v_mfma_f32_16x16x32_bf16 v[94:97], v[130:133], v[146:149], 0
	v_mfma_f32_16x16x32_bf16 v[28:31], v[138:141], v[146:149], 0
	s_waitcnt lgkmcnt(3)
	v_mfma_f32_16x16x32_bf16 v[86:89], v[130:133], v[154:157], 0
	v_mfma_f32_16x16x32_bf16 v[20:23], v[138:141], v[154:157], 0
	v_mfma_f32_16x16x32_bf16 v[78:81], v[130:133], v[162:165], 0
	v_mfma_f32_16x16x32_bf16 v[12:15], v[138:141], v[162:165], 0
	s_waitcnt lgkmcnt(0)
	v_mfma_f32_16x16x32_bf16 v[70:73], v[130:133], v[170:173], 0
	v_mfma_f32_16x16x32_bf16 v[4:7], v[138:141], v[170:173], 0
	v_mfma_f32_16x16x32_bf16 v[94:97], v[134:137], v[150:153], v[94:97]
	v_mfma_f32_16x16x32_bf16 v[28:31], v[142:145], v[150:153], v[28:31]
	v_mfma_f32_16x16x32_bf16 v[86:89], v[134:137], v[158:161], v[86:89]
	v_mfma_f32_16x16x32_bf16 v[20:23], v[142:145], v[158:161], v[20:23]
	v_mfma_f32_16x16x32_bf16 v[78:81], v[134:137], v[166:169], v[78:81]
	v_mfma_f32_16x16x32_bf16 v[12:15], v[142:145], v[166:169], v[12:15]
	v_mfma_f32_16x16x32_bf16 v[70:73], v[134:137], v[188:191], v[70:73]
	v_mfma_f32_16x16x32_bf16 v[4:7], v[142:145], v[188:191], v[4:7]
	s_barrier
; #define PG8_STAGE(bufoff, gbase, voff) do { _Pragma("unroll") for (int _i = 0; _i < 2; ++_i) \
;         __builtin_amdgcn_global_load_lds((const unsigned*)((const char*)(gbase) + (voff)[_i]), (PG8_LAS unsigned*)(lds + (bufoff) + ldsw + _i * 8192), 16, 0, 0); } while (0)
; #define PG8_LDA(dst, b, h) do { _Pragma("unroll") for (int m = 0; m < 4; ++m) _Pragma("unroll") for (int k = 0; k < 2; ++k) dst[m][k] = *(const PG8_LAS bf16x8*)(lds + PG8_SA(b, h) + aoff + m * 2048 + k * 1024); } while (0)
; #define PG8_LDB(dst, b, h) do { _Pragma("unroll") for (int n = 0; n < 2; ++n) _Pragma("unroll") for (int k = 0; k < 2; ++k) dst[n][k] = *(const PG8_LAS bf16x8*)(lds + PG8_SB(b, h) + boff + n * 2048 + k * 1024); } while (0)
; #define PG8_MMA(ai, bj, At, Bt) do { __builtin_amdgcn_s_setprio(1); _Pragma("unroll") for (int m = 0; m < 4; ++m) _Pragma("unroll") for (int n = 0; n < 2; ++n) _Pragma("unroll") for (int k = 0; k < 2; ++k) \
;         acc[ai][bj][m][n] = __builtin_amdgcn_mfma_f32_16x16x32_bf16(Bt[n][k], At[m][k], acc[ai][bj][m][n], 0, 0, 0); __builtin_amdgcn_s_setprio(0); } while (0)
; #define PG8_WAIT_V(n) asm volatile("s_waitcnt vmcnt(" #n ")" ::: "memory")
; #define PG8_WAIT_L(n) asm volatile("s_waitcnt lgkmcnt(" #n ")" ::: "memory")
; #define PG8_BAR __builtin_amdgcn_s_barrier()
; #define PG8_SCHED __builtin_amdgcn_sched_barrier(0)
; template <class Epi, class Sched>
; __device__ __forceinline__ void gemm_phase(PG8_LAS unsigned char* lds, const Gemm g, const Sched& S, const Epi& E) {
;     ...
;             PG8_STAGE(PG8_SB(0, 1), b2 + hstep, voffB);
;             PG8_WAIT_V(6); PG8_BAR; PG8_MMA(1, 1, At, B1); PG8_BAR;
;             PG8_LDB(B0, 1, 0); PG8_SCHED; PG8_LDA(At, 1, 0); PG8_STAGE(PG8_SA(0, 1), a2 + hstep, voffA);
;             PG8_WAIT_L(8); PG8_BAR; PG8_WAIT_L(0); PG8_MMA(0, 0, At, B0); PG8_BAR; PG8_SCHED;
;             PG8_LDB(B1, 1, 1); PG8_STAGE(PG8_SB(1, 0), b3, voffB);
;             PG8_BAR; PG8_WAIT_L(0); PG8_MMA(0, 1, At, B1); PG8_BAR;
;             PG8_LDA(At, 1, 1); PG8_STAGE(PG8_SA(1, 0), a3, voffA);
	s_add_u32 s22, s12, 0x40000
	s_addc_u32 s23, s13, 0
	s_add_i32 s31, s31, s36
	s_mov_b32 m0, s31
	v_lshl_add_u64 v[130:131], s[22:23], 0, v[178:179]
	global_load_lds_dwordx4 v[130:131], off
	s_add_i32 m0, s31, 0x2000
	v_lshl_add_u64 v[130:131], s[22:23], 0, v[182:183]
	global_load_lds_dwordx4 v[130:131], off
	s_waitcnt vmcnt(6)
	s_barrier
	v_mfma_f32_16x16x32_bf16 v[90:93], v[192:195], v[146:149], 0
	v_mfma_f32_16x16x32_bf16 v[24:27], v[200:203], v[146:149], 0
	v_mfma_f32_16x16x32_bf16 v[82:85], v[192:195], v[154:157], 0
	v_mfma_f32_16x16x32_bf16 v[16:19], v[200:203], v[154:157], 0
	v_mfma_f32_16x16x32_bf16 v[74:77], v[192:195], v[162:165], 0
	v_mfma_f32_16x16x32_bf16 v[8:11], v[200:203], v[162:165], 0
	v_mfma_f32_16x16x32_bf16 v[66:69], v[192:195], v[170:173], 0
	v_mfma_f32_16x16x32_bf16 v[0:3], v[200:203], v[170:173], 0
	v_mfma_f32_16x16x32_bf16 v[90:93], v[196:199], v[150:153], v[90:93]
	v_mfma_f32_16x16x32_bf16 v[24:27], v[204:207], v[150:153], v[24:27]
	v_mfma_f32_16x16x32_bf16 v[82:85], v[196:199], v[158:161], v[82:85]
	v_mfma_f32_16x16x32_bf16 v[16:19], v[204:207], v[158:161], v[16:19]
	v_mfma_f32_16x16x32_bf16 v[74:77], v[196:199], v[166:169], v[74:77]
	v_mfma_f32_16x16x32_bf16 v[8:11], v[204:207], v[166:169], v[8:11]
	v_mfma_f32_16x16x32_bf16 v[66:69], v[196:199], v[188:191], v[66:69]
	v_mfma_f32_16x16x32_bf16 v[0:3], v[204:207], v[188:191], v[0:3]
	s_add_i32 s22, 0, 0x18000
	v_add_u32_e32 v48, s22, v250
	s_barrier
	ds_read_b128 v[130:133], v48
	ds_read_b128 v[134:137], v48 offset:1024
	ds_read_b128 v[138:141], v48 offset:2048
	ds_read_b128 v[142:145], v48 offset:3072
	s_add_u32 s16, s16, 0x40000
	s_addc_u32 s17, s17, 0
	s_mov_b32 m0, s11
	v_lshl_add_u64 v[192:193], s[16:17], 0, v[176:177]
	ds_read_b128 v[146:149], v242 offset:32768
	ds_read_b128 v[150:153], v242 offset:33792
	ds_read_b128 v[154:157], v242 offset:34816
	ds_read_b128 v[158:161], v242 offset:35840
	ds_read_b128 v[162:165], v242 offset:36864
	ds_read_b128 v[166:169], v242 offset:37888
	ds_read_b128 v[170:173], v242 offset:38912
	ds_read_b128 v[188:191], v242 offset:39936
	global_load_lds_dwordx4 v[192:193], off
	s_mov_b32 m0, s24
	v_lshl_add_u64 v[192:193], s[16:17], 0, v[180:181]
	global_load_lds_dwordx4 v[192:193], off
	s_waitcnt lgkmcnt(8)
	s_barrier
	s_waitcnt lgkmcnt(7)
	v_mfma_f32_16x16x32_bf16 v[126:129], v[130:133], v[146:149], v[126:129]
	v_mfma_f32_16x16x32_bf16 v[62:65], v[138:141], v[146:149], v[62:65]
	s_waitcnt lgkmcnt(3)
	v_mfma_f32_16x16x32_bf16 v[118:121], v[130:133], v[154:157], v[118:121]
	v_mfma_f32_16x16x32_bf16 v[54:57], v[138:141], v[154:157], v[54:57]
	v_mfma_f32_16x16x32_bf16 v[110:113], v[130:133], v[162:165], v[110:113]
	v_mfma_f32_16x16x32_bf16 v[44:47], v[138:141], v[162:165], v[44:47]
	s_waitcnt lgkmcnt(0)
	v_mfma_f32_16x16x32_bf16 v[102:105], v[130:133], v[170:173], v[102:105]
	v_mfma_f32_16x16x32_bf16 v[36:39], v[138:141], v[170:173], v[36:39]
	v_mfma_f32_16x16x32_bf16 v[126:129], v[134:137], v[150:153], v[126:129]
	v_mfma_f32_16x16x32_bf16 v[62:65], v[142:145], v[150:153], v[62:65]
	v_mfma_f32_16x16x32_bf16 v[118:121], v[134:137], v[158:161], v[118:121]
	v_mfma_f32_16x16x32_bf16 v[54:57], v[142:145], v[158:161], v[54:57]
	v_mfma_f32_16x16x32_bf16 v[110:113], v[134:137], v[166:169], v[110:113]
	v_mfma_f32_16x16x32_bf16 v[44:47], v[142:145], v[166:169], v[44:47]
	v_mfma_f32_16x16x32_bf16 v[102:105], v[134:137], v[188:191], v[102:105]
	v_mfma_f32_16x16x32_bf16 v[36:39], v[142:145], v[188:191], v[36:39]
	s_barrier
	s_add_i32 s16, 0, 0x1c000
	s_add_i32 s17, s22, s36
	v_add_u32_e32 v48, s16, v250
	v_lshl_add_u64 v[208:209], v[208:209], 0, s[0:1]
	s_mov_b32 m0, s17
	ds_read_b128 v[192:195], v48
	ds_read_b128 v[196:199], v48 offset:1024
	ds_read_b128 v[200:203], v48 offset:2048
	ds_read_b128 v[204:207], v48 offset:3072
	global_load_lds_dwordx4 v[208:209], off
	s_add_i32 m0, s17, 0x2000
	v_lshl_add_u64 v[208:209], v[210:211], 0, s[0:1]
	global_load_lds_dwordx4 v[208:209], off
	s_barrier
	s_waitcnt lgkmcnt(3)
	v_mfma_f32_16x16x32_bf16 v[122:125], v[192:195], v[146:149], v[122:125]
	s_waitcnt lgkmcnt(0)
	v_mfma_f32_16x16x32_bf16 v[58:61], v[200:203], v[146:149], v[58:61]
	v_mfma_f32_16x16x32_bf16 v[114:117], v[192:195], v[154:157], v[114:117]
	v_mfma_f32_16x16x32_bf16 v[50:53], v[200:203], v[154:157], v[50:53]
	v_mfma_f32_16x16x32_bf16 v[106:109], v[192:195], v[162:165], v[106:109]
	v_mfma_f32_16x16x32_bf16 v[40:43], v[200:203], v[162:165], v[40:43]
	v_mfma_f32_16x16x32_bf16 v[98:101], v[192:195], v[170:173], v[98:101]
	v_mfma_f32_16x16x32_bf16 v[32:35], v[200:203], v[170:173], v[32:35]
	v_mfma_f32_16x16x32_bf16 v[122:125], v[196:199], v[150:153], v[122:125]
	v_mfma_f32_16x16x32_bf16 v[58:61], v[204:207], v[150:153], v[58:61]
	v_mfma_f32_16x16x32_bf16 v[114:117], v[196:199], v[158:161], v[114:117]
	v_mfma_f32_16x16x32_bf16 v[50:53], v[204:207], v[158:161], v[50:53]
	v_mfma_f32_16x16x32_bf16 v[106:109], v[196:199], v[166:169], v[106:109]
	v_mfma_f32_16x16x32_bf16 v[40:43], v[204:207], v[166:169], v[40:43]
	v_mfma_f32_16x16x32_bf16 v[98:101], v[196:199], v[188:191], v[98:101]
	v_mfma_f32_16x16x32_bf16 v[32:35], v[204:207], v[188:191], v[32:35]
	s_mov_b32 m0, s25
	v_lshl_add_u64 v[208:209], v[212:213], 0, s[0:1]
	s_barrier
	ds_read_b128 v[146:149], v242 offset:49152
	ds_read_b128 v[150:153], v242 offset:50176
	ds_read_b128 v[154:157], v242 offset:51200
	ds_read_b128 v[158:161], v242 offset:52224
	ds_read_b128 v[162:165], v242 offset:53248
	ds_read_b128 v[166:169], v242 offset:54272
	ds_read_b128 v[170:173], v242 offset:55296
	ds_read_b128 v[188:191], v242 offset:56320
	global_load_lds_dwordx4 v[208:209], off
	s_mov_b32 m0, s18
	v_lshl_add_u64 v[208:209], v[214:215], 0, s[0:1]
	global_load_lds_dwordx4 v[208:209], off
	s_barrier
; #define PG8_STAGE(bufoff, gbase, voff) do { _Pragma("unroll") for (int _i = 0; _i < 2; ++_i) \
;         __builtin_amdgcn_global_load_lds((const unsigned*)((const char*)(gbase) + (voff)[_i]), (PG8_LAS unsigned*)(lds + (bufoff) + ldsw + _i * 8192), 16, 0, 0); } while (0)
; #define PG8_LDA(dst, b, h) do { _Pragma("unroll") for (int m = 0; m < 4; ++m) _Pragma("unroll") for (int k = 0; k < 2; ++k) dst[m][k] = *(const PG8_LAS bf16x8*)(lds + PG8_SA(b, h) + aoff + m * 2048 + k * 1024); } while (0)
; #define PG8_LDB(dst, b, h) do { _Pragma("unroll") for (int n = 0; n < 2; ++n) _Pragma("unroll") for (int k = 0; k < 2; ++k) dst[n][k] = *(const PG8_LAS bf16x8*)(lds + PG8_SB(b, h) + boff + n * 2048 + k * 1024); } while (0)
; #define PG8_MMA(ai, bj, At, Bt) do { __builtin_amdgcn_s_setprio(1); _Pragma("unroll") for (int m = 0; m < 4; ++m) _Pragma("unroll") for (int n = 0; n < 2; ++n) _Pragma("unroll") for (int k = 0; k < 2; ++k) \
;         acc[ai][bj][m][n] = __builtin_amdgcn_mfma_f32_16x16x32_bf16(Bt[n][k], At[m][k], acc[ai][bj][m][n], 0, 0, 0); __builtin_amdgcn_s_setprio(0); } while (0)
; #define PG8_WAIT_V(n) asm volatile("s_waitcnt vmcnt(" #n ")" ::: "memory")
; #define PG8_WAIT_L(n) asm volatile("s_waitcnt lgkmcnt(" #n ")" ::: "memory")
; #define PG8_BAR __builtin_amdgcn_s_barrier()
; #define PG8_SCHED __builtin_amdgcn_sched_barrier(0)
; template <class Epi, class Sched>
; __device__ __forceinline__ void gemm_phase(PG8_LAS unsigned char* lds, const Gemm g, const Sched& S, const Epi& E) {
;     ...
;             const bool last = (t == nt - 2);
;             const char* a1 = cA + (size_t)(t + 1) * kstep;
;             const char* a2 = last ? nA : cA + (size_t)(t + 2) * kstep; const char* b2 = last ? nB : cB + (size_t)(t + 2) * kstep;
;             const char* a3 = a2 + kstep; const char* b3 = b2 + kstep;
;             if (last && has_next) S.a_ready(nxt);
;             PG8_LDB(B0, 0, 0); PG8_SCHED; PG8_LDA(At, 0, 0); PG8_STAGE(PG8_SA(1, 1), a1 + hstep, voffA);
;             PG8_WAIT_L(8); PG8_BAR; PG8_WAIT_L(0); PG8_MMA(0, 0, At, B0); PG8_BAR; PG8_SCHED;
;             PG8_LDB(B1, 0, 1); PG8_STAGE(PG8_SB(0, 0), b2, voffB);
;     ...
;             PG8_BAR; PG8_WAIT_L(0); PG8_MMA(1, 0, At, B0); PG8_BAR; PG8_SCHED;
;             PG8_STAGE(PG8_SB(1, 1), b3 + hstep, voffB);
;             PG8_WAIT_V(6); PG8_BAR; PG8_MMA(1, 1, At, B1); PG8_BAR;
;         }
	s_waitcnt lgkmcnt(7)
	v_mfma_f32_16x16x32_bf16 v[94:97], v[130:133], v[146:149], v[94:97]
	v_mfma_f32_16x16x32_bf16 v[28:31], v[138:141], v[146:149], v[28:31]
	s_waitcnt lgkmcnt(3)
	v_mfma_f32_16x16x32_bf16 v[86:89], v[130:133], v[154:157], v[86:89]
	v_mfma_f32_16x16x32_bf16 v[20:23], v[138:141], v[154:157], v[20:23]
	v_mfma_f32_16x16x32_bf16 v[78:81], v[130:133], v[162:165], v[78:81]
	v_mfma_f32_16x16x32_bf16 v[12:15], v[138:141], v[162:165], v[12:15]
	s_waitcnt lgkmcnt(0)
	v_mfma_f32_16x16x32_bf16 v[70:73], v[130:133], v[170:173], v[70:73]
	v_mfma_f32_16x16x32_bf16 v[4:7], v[138:141], v[170:173], v[4:7]
	v_mfma_f32_16x16x32_bf16 v[94:97], v[134:137], v[150:153], v[94:97]
	v_mfma_f32_16x16x32_bf16 v[28:31], v[142:145], v[150:153], v[28:31]
	v_mfma_f32_16x16x32_bf16 v[86:89], v[134:137], v[158:161], v[86:89]
	v_mfma_f32_16x16x32_bf16 v[20:23], v[142:145], v[158:161], v[20:23]
	v_mfma_f32_16x16x32_bf16 v[78:81], v[134:137], v[166:169], v[78:81]
	v_mfma_f32_16x16x32_bf16 v[12:15], v[142:145], v[166:169], v[12:15]
	v_mfma_f32_16x16x32_bf16 v[70:73], v[134:137], v[188:191], v[70:73]
	v_mfma_f32_16x16x32_bf16 v[4:7], v[142:145], v[188:191], v[4:7]
	s_barrier
	s_add_u32 s12, s12, 0x40080
	s_addc_u32 s13, s13, 0
	s_add_i32 s16, s16, s36
	s_mov_b32 m0, s16
	v_lshl_add_u64 v[130:131], s[12:13], 0, v[178:179]
	global_load_lds_dwordx4 v[130:131], off
	s_add_i32 m0, s16, 0x2000
	v_lshl_add_u64 v[130:131], s[12:13], 0, v[182:183]
	global_load_lds_dwordx4 v[130:131], off
	s_waitcnt vmcnt(6)
	s_barrier
	v_mfma_f32_16x16x32_bf16 v[90:93], v[192:195], v[146:149], v[90:93]
	v_mfma_f32_16x16x32_bf16 v[24:27], v[200:203], v[146:149], v[24:27]
	v_mfma_f32_16x16x32_bf16 v[82:85], v[192:195], v[154:157], v[82:85]
	v_mfma_f32_16x16x32_bf16 v[16:19], v[200:203], v[154:157], v[16:19]
	v_mfma_f32_16x16x32_bf16 v[74:77], v[192:195], v[162:165], v[74:77]
	v_mfma_f32_16x16x32_bf16 v[8:11], v[200:203], v[162:165], v[8:11]
	v_mfma_f32_16x16x32_bf16 v[66:69], v[192:195], v[170:173], v[66:69]
	v_mfma_f32_16x16x32_bf16 v[0:3], v[200:203], v[170:173], v[0:3]
	v_mfma_f32_16x16x32_bf16 v[90:93], v[196:199], v[150:153], v[90:93]
	v_mfma_f32_16x16x32_bf16 v[24:27], v[204:207], v[150:153], v[24:27]
	v_mfma_f32_16x16x32_bf16 v[82:85], v[196:199], v[158:161], v[82:85]
	v_mfma_f32_16x16x32_bf16 v[16:19], v[204:207], v[158:161], v[16:19]
	v_mfma_f32_16x16x32_bf16 v[74:77], v[196:199], v[166:169], v[74:77]
	v_mfma_f32_16x16x32_bf16 v[8:11], v[204:207], v[166:169], v[8:11]
	v_mfma_f32_16x16x32_bf16 v[66:69], v[196:199], v[188:191], v[66:69]
	v_mfma_f32_16x16x32_bf16 v[0:3], v[204:207], v[188:191], v[0:3]
	s_add_i32 s30, s30, 2
	s_add_u32 s6, s6, 0x100
	s_addc_u32 s7, s7, 0
	s_add_u32 s27, s27, 0x100
	s_addc_u32 s29, s29, 0
	s_cmp_gt_u32 s30, 13
	s_barrier
	s_cbranch_scc1 .Lkpeel_exit_388
.LBB0_388:
	s_add_u32 s12, s6, 0xfffc0080
	s_addc_u32 s13, s7, -1
	s_add_i32 s22, 0, 0x10000
	v_add_u32_e32 v48, s22, v250
	ds_read_b128 v[130:133], v48
	ds_read_b128 v[134:137], v48 offset:1024
	ds_read_b128 v[138:141], v48 offset:2048
	ds_read_b128 v[142:145], v48 offset:3072
	s_cmp_eq_u32 s30, 12
	s_cselect_b32 s17, s9, s13
	s_cselect_b32 s16, s8, s12
	s_cselect_b32 s13, s3, s29
	s_cselect_b32 s12, s26, s27
	v_lshl_add_u64 v[192:193], s[6:7], 0, v[184:185]
	s_add_i32 m0, s37, 0xc000
	ds_read_b128 v[146:149], v242
	ds_read_b128 v[150:153], v242 offset:1024
	ds_read_b128 v[154:157], v242 offset:2048
	ds_read_b128 v[158:161], v242 offset:3072
	ds_read_b128 v[162:165], v242 offset:4096
	ds_read_b128 v[166:169], v242 offset:5120
	ds_read_b128 v[170:173], v242 offset:6144
	ds_read_b128 v[188:191], v242 offset:7168
	global_load_lds_dwordx4 v[192:193], off
	s_add_i32 m0, s37, 0xe000
	v_lshl_add_u64 v[192:193], s[6:7], 0, v[186:187]
	global_load_lds_dwordx4 v[192:193], off
	s_waitcnt lgkmcnt(8)
	s_barrier
	s_waitcnt lgkmcnt(7)
	v_mfma_f32_16x16x32_bf16 v[126:129], v[130:133], v[146:149], v[126:129]
	v_mfma_f32_16x16x32_bf16 v[62:65], v[138:141], v[146:149], v[62:65]
	s_waitcnt lgkmcnt(3)
	v_mfma_f32_16x16x32_bf16 v[118:121], v[130:133], v[154:157], v[118:121]
	v_mfma_f32_16x16x32_bf16 v[54:57], v[138:141], v[154:157], v[54:57]
	v_mfma_f32_16x16x32_bf16 v[110:113], v[130:133], v[162:165], v[110:113]
	v_mfma_f32_16x16x32_bf16 v[44:47], v[138:141], v[162:165], v[44:47]
	s_waitcnt lgkmcnt(0)
	v_mfma_f32_16x16x32_bf16 v[102:105], v[130:133], v[170:173], v[102:105]
	v_mfma_f32_16x16x32_bf16 v[36:39], v[138:141], v[170:173], v[36:39]
	v_mfma_f32_16x16x32_bf16 v[126:129], v[134:137], v[150:153], v[126:129]
	v_mfma_f32_16x16x32_bf16 v[62:65], v[142:145], v[150:153], v[62:65]
	v_mfma_f32_16x16x32_bf16 v[118:121], v[134:137], v[158:161], v[118:121]
	v_mfma_f32_16x16x32_bf16 v[54:57], v[142:145], v[158:161], v[54:57]
	v_mfma_f32_16x16x32_bf16 v[110:113], v[134:137], v[166:169], v[110:113]
	v_mfma_f32_16x16x32_bf16 v[44:47], v[142:145], v[166:169], v[44:47]
	v_mfma_f32_16x16x32_bf16 v[102:105], v[134:137], v[188:191], v[102:105]
	v_mfma_f32_16x16x32_bf16 v[36:39], v[142:145], v[188:191], v[36:39]
	s_barrier
	s_add_i32 s31, 0, 0x14000
	s_add_i32 s22, s22, s36
	v_add_u32_e32 v48, s31, v250
	v_lshl_add_u64 v[208:209], s[12:13], 0, v[178:179]
	s_mov_b32 m0, s22
	ds_read_b128 v[192:195], v48
	ds_read_b128 v[196:199], v48 offset:1024
	ds_read_b128 v[200:203], v48 offset:2048
	ds_read_b128 v[204:207], v48 offset:3072
	global_load_lds_dwordx4 v[208:209], off
	s_add_i32 m0, s22, 0x2000
	v_lshl_add_u64 v[210:211], s[12:13], 0, v[182:183]
	global_load_lds_dwordx4 v[210:211], off
	s_barrier
; #define PG8_STAGE(bufoff, gbase, voff) do { _Pragma("unroll") for (int _i = 0; _i < 2; ++_i) \
;         __builtin_amdgcn_global_load_lds((const unsigned*)((const char*)(gbase) + (voff)[_i]), (PG8_LAS unsigned*)(lds + (bufoff) + ldsw + _i * 8192), 16, 0, 0); } while (0)
; #define PG8_LDA(dst, b, h) do { _Pragma("unroll") for (int m = 0; m < 4; ++m) _Pragma("unroll") for (int k = 0; k < 2; ++k) dst[m][k] = *(const PG8_LAS bf16x8*)(lds + PG8_SA(b, h) + aoff + m * 2048 + k * 1024); } while (0)
; #define PG8_LDB(dst, b, h) do { _Pragma("unroll") for (int n = 0; n < 2; ++n) _Pragma("unroll") for (int k = 0; k < 2; ++k) dst[n][k] = *(const PG8_LAS bf16x8*)(lds + PG8_SB(b, h) + boff + n * 2048 + k * 1024); } while (0)
; #define PG8_MMA(ai, bj, At, Bt) do { __builtin_amdgcn_s_setprio(1); _Pragma("unroll") for (int m = 0; m < 4; ++m) _Pragma("unroll") for (int n = 0; n < 2; ++n) _Pragma("unroll") for (int k = 0; k < 2; ++k) \
;         acc[ai][bj][m][n] = __builtin_amdgcn_mfma_f32_16x16x32_bf16(Bt[n][k], At[m][k], acc[ai][bj][m][n], 0, 0, 0); __builtin_amdgcn_s_setprio(0); } while (0)
; #define PG8_WAIT_V(n) asm volatile("s_waitcnt vmcnt(" #n ")" ::: "memory")
; #define PG8_WAIT_L(n) asm volatile("s_waitcnt lgkmcnt(" #n ")" ::: "memory")
; #define PG8_BAR __builtin_amdgcn_s_barrier()
; #define PG8_SCHED __builtin_amdgcn_sched_barrier(0)
; template <class Epi, class Sched>
; __device__ __forceinline__ void gemm_phase(PG8_LAS unsigned char* lds, const Gemm g, const Sched& S, const Epi& E) {
;     ...
;             PG8_BAR; PG8_WAIT_L(0); PG8_MMA(0, 1, At, B1); PG8_BAR;
;             PG8_LDA(At, 0, 1); PG8_STAGE(PG8_SA(0, 0), a2, voffA);
;             PG8_BAR; PG8_WAIT_L(0); PG8_MMA(1, 0, At, B0); PG8_BAR; PG8_SCHED;
;             PG8_STAGE(PG8_SB(0, 1), b2 + hstep, voffB);
;             PG8_WAIT_V(6); PG8_BAR; PG8_MMA(1, 1, At, B1); PG8_BAR;
;             PG8_LDB(B0, 1, 0); PG8_SCHED; PG8_LDA(At, 1, 0); PG8_STAGE(PG8_SA(0, 1), a2 + hstep, voffA);
;             PG8_WAIT_L(8); PG8_BAR; PG8_WAIT_L(0); PG8_MMA(0, 0, At, B0); PG8_BAR; PG8_SCHED;
	s_waitcnt lgkmcnt(3)
	v_mfma_f32_16x16x32_bf16 v[122:125], v[192:195], v[146:149], v[122:125]
	s_waitcnt lgkmcnt(0)
	v_mfma_f32_16x16x32_bf16 v[58:61], v[200:203], v[146:149], v[58:61]
	v_mfma_f32_16x16x32_bf16 v[114:117], v[192:195], v[154:157], v[114:117]
	v_mfma_f32_16x16x32_bf16 v[50:53], v[200:203], v[154:157], v[50:53]
	v_mfma_f32_16x16x32_bf16 v[106:109], v[192:195], v[162:165], v[106:109]
	v_mfma_f32_16x16x32_bf16 v[40:43], v[200:203], v[162:165], v[40:43]
	v_mfma_f32_16x16x32_bf16 v[98:101], v[192:195], v[170:173], v[98:101]
	v_mfma_f32_16x16x32_bf16 v[32:35], v[200:203], v[170:173], v[32:35]
	v_mfma_f32_16x16x32_bf16 v[122:125], v[196:199], v[150:153], v[122:125]
	v_mfma_f32_16x16x32_bf16 v[58:61], v[204:207], v[150:153], v[58:61]
	v_mfma_f32_16x16x32_bf16 v[114:117], v[196:199], v[158:161], v[114:117]
	v_mfma_f32_16x16x32_bf16 v[50:53], v[204:207], v[158:161], v[50:53]
	v_mfma_f32_16x16x32_bf16 v[106:109], v[196:199], v[166:169], v[106:109]
	v_mfma_f32_16x16x32_bf16 v[40:43], v[204:207], v[166:169], v[40:43]
	v_mfma_f32_16x16x32_bf16 v[98:101], v[196:199], v[188:191], v[98:101]
	v_mfma_f32_16x16x32_bf16 v[32:35], v[204:207], v[188:191], v[32:35]
	s_mov_b32 m0, s37
	v_lshl_add_u64 v[212:213], s[16:17], 0, v[176:177]
	s_barrier
	ds_read_b128 v[146:149], v242 offset:16384
	ds_read_b128 v[150:153], v242 offset:17408
	ds_read_b128 v[154:157], v242 offset:18432
	ds_read_b128 v[158:161], v242 offset:19456
	ds_read_b128 v[162:165], v242 offset:20480
	ds_read_b128 v[166:169], v242 offset:21504
	ds_read_b128 v[170:173], v242 offset:22528
	ds_read_b128 v[188:191], v242 offset:23552
	global_load_lds_dwordx4 v[212:213], off
	s_mov_b32 m0, s10
	v_lshl_add_u64 v[214:215], s[16:17], 0, v[180:181]
	global_load_lds_dwordx4 v[214:215], off
	s_barrier
	s_waitcnt lgkmcnt(7)
	v_mfma_f32_16x16x32_bf16 v[94:97], v[130:133], v[146:149], v[94:97]
	v_mfma_f32_16x16x32_bf16 v[28:31], v[138:141], v[146:149], v[28:31]
	s_waitcnt lgkmcnt(3)
	v_mfma_f32_16x16x32_bf16 v[86:89], v[130:133], v[154:157], v[86:89]
	v_mfma_f32_16x16x32_bf16 v[20:23], v[138:141], v[154:157], v[20:23]
	v_mfma_f32_16x16x32_bf16 v[78:81], v[130:133], v[162:165], v[78:81]
	v_mfma_f32_16x16x32_bf16 v[12:15], v[138:141], v[162:165], v[12:15]
	s_waitcnt lgkmcnt(0)
	v_mfma_f32_16x16x32_bf16 v[70:73], v[130:133], v[170:173], v[70:73]
	v_mfma_f32_16x16x32_bf16 v[4:7], v[138:141], v[170:173], v[4:7]
	v_mfma_f32_16x16x32_bf16 v[94:97], v[134:137], v[150:153], v[94:97]
	v_mfma_f32_16x16x32_bf16 v[28:31], v[142:145], v[150:153], v[28:31]
	v_mfma_f32_16x16x32_bf16 v[86:89], v[134:137], v[158:161], v[86:89]
	v_mfma_f32_16x16x32_bf16 v[20:23], v[142:145], v[158:161], v[20:23]
	v_mfma_f32_16x16x32_bf16 v[78:81], v[134:137], v[166:169], v[78:81]
	v_mfma_f32_16x16x32_bf16 v[12:15], v[142:145], v[166:169], v[12:15]
	v_mfma_f32_16x16x32_bf16 v[70:73], v[134:137], v[188:191], v[70:73]
	v_mfma_f32_16x16x32_bf16 v[4:7], v[142:145], v[188:191], v[4:7]
	s_barrier
	s_add_u32 s22, s12, 0x40000
	s_addc_u32 s23, s13, 0
	s_add_i32 s31, s31, s36
	s_mov_b32 m0, s31
	v_lshl_add_u64 v[130:131], s[22:23], 0, v[178:179]
	global_load_lds_dwordx4 v[130:131], off
	s_add_i32 m0, s31, 0x2000
	v_lshl_add_u64 v[130:131], s[22:23], 0, v[182:183]
	global_load_lds_dwordx4 v[130:131], off
	s_waitcnt vmcnt(6)
	s_barrier
	v_mfma_f32_16x16x32_bf16 v[90:93], v[192:195], v[146:149], v[90:93]
	v_mfma_f32_16x16x32_bf16 v[24:27], v[200:203], v[146:149], v[24:27]
	v_mfma_f32_16x16x32_bf16 v[82:85], v[192:195], v[154:157], v[82:85]
	v_mfma_f32_16x16x32_bf16 v[16:19], v[200:203], v[154:157], v[16:19]
	v_mfma_f32_16x16x32_bf16 v[74:77], v[192:195], v[162:165], v[74:77]
	v_mfma_f32_16x16x32_bf16 v[8:11], v[200:203], v[162:165], v[8:11]
	v_mfma_f32_16x16x32_bf16 v[66:69], v[192:195], v[170:173], v[66:69]
	v_mfma_f32_16x16x32_bf16 v[0:3], v[200:203], v[170:173], v[0:3]
	v_mfma_f32_16x16x32_bf16 v[90:93], v[196:199], v[150:153], v[90:93]
	v_mfma_f32_16x16x32_bf16 v[24:27], v[204:207], v[150:153], v[24:27]
	v_mfma_f32_16x16x32_bf16 v[82:85], v[196:199], v[158:161], v[82:85]
	v_mfma_f32_16x16x32_bf16 v[16:19], v[204:207], v[158:161], v[16:19]
	v_mfma_f32_16x16x32_bf16 v[74:77], v[196:199], v[166:169], v[74:77]
	v_mfma_f32_16x16x32_bf16 v[8:11], v[204:207], v[166:169], v[8:11]
	v_mfma_f32_16x16x32_bf16 v[66:69], v[196:199], v[188:191], v[66:69]
	v_mfma_f32_16x16x32_bf16 v[0:3], v[204:207], v[188:191], v[0:3]
	s_add_i32 s22, 0, 0x18000
	v_add_u32_e32 v48, s22, v250
	s_barrier
	ds_read_b128 v[130:133], v48
	ds_read_b128 v[134:137], v48 offset:1024
	ds_read_b128 v[138:141], v48 offset:2048
	ds_read_b128 v[142:145], v48 offset:3072
	s_add_u32 s16, s16, 0x40000
	s_addc_u32 s17, s17, 0
	s_mov_b32 m0, s11
	v_lshl_add_u64 v[192:193], s[16:17], 0, v[176:177]
	ds_read_b128 v[146:149], v242 offset:32768
	ds_read_b128 v[150:153], v242 offset:33792
	ds_read_b128 v[154:157], v242 offset:34816
	ds_read_b128 v[158:161], v242 offset:35840
	ds_read_b128 v[162:165], v242 offset:36864
	ds_read_b128 v[166:169], v242 offset:37888
	ds_read_b128 v[170:173], v242 offset:38912
	ds_read_b128 v[188:191], v242 offset:39936
	global_load_lds_dwordx4 v[192:193], off
	s_mov_b32 m0, s24
	v_lshl_add_u64 v[192:193], s[16:17], 0, v[180:181]
	global_load_lds_dwordx4 v[192:193], off
	s_waitcnt lgkmcnt(8)
	s_barrier
; #define PG8_STAGE(bufoff, gbase, voff) do { _Pragma("unroll") for (int _i = 0; _i < 2; ++_i) \
;         __builtin_amdgcn_global_load_lds((const unsigned*)((const char*)(gbase) + (voff)[_i]), (PG8_LAS unsigned*)(lds + (bufoff) + ldsw + _i * 8192), 16, 0, 0); } while (0)
; #define PG8_LDA(dst, b, h) do { _Pragma("unroll") for (int m = 0; m < 4; ++m) _Pragma("unroll") for (int k = 0; k < 2; ++k) dst[m][k] = *(const PG8_LAS bf16x8*)(lds + PG8_SA(b, h) + aoff + m * 2048 + k * 1024); } while (0)
; #define PG8_LDB(dst, b, h) do { _Pragma("unroll") for (int n = 0; n < 2; ++n) _Pragma("unroll") for (int k = 0; k < 2; ++k) dst[n][k] = *(const PG8_LAS bf16x8*)(lds + PG8_SB(b, h) + boff + n * 2048 + k * 1024); } while (0)
; #define PG8_MMA(ai, bj, At, Bt) do { __builtin_amdgcn_s_setprio(1); _Pragma("unroll") for (int m = 0; m < 4; ++m) _Pragma("unroll") for (int n = 0; n < 2; ++n) _Pragma("unroll") for (int k = 0; k < 2; ++k) \
;         acc[ai][bj][m][n] = __builtin_amdgcn_mfma_f32_16x16x32_bf16(Bt[n][k], At[m][k], acc[ai][bj][m][n], 0, 0, 0); __builtin_amdgcn_s_setprio(0); } while (0)
; #define PG8_WAIT_V(n) asm volatile("s_waitcnt vmcnt(" #n ")" ::: "memory")
; #define PG8_WAIT_L(n) asm volatile("s_waitcnt lgkmcnt(" #n ")" ::: "memory")
; #define PG8_BAR __builtin_amdgcn_s_barrier()
; #define PG8_SCHED __builtin_amdgcn_sched_barrier(0)
; template <class Epi, class Sched>
; __device__ __forceinline__ void gemm_phase(PG8_LAS unsigned char* lds, const Gemm g, const Sched& S, const Epi& E) {
;     ...
;             PG8_WAIT_L(8); PG8_BAR; PG8_WAIT_L(0); PG8_MMA(0, 0, At, B0); PG8_BAR; PG8_SCHED;
;             PG8_LDB(B1, 1, 1); PG8_STAGE(PG8_SB(1, 0), b3, voffB);
;             PG8_BAR; PG8_WAIT_L(0); PG8_MMA(0, 1, At, B1); PG8_BAR;
;             PG8_LDA(At, 1, 1); PG8_STAGE(PG8_SA(1, 0), a3, voffA);
;             PG8_BAR; PG8_WAIT_L(0); PG8_MMA(1, 0, At, B0); PG8_BAR; PG8_SCHED;
;             PG8_STAGE(PG8_SB(1, 1), b3 + hstep, voffB);
;             PG8_WAIT_V(6); PG8_BAR; PG8_MMA(1, 1, At, B1); PG8_BAR;
	s_waitcnt lgkmcnt(7)
	v_mfma_f32_16x16x32_bf16 v[126:129], v[130:133], v[146:149], v[126:129]
	v_mfma_f32_16x16x32_bf16 v[62:65], v[138:141], v[146:149], v[62:65]
	s_waitcnt lgkmcnt(3)
	v_mfma_f32_16x16x32_bf16 v[118:121], v[130:133], v[154:157], v[118:121]
	v_mfma_f32_16x16x32_bf16 v[54:57], v[138:141], v[154:157], v[54:57]
	v_mfma_f32_16x16x32_bf16 v[110:113], v[130:133], v[162:165], v[110:113]
	v_mfma_f32_16x16x32_bf16 v[44:47], v[138:141], v[162:165], v[44:47]
	s_waitcnt lgkmcnt(0)
	v_mfma_f32_16x16x32_bf16 v[102:105], v[130:133], v[170:173], v[102:105]
	v_mfma_f32_16x16x32_bf16 v[36:39], v[138:141], v[170:173], v[36:39]
	v_mfma_f32_16x16x32_bf16 v[126:129], v[134:137], v[150:153], v[126:129]
	v_mfma_f32_16x16x32_bf16 v[62:65], v[142:145], v[150:153], v[62:65]
	v_mfma_f32_16x16x32_bf16 v[118:121], v[134:137], v[158:161], v[118:121]
	v_mfma_f32_16x16x32_bf16 v[54:57], v[142:145], v[158:161], v[54:57]
	v_mfma_f32_16x16x32_bf16 v[110:113], v[134:137], v[166:169], v[110:113]
	v_mfma_f32_16x16x32_bf16 v[44:47], v[142:145], v[166:169], v[44:47]
	v_mfma_f32_16x16x32_bf16 v[102:105], v[134:137], v[188:191], v[102:105]
	v_mfma_f32_16x16x32_bf16 v[36:39], v[142:145], v[188:191], v[36:39]
	s_barrier
	s_add_i32 s16, 0, 0x1c000
	s_add_i32 s17, s22, s36
	v_add_u32_e32 v48, s16, v250
	v_lshl_add_u64 v[208:209], v[208:209], 0, s[0:1]
	s_mov_b32 m0, s17
	ds_read_b128 v[192:195], v48
	ds_read_b128 v[196:199], v48 offset:1024
	ds_read_b128 v[200:203], v48 offset:2048
	ds_read_b128 v[204:207], v48 offset:3072
	global_load_lds_dwordx4 v[208:209], off
	s_add_i32 m0, s17, 0x2000
	v_lshl_add_u64 v[208:209], v[210:211], 0, s[0:1]
	global_load_lds_dwordx4 v[208:209], off
	s_barrier
	s_waitcnt lgkmcnt(3)
	v_mfma_f32_16x16x32_bf16 v[122:125], v[192:195], v[146:149], v[122:125]
	s_waitcnt lgkmcnt(0)
	v_mfma_f32_16x16x32_bf16 v[58:61], v[200:203], v[146:149], v[58:61]
	v_mfma_f32_16x16x32_bf16 v[114:117], v[192:195], v[154:157], v[114:117]
	v_mfma_f32_16x16x32_bf16 v[50:53], v[200:203], v[154:157], v[50:53]
	v_mfma_f32_16x16x32_bf16 v[106:109], v[192:195], v[162:165], v[106:109]
	v_mfma_f32_16x16x32_bf16 v[40:43], v[200:203], v[162:165], v[40:43]
	v_mfma_f32_16x16x32_bf16 v[98:101], v[192:195], v[170:173], v[98:101]
	v_mfma_f32_16x16x32_bf16 v[32:35], v[200:203], v[170:173], v[32:35]
	v_mfma_f32_16x16x32_bf16 v[122:125], v[196:199], v[150:153], v[122:125]
	v_mfma_f32_16x16x32_bf16 v[58:61], v[204:207], v[150:153], v[58:61]
	v_mfma_f32_16x16x32_bf16 v[114:117], v[196:199], v[158:161], v[114:117]
	v_mfma_f32_16x16x32_bf16 v[50:53], v[204:207], v[158:161], v[50:53]
	v_mfma_f32_16x16x32_bf16 v[106:109], v[196:199], v[166:169], v[106:109]
	v_mfma_f32_16x16x32_bf16 v[40:43], v[204:207], v[166:169], v[40:43]
	v_mfma_f32_16x16x32_bf16 v[98:101], v[196:199], v[188:191], v[98:101]
	v_mfma_f32_16x16x32_bf16 v[32:35], v[204:207], v[188:191], v[32:35]
	s_mov_b32 m0, s25
	v_lshl_add_u64 v[208:209], v[212:213], 0, s[0:1]
	s_barrier
	ds_read_b128 v[146:149], v242 offset:49152
	ds_read_b128 v[150:153], v242 offset:50176
	ds_read_b128 v[154:157], v242 offset:51200
	ds_read_b128 v[158:161], v242 offset:52224
	ds_read_b128 v[162:165], v242 offset:53248
	ds_read_b128 v[166:169], v242 offset:54272
	ds_read_b128 v[170:173], v242 offset:55296
	ds_read_b128 v[188:191], v242 offset:56320
	global_load_lds_dwordx4 v[208:209], off
	s_mov_b32 m0, s18
	v_lshl_add_u64 v[208:209], v[214:215], 0, s[0:1]
	global_load_lds_dwordx4 v[208:209], off
	s_barrier
	s_waitcnt lgkmcnt(7)
	v_mfma_f32_16x16x32_bf16 v[94:97], v[130:133], v[146:149], v[94:97]
	v_mfma_f32_16x16x32_bf16 v[28:31], v[138:141], v[146:149], v[28:31]
	s_waitcnt lgkmcnt(3)
	v_mfma_f32_16x16x32_bf16 v[86:89], v[130:133], v[154:157], v[86:89]
	v_mfma_f32_16x16x32_bf16 v[20:23], v[138:141], v[154:157], v[20:23]
	v_mfma_f32_16x16x32_bf16 v[78:81], v[130:133], v[162:165], v[78:81]
	v_mfma_f32_16x16x32_bf16 v[12:15], v[138:141], v[162:165], v[12:15]
	s_waitcnt lgkmcnt(0)
	v_mfma_f32_16x16x32_bf16 v[70:73], v[130:133], v[170:173], v[70:73]
	v_mfma_f32_16x16x32_bf16 v[4:7], v[138:141], v[170:173], v[4:7]
	v_mfma_f32_16x16x32_bf16 v[94:97], v[134:137], v[150:153], v[94:97]
	v_mfma_f32_16x16x32_bf16 v[28:31], v[142:145], v[150:153], v[28:31]
	v_mfma_f32_16x16x32_bf16 v[86:89], v[134:137], v[158:161], v[86:89]
	v_mfma_f32_16x16x32_bf16 v[20:23], v[142:145], v[158:161], v[20:23]
	v_mfma_f32_16x16x32_bf16 v[78:81], v[134:137], v[166:169], v[78:81]
	v_mfma_f32_16x16x32_bf16 v[12:15], v[142:145], v[166:169], v[12:15]
	v_mfma_f32_16x16x32_bf16 v[70:73], v[134:137], v[188:191], v[70:73]
	v_mfma_f32_16x16x32_bf16 v[4:7], v[142:145], v[188:191], v[4:7]
	s_barrier
	s_add_u32 s12, s12, 0x40080
	s_addc_u32 s13, s13, 0
	s_add_i32 s16, s16, s36
	s_mov_b32 m0, s16
	v_lshl_add_u64 v[130:131], s[12:13], 0, v[178:179]
	global_load_lds_dwordx4 v[130:131], off
	s_add_i32 m0, s16, 0x2000
	v_lshl_add_u64 v[130:131], s[12:13], 0, v[182:183]
	global_load_lds_dwordx4 v[130:131], off
	s_waitcnt vmcnt(6)
	s_barrier
	v_mfma_f32_16x16x32_bf16 v[90:93], v[192:195], v[146:149], v[90:93]
	v_mfma_f32_16x16x32_bf16 v[24:27], v[200:203], v[146:149], v[24:27]
	v_mfma_f32_16x16x32_bf16 v[82:85], v[192:195], v[154:157], v[82:85]
	v_mfma_f32_16x16x32_bf16 v[16:19], v[200:203], v[154:157], v[16:19]
	v_mfma_f32_16x16x32_bf16 v[74:77], v[192:195], v[162:165], v[74:77]
	v_mfma_f32_16x16x32_bf16 v[8:11], v[200:203], v[162:165], v[8:11]
	v_mfma_f32_16x16x32_bf16 v[66:69], v[192:195], v[170:173], v[66:69]
	v_mfma_f32_16x16x32_bf16 v[0:3], v[200:203], v[170:173], v[0:3]
	v_mfma_f32_16x16x32_bf16 v[90:93], v[196:199], v[150:153], v[90:93]
	v_mfma_f32_16x16x32_bf16 v[24:27], v[204:207], v[150:153], v[24:27]
	v_mfma_f32_16x16x32_bf16 v[82:85], v[196:199], v[158:161], v[82:85]
	v_mfma_f32_16x16x32_bf16 v[16:19], v[204:207], v[158:161], v[16:19]
	v_mfma_f32_16x16x32_bf16 v[74:77], v[196:199], v[166:169], v[74:77]
	v_mfma_f32_16x16x32_bf16 v[8:11], v[204:207], v[166:169], v[8:11]
	v_mfma_f32_16x16x32_bf16 v[66:69], v[196:199], v[188:191], v[66:69]
	v_mfma_f32_16x16x32_bf16 v[0:3], v[204:207], v[188:191], v[0:3]
	s_add_i32 s30, s30, 2
	s_add_u32 s6, s6, 0x100
	s_addc_u32 s7, s7, 0
	s_add_u32 s27, s27, 0x100
	s_addc_u32 s29, s29, 0
	s_cmp_gt_u32 s30, 13
	s_barrier
	s_cbranch_scc0 .LBB0_388
